# v52 + dropped the spare s_nop between the P pack converts and the permlane swaps (wait states already met by the instruction order)
# baseline (speedup 1.0000x reference)
; DI int v_rd_base(int lane) { return ((lane & 3) << 3) | (((lane >> 2) & 3) << 6) | (((lane >> 4) & 1) << 5) | (((lane >> 5) & 1) << 8); }
; DI void expsum(f32x16& p, float& l_reg, bf16x8& pa0, bf16x8& pa1) {
; #pragma unroll
;     for (int r = 0; r < 16; ++r) p[r] = __builtin_amdgcn_exp2f(p[r]);
;     float ps = 0.f;
; #pragma unroll
;     for (int r = 0; r < 16; ++r) ps += p[r];
;     l_reg += ps; asm volatile("" : "+v"(l_reg));
;     ...
;     ATT_PK4(p, 0, pa0); ATT_PK4(p, 8, pa1);
;     ...
; }
; template <int DQK, int MODE, int LDQ, int LDK, int LDV> ...
;     ...
;     const int vbase = (int)(unsigned)(size_t)lds + V_OFF + v_rd_base(lane);
;     ...
;     constexpr int NDA = ND0 > 6 ? 6 : ND0;
.LBB0_1922:
	s_add_i32 s3, s0, -1
	s_add_i32 s2, s22, 0xffffa000
	s_and_b32 s2, s2, 0x6000
	v_add_u32_e32 v121, s2, v114
	v_add_u32_e32 v122, v121, v115
	v_add_u32_e32 v126, v121, v116
	ds_read_b128 v[122:125], v122 offset:4096
	ds_read_b128 v[132:135], v126 offset:4096
	v_add_u32_e32 v126, v121, v117
	v_add_u32_e32 v121, v121, v118
	s_lshl_b32 s2, s1, 14
	ds_read_b128 v[136:139], v126 offset:4096
	ds_read_b128 v[140:143], v121 offset:4096
	v_add_u32_e32 v121, s2, v106
	ds_read_b64_tr_b16 v[144:145], v121 offset:0
	ds_read_b64_tr_b16 v[146:147], v121 offset:0x800
	ds_read_b64_tr_b16 v[148:149], v121 offset:0x1000
	ds_read_b64_tr_b16 v[150:151], v121 offset:0x1800
	ds_read_b64_tr_b16 v[152:153], v121 offset:0x200
	ds_read_b64_tr_b16 v[154:155], v121 offset:0xa00
	ds_read_b64_tr_b16 v[156:157], v121 offset:0x1200
	ds_read_b64_tr_b16 v[158:159], v121 offset:0x1a00
	ds_read_b64_tr_b16 v[162:163], v121 offset:0x400
	ds_read_b64_tr_b16 v[164:165], v121 offset:0xc00
	ds_read_b64_tr_b16 v[166:167], v121 offset:0x1400
	ds_read_b64_tr_b16 v[168:169], v121 offset:0x1c00
	ds_read_b64_tr_b16 v[170:171], v121 offset:0x600
	ds_read_b64_tr_b16 v[172:173], v121 offset:0xe00
	ds_read_b64_tr_b16 v[174:175], v121 offset:0x1600
	ds_read_b64_tr_b16 v[176:177], v121 offset:0x1e00
	s_setprio 2
	v_exp_f32_e32 v64, v64
	v_exp_f32_e32 v65, v65
	v_exp_f32_e32 v66, v66
	v_exp_f32_e32 v67, v67
	v_exp_f32_e32 v68, v68
	v_exp_f32_e32 v69, v69
	v_add_f32_e32 v126, v65, v64
	v_exp_f32_e32 v70, v70
	v_add_f32_e32 v126, v66, v126
	v_exp_f32_e32 v71, v71
	v_add_f32_e32 v126, v67, v126
	v_exp_f32_e32 v72, v72
	v_add_f32_e32 v126, v68, v126
	v_exp_f32_e32 v73, v73
	v_add_f32_e32 v126, v69, v126
	v_exp_f32_e32 v74, v74
	v_add_f32_e32 v126, v70, v126
	v_exp_f32_e32 v75, v75
	v_add_f32_e32 v126, v71, v126
	v_exp_f32_e32 v76, v76
	v_add_f32_e32 v126, v72, v126
	v_exp_f32_e32 v77, v77
	v_add_f32_e32 v126, v73, v126
	v_exp_f32_e32 v78, v78
	v_add_f32_e32 v126, v74, v126
	v_exp_f32_e32 v79, v79
	v_add_f32_e32 v126, v75, v126
	v_add_f32_e32 v126, v76, v126
	v_add_f32_e32 v126, v77, v126
	v_add_f32_e32 v126, v78, v126
	v_add_f32_e32 v126, v79, v126
	v_add_f32_e32 v120, v126, v120
	v_cvt_pk_bf16_f32 v64, v64, v65
	v_cvt_pk_bf16_f32 v65, v66, v67
	v_cvt_pk_bf16_f32 v66, v68, v69
	v_cvt_pk_bf16_f32 v67, v70, v71
	v_cvt_pk_bf16_f32 v68, v72, v73
	v_cvt_pk_bf16_f32 v69, v74, v75
	v_cvt_pk_bf16_f32 v70, v76, v77
	v_cvt_pk_bf16_f32 v71, v78, v79
	v_permlane32_swap_b32_e32 v64, v66
	v_permlane32_swap_b32_e32 v65, v67
	v_permlane32_swap_b32_e32 v68, v70
	v_permlane32_swap_b32_e32 v69, v71
	s_waitcnt lgkmcnt(0)
	s_setprio 1
	v_mfma_f32_32x32x16_bf16 v[0:15], v[64:67], v[144:147], v[0:15]
	s_cmp_lt_i32 s3, s55
	s_cselect_b64 vcc, -1, 0
	s_cmp_ge_i32 s3, s97
	s_cselect_b64 s[74:75], -1, 0
	s_or_b64 s[74:75], vcc, s[74:75]
	s_and_b64 vcc, exec, s[74:75]
	v_mfma_f32_32x32x16_bf16 v[48:63], v[64:67], v[152:155], v[48:63]
	v_mfma_f32_32x32x16_bf16 v[32:47], v[64:67], v[162:165], v[32:47]
	v_mfma_f32_32x32x16_bf16 v[16:31], v[64:67], v[170:173], v[16:31]
	v_mfma_f32_32x32x16_bf16 v[0:15], v[68:71], v[148:151], v[0:15]
	v_mfma_f32_32x32x16_bf16 v[48:63], v[68:71], v[156:159], v[48:63]
	v_mfma_f32_32x32x16_bf16 v[32:47], v[68:71], v[166:169], v[32:47]
	v_mfma_f32_32x32x16_bf16 v[16:31], v[68:71], v[174:177], v[16:31]
	v_mfma_f32_32x32x16_bf16 v[64:79], v[122:125], v[92:95], 0
	v_mfma_f32_32x32x16_bf16 v[64:79], v[132:135], v[88:91], v[64:79]
	v_mfma_f32_32x32x16_bf16 v[64:79], v[136:139], v[84:87], v[64:79]
	v_mfma_f32_32x32x16_bf16 v[64:79], v[140:143], v[80:83], v[64:79]
	s_setprio 0
	v_add_u32_e32 v122, s7, v119
	s_cbranch_vccnz .LBB0_1924
	v_add_u32_e32 v138, 0x28908, v122
	v_add_u32_e32 v140, 0x28920, v122
	v_add_u32_e32 v142, 0x28928, v122
	v_add_u32_e32 v124, 0x28940, v122
	v_add_u32_e32 v126, 0x28948, v122
	v_add_u32_e32 v132, 0x28960, v122
	v_add_u32_e32 v134, 0x28968, v122
	v_add_u32_e32 v123, 0x28900, v122
	ds_read2_b32 v[124:125], v124 offset1:1
	ds_read2_b32 v[126:127], v126 offset1:1
	ds_read2_b32 v[132:133], v132 offset1:1
	ds_read2_b32 v[134:135], v134 offset1:1
	ds_read2_b32 v[136:137], v123 offset1:1
	ds_read2_b32 v[138:139], v138 offset1:1
	ds_read2_b32 v[140:141], v140 offset1:1
	ds_read2_b32 v[142:143], v142 offset1:1
	s_waitcnt lgkmcnt(0)
	v_pk_add_f32 v[78:79], v[78:79], v[134:135]
	v_pk_add_f32 v[76:77], v[76:77], v[132:133]
	v_pk_add_f32 v[74:75], v[74:75], v[126:127]
	v_pk_add_f32 v[72:73], v[72:73], v[124:125]
	v_pk_add_f32 v[70:71], v[70:71], v[142:143]
	v_pk_add_f32 v[68:69], v[68:69], v[140:141]
	v_pk_add_f32 v[66:67], v[66:67], v[138:139]
	v_pk_add_f32 v[64:65], v[64:65], v[136:137]
; DI void expsum(f32x16& p, float& l_reg, bf16x8& pa0, bf16x8& pa1) {
; #pragma unroll
;     for (int r = 0; r < 16; ++r) p[r] = __builtin_amdgcn_exp2f(p[r]);
;     float ps = 0.f;
; #pragma unroll
;     for (int r = 0; r < 16; ++r) ps += p[r];
;     l_reg += ps; asm volatile("" : "+v"(l_reg));
;     ...
;     ATT_PK4(p, 0, pa0); ATT_PK4(p, 8, pa1);
;     ...
; }
; template <int DQK, int MODE, int LDQ, int LDK, int LDV> ...
;     ...
;     constexpr int NDA = ND0 > 6 ? 6 : ND0;
.LBB0_1924:
	s_add_i32 s3, s22, 0xffffc000
	s_and_b32 s3, s3, 0x6000
	v_add_u32_e32 v123, s3, v114
	v_add_u32_e32 v140, v123, v118
	v_add_u32_e32 v136, v123, v117
	v_add_u32_e32 v132, v123, v116
	v_add_u32_e32 v123, v123, v115
	ds_read_b128 v[124:127], v123
	ds_read_b128 v[132:135], v132
	ds_read_b128 v[136:139], v136
	ds_read_b128 v[140:143], v140
	ds_read_b64_tr_b16 v[144:145], v121 offset:0x2000
	ds_read_b64_tr_b16 v[146:147], v121 offset:0x2800
	ds_read_b64_tr_b16 v[148:149], v121 offset:0x3000
	ds_read_b64_tr_b16 v[150:151], v121 offset:0x3800
	ds_read_b64_tr_b16 v[152:153], v121 offset:0x2200
	ds_read_b64_tr_b16 v[154:155], v121 offset:0x2a00
	ds_read_b64_tr_b16 v[156:157], v121 offset:0x3200
	ds_read_b64_tr_b16 v[158:159], v121 offset:0x3a00
	ds_read_b64_tr_b16 v[162:163], v121 offset:0x2400
	ds_read_b64_tr_b16 v[164:165], v121 offset:0x2c00
	ds_read_b64_tr_b16 v[166:167], v121 offset:0x3400
	ds_read_b64_tr_b16 v[168:169], v121 offset:0x3c00
	ds_read_b64_tr_b16 v[170:171], v121 offset:0x2600
	ds_read_b64_tr_b16 v[172:173], v121 offset:0x2e00
	ds_read_b64_tr_b16 v[174:175], v121 offset:0x3600
	ds_read_b64_tr_b16 v[176:177], v121 offset:0x3e00
	s_setprio 2
	v_exp_f32_e32 v64, v64
	v_exp_f32_e32 v65, v65
	v_exp_f32_e32 v66, v66
	v_exp_f32_e32 v67, v67
	v_exp_f32_e32 v68, v68
	v_exp_f32_e32 v69, v69
	v_add_f32_e32 v121, v65, v64
	v_exp_f32_e32 v70, v70
	v_add_f32_e32 v121, v66, v121
	v_exp_f32_e32 v71, v71
	v_add_f32_e32 v121, v67, v121
	v_exp_f32_e32 v72, v72
	v_add_f32_e32 v121, v68, v121
	v_exp_f32_e32 v73, v73
	v_add_f32_e32 v121, v69, v121
	v_exp_f32_e32 v74, v74
	v_add_f32_e32 v121, v70, v121
	v_exp_f32_e32 v75, v75
	v_add_f32_e32 v121, v71, v121
	v_exp_f32_e32 v76, v76
	v_add_f32_e32 v121, v72, v121
	v_exp_f32_e32 v77, v77
	v_add_f32_e32 v121, v73, v121
	v_exp_f32_e32 v78, v78
	v_add_f32_e32 v121, v74, v121
	v_exp_f32_e32 v79, v79
	v_add_f32_e32 v121, v75, v121
	v_add_f32_e32 v121, v76, v121
	v_add_f32_e32 v121, v77, v121
	v_add_f32_e32 v121, v78, v121
	v_add_f32_e32 v121, v79, v121
	v_add_f32_e32 v120, v120, v121
	v_cvt_pk_bf16_f32 v64, v64, v65
	v_cvt_pk_bf16_f32 v65, v66, v67
	v_cvt_pk_bf16_f32 v66, v68, v69
	v_cvt_pk_bf16_f32 v67, v70, v71
	v_cvt_pk_bf16_f32 v68, v72, v73
	v_cvt_pk_bf16_f32 v69, v74, v75
	v_cvt_pk_bf16_f32 v70, v76, v77
	v_cvt_pk_bf16_f32 v71, v78, v79
	v_permlane32_swap_b32_e32 v64, v66
	v_permlane32_swap_b32_e32 v65, v67
	v_permlane32_swap_b32_e32 v68, v70
	v_permlane32_swap_b32_e32 v69, v71
	s_waitcnt lgkmcnt(0)
	s_setprio 1
	s_cmp_lt_u32 s33, 0x100
	s_cbranch_scc1 .Lstg_d0_mid_11
	s_waitcnt vmcnt(3)
	s_barrier

; DI void expsum(f32x16& p, float& l_reg, bf16x8& pa0, bf16x8& pa1) {
; #pragma unroll
;     for (int r = 0; r < 16; ++r) p[r] = __builtin_amdgcn_exp2f(p[r]);
;     float ps = 0.f;
; #pragma unroll
;     for (int r = 0; r < 16; ++r) ps += p[r];
;     l_reg += ps; asm volatile("" : "+v"(l_reg));
;     ...
;     ATT_PK4(p, 0, pa0); ATT_PK4(p, 8, pa1);
;     ...
; }
.LBB0_1930:
	s_mov_b64 s[96:97], 0xc00
	ds_read_b128 v[98:101], v107 offset:12288
	ds_read_b128 v[102:105], v108 offset:12288
	ds_read_b128 v[114:117], v109 offset:12288
	ds_read_b128 v[122:125], v110 offset:12288
	v_lshl_add_u32 v96, s64, 14, v106
	ds_read_b64_tr_b16 v[132:133], v96 offset:0
	ds_read_b64_tr_b16 v[134:135], v96 offset:0x800
	ds_read_b64_tr_b16 v[136:137], v96 offset:0x1000
	ds_read_b64_tr_b16 v[138:139], v96 offset:0x1800
	ds_read_b64_tr_b16 v[140:141], v96 offset:0x200
	ds_read_b64_tr_b16 v[142:143], v96 offset:0xa00
	ds_read_b64_tr_b16 v[144:145], v96 offset:0x1200
	ds_read_b64_tr_b16 v[146:147], v96 offset:0x1a00
	ds_read_b64_tr_b16 v[148:149], v96 offset:0x400
	ds_read_b64_tr_b16 v[150:151], v96 offset:0xc00
	ds_read_b64_tr_b16 v[152:153], v96 offset:0x1400
	ds_read_b64_tr_b16 v[154:155], v96 offset:0x1c00
	ds_read_b64_tr_b16 v[156:157], v96 offset:0x600
	ds_read_b64_tr_b16 v[158:159], v96 offset:0xe00
	ds_read_b64_tr_b16 v[162:163], v96 offset:0x1600
	ds_read_b64_tr_b16 v[164:165], v96 offset:0x1e00
	s_setprio 2
	v_exp_f32_e32 v64, v64
	v_exp_f32_e32 v65, v65
	v_exp_f32_e32 v66, v66
	v_exp_f32_e32 v67, v67
	v_exp_f32_e32 v68, v68
	v_exp_f32_e32 v69, v69
	v_add_f32_e32 v97, v65, v64
	v_exp_f32_e32 v70, v70
	v_add_f32_e32 v97, v66, v97
	v_exp_f32_e32 v71, v71
	v_add_f32_e32 v97, v67, v97
	v_exp_f32_e32 v72, v72
	v_add_f32_e32 v97, v68, v97
	v_exp_f32_e32 v73, v73
	v_add_f32_e32 v97, v69, v97
	v_exp_f32_e32 v74, v74
	v_add_f32_e32 v97, v70, v97
	v_exp_f32_e32 v75, v75
	v_add_f32_e32 v97, v71, v97
	v_exp_f32_e32 v76, v76
	v_add_f32_e32 v97, v72, v97
	v_exp_f32_e32 v77, v77
	v_add_f32_e32 v97, v73, v97
	v_exp_f32_e32 v78, v78
	v_add_f32_e32 v97, v74, v97
	v_exp_f32_e32 v79, v79
	v_add_f32_e32 v97, v75, v97
	v_add_f32_e32 v97, v76, v97
	v_add_f32_e32 v97, v77, v97
	v_add_f32_e32 v97, v78, v97
	v_add_f32_e32 v97, v79, v97
	v_add_f32_e32 v97, v97, v120
	v_cvt_pk_bf16_f32 v64, v64, v65
	v_cvt_pk_bf16_f32 v65, v66, v67
	v_cvt_pk_bf16_f32 v66, v68, v69
	v_cvt_pk_bf16_f32 v67, v70, v71
	v_cvt_pk_bf16_f32 v68, v72, v73
	v_cvt_pk_bf16_f32 v69, v74, v75
	v_cvt_pk_bf16_f32 v70, v76, v77
	v_cvt_pk_bf16_f32 v71, v78, v79
	v_permlane32_swap_b32_e32 v64, v66
	v_permlane32_swap_b32_e32 v65, v67
	v_permlane32_swap_b32_e32 v68, v70
	v_permlane32_swap_b32_e32 v69, v71
	s_waitcnt lgkmcnt(0)
	s_setprio 1
	v_mfma_f32_32x32x16_bf16 v[0:15], v[64:67], v[132:135], v[0:15]
	s_cmp_gt_i32 s55, 61
	s_cselect_b64 s[0:1], -1, 0
	s_cmp_lt_i32 s58, 62
	s_cselect_b64 s[2:3], -1, 0
	s_or_b64 s[0:1], s[0:1], s[2:3]
	s_and_b64 vcc, exec, s[0:1]
	v_mfma_f32_32x32x16_bf16 v[48:63], v[64:67], v[140:143], v[48:63]
	v_mfma_f32_32x32x16_bf16 v[32:47], v[64:67], v[148:151], v[32:47]
	v_mfma_f32_32x32x16_bf16 v[16:31], v[64:67], v[156:159], v[16:31]
	v_mfma_f32_32x32x16_bf16 v[0:15], v[68:71], v[136:139], v[0:15]
	v_mfma_f32_32x32x16_bf16 v[48:63], v[68:71], v[144:147], v[48:63]
	v_mfma_f32_32x32x16_bf16 v[32:47], v[68:71], v[152:155], v[32:47]
	v_mfma_f32_32x32x16_bf16 v[16:31], v[68:71], v[162:165], v[16:31]
	s_waitcnt lgkmcnt(0)
	v_mfma_f32_32x32x16_bf16 v[64:79], v[98:101], v[92:95], 0
	v_mfma_f32_32x32x16_bf16 v[64:79], v[102:105], v[88:91], v[64:79]
	v_mfma_f32_32x32x16_bf16 v[64:79], v[114:117], v[84:87], v[64:79]
	v_mfma_f32_32x32x16_bf16 v[64:79], v[122:125], v[80:83], v[64:79]
	s_setprio 0
	s_cbranch_vccnz .LBB0_1932
	v_sub_u32_e32 v98, 0xf40, v111
	v_lshlrev_b32_e32 v98, 2, v98
	v_add3_u32 v98, s88, v98, v130
	v_add_u32_e32 v114, 0x400, v98
	v_add_u32_e32 v116, 0x408, v98
	v_add_u32_e32 v118, 0x420, v98
	v_add_u32_e32 v120, 0x428, v98
	v_add_u32_e32 v99, 0x440, v98
	v_add_u32_e32 v100, 0x448, v98
	v_add_u32_e32 v102, 0x460, v98
	v_add_u32_e32 v104, 0x468, v98
	ds_read2_b32 v[98:99], v99 offset1:1
	ds_read2_b32 v[100:101], v100 offset1:1
	ds_read2_b32 v[102:103], v102 offset1:1
	ds_read2_b32 v[104:105], v104 offset1:1
	ds_read2_b32 v[114:115], v114 offset1:1
	ds_read2_b32 v[116:117], v116 offset1:1
	ds_read2_b32 v[118:119], v118 offset1:1
	ds_read2_b32 v[120:121], v120 offset1:1
	s_waitcnt lgkmcnt(0)
	v_pk_add_f32 v[78:79], v[78:79], v[104:105]
	v_pk_add_f32 v[76:77], v[76:77], v[102:103]
	v_pk_add_f32 v[74:75], v[74:75], v[100:101]
	v_pk_add_f32 v[72:73], v[72:73], v[98:99]
	v_pk_add_f32 v[70:71], v[70:71], v[120:121]
	v_pk_add_f32 v[68:69], v[68:69], v[118:119]
	v_pk_add_f32 v[66:67], v[66:67], v[116:117]
	v_pk_add_f32 v[64:65], v[64:65], v[114:115]
.LBB0_1932:
	s_movk_i32 s64, 0x70
	ds_read_b128 v[98:101], v107 offset:16384
	ds_read_b128 v[102:105], v108 offset:16384
	ds_read_b128 v[114:117], v109 offset:16384
	ds_read_b128 v[118:121], v110 offset:16384
	ds_read_b64_tr_b16 v[122:123], v96 offset:0x2000
	ds_read_b64_tr_b16 v[124:125], v96 offset:0x2800
	ds_read_b64_tr_b16 v[132:133], v96 offset:0x3000
	ds_read_b64_tr_b16 v[134:135], v96 offset:0x3800
	ds_read_b64_tr_b16 v[136:137], v96 offset:0x2200
	ds_read_b64_tr_b16 v[138:139], v96 offset:0x2a00
	ds_read_b64_tr_b16 v[140:141], v96 offset:0x3200
	ds_read_b64_tr_b16 v[142:143], v96 offset:0x3a00
	ds_read_b64_tr_b16 v[144:145], v96 offset:0x2400
	ds_read_b64_tr_b16 v[146:147], v96 offset:0x2c00
	ds_read_b64_tr_b16 v[148:149], v96 offset:0x3400
	ds_read_b64_tr_b16 v[150:151], v96 offset:0x3c00
	ds_read_b64_tr_b16 v[152:153], v96 offset:0x2600
	ds_read_b64_tr_b16 v[154:155], v96 offset:0x2e00
	ds_read_b64_tr_b16 v[156:157], v96 offset:0x3600
	ds_read_b64_tr_b16 v[158:159], v96 offset:0x3e00
	s_nop 5
	s_setprio 2
	v_exp_f32_e32 v64, v64
	v_exp_f32_e32 v65, v65
	v_exp_f32_e32 v66, v66
	v_exp_f32_e32 v67, v67
	v_exp_f32_e32 v68, v68
	v_exp_f32_e32 v69, v69
	v_add_f32_e32 v96, v65, v64
	v_exp_f32_e32 v70, v70
	v_add_f32_e32 v96, v66, v96
	v_exp_f32_e32 v71, v71
	v_add_f32_e32 v96, v67, v96
	v_exp_f32_e32 v72, v72
	v_add_f32_e32 v96, v68, v96
	v_exp_f32_e32 v73, v73
	v_add_f32_e32 v96, v69, v96
	v_exp_f32_e32 v74, v74
	v_add_f32_e32 v96, v70, v96
	v_exp_f32_e32 v75, v75
	v_add_f32_e32 v96, v71, v96
	v_exp_f32_e32 v76, v76
	v_add_f32_e32 v96, v72, v96
	v_exp_f32_e32 v77, v77
	v_add_f32_e32 v96, v73, v96
	v_exp_f32_e32 v78, v78
	v_add_f32_e32 v96, v74, v96
	v_exp_f32_e32 v79, v79
	v_add_f32_e32 v96, v75, v96
	v_add_f32_e32 v96, v76, v96
	v_add_f32_e32 v96, v77, v96
	v_add_f32_e32 v96, v78, v96
	v_add_f32_e32 v96, v79, v96
	v_add_f32_e32 v96, v97, v96
	v_cvt_pk_bf16_f32 v64, v64, v65
	v_cvt_pk_bf16_f32 v65, v66, v67
	v_cvt_pk_bf16_f32 v66, v68, v69
	v_cvt_pk_bf16_f32 v67, v70, v71
	v_cvt_pk_bf16_f32 v68, v72, v73
	v_cvt_pk_bf16_f32 v69, v74, v75
	v_cvt_pk_bf16_f32 v70, v76, v77
	v_cvt_pk_bf16_f32 v71, v78, v79
	v_permlane32_swap_b32_e32 v64, v66
	v_permlane32_swap_b32_e32 v65, v67
	v_permlane32_swap_b32_e32 v68, v70
	v_permlane32_swap_b32_e32 v69, v71
	s_waitcnt lgkmcnt(0)
	s_setprio 1
	s_cmp_lt_u32 s33, 0x100
	s_cbranch_scc1 .Lstg_d0_m61_13
	s_waitcnt vmcnt(0)
	s_barrier

; DI void expsum(f32x16& p, float& l_reg, bf16x8& pa0, bf16x8& pa1) {
; #pragma unroll
;     for (int r = 0; r < 16; ++r) p[r] = __builtin_amdgcn_exp2f(p[r]);
;     float ps = 0.f;
; #pragma unroll
;     for (int r = 0; r < 16; ++r) ps += p[r];
;     l_reg += ps; asm volatile("" : "+v"(l_reg));
;     ...
;     ATT_PK4(p, 0, pa0); ATT_PK4(p, 8, pa1);
;     ...
; }
.LBB0_1936:
	ds_read_b128 v[100:103], v107 offset:20480
	ds_read_b128 v[114:117], v108 offset:20480
	ds_read_b128 v[118:121], v109 offset:20480
	ds_read_b128 v[122:125], v110 offset:20480
	v_add_u32_e32 v98, 0x8000, v106
	ds_read_b64_tr_b16 v[132:133], v98 offset:0
	ds_read_b64_tr_b16 v[134:135], v98 offset:0x800
	ds_read_b64_tr_b16 v[136:137], v98 offset:0x1000
	ds_read_b64_tr_b16 v[138:139], v98 offset:0x1800
	ds_read_b64_tr_b16 v[140:141], v98 offset:0x200
	ds_read_b64_tr_b16 v[142:143], v98 offset:0xa00
	ds_read_b64_tr_b16 v[144:145], v98 offset:0x1200
	ds_read_b64_tr_b16 v[146:147], v98 offset:0x1a00
	ds_read_b64_tr_b16 v[148:149], v98 offset:0x400
	ds_read_b64_tr_b16 v[150:151], v98 offset:0xc00
	ds_read_b64_tr_b16 v[152:153], v98 offset:0x1400
	ds_read_b64_tr_b16 v[154:155], v98 offset:0x1c00
	ds_read_b64_tr_b16 v[156:157], v98 offset:0x600
	ds_read_b64_tr_b16 v[158:159], v98 offset:0xe00
	ds_read_b64_tr_b16 v[162:163], v98 offset:0x1600
	ds_read_b64_tr_b16 v[164:165], v98 offset:0x1e00
	s_setprio 2
	v_exp_f32_e32 v64, v64
	v_exp_f32_e32 v65, v65
	v_exp_f32_e32 v66, v66
	v_exp_f32_e32 v67, v67
	v_exp_f32_e32 v68, v68
	v_exp_f32_e32 v69, v69
	v_add_f32_e32 v99, v65, v64
	v_exp_f32_e32 v70, v70
	v_add_f32_e32 v99, v66, v99
	v_exp_f32_e32 v71, v71
	v_add_f32_e32 v99, v67, v99
	v_exp_f32_e32 v72, v72
	v_add_f32_e32 v99, v68, v99
	v_exp_f32_e32 v73, v73
	v_add_f32_e32 v99, v69, v99
	v_exp_f32_e32 v74, v74
	v_add_f32_e32 v99, v70, v99
	v_exp_f32_e32 v75, v75
	v_add_f32_e32 v99, v71, v99
	v_exp_f32_e32 v76, v76
	v_add_f32_e32 v99, v72, v99
	v_exp_f32_e32 v77, v77
	v_add_f32_e32 v99, v73, v99
	v_exp_f32_e32 v78, v78
	v_add_f32_e32 v99, v74, v99
	v_exp_f32_e32 v79, v79
	v_add_f32_e32 v99, v75, v99
	v_add_f32_e32 v99, v76, v99
	v_add_f32_e32 v99, v77, v99
	v_add_f32_e32 v99, v78, v99
	v_add_f32_e32 v99, v79, v99
	v_add_f32_e32 v96, v99, v96
	v_cvt_pk_bf16_f32 v64, v64, v65
	v_cvt_pk_bf16_f32 v65, v66, v67
	v_cvt_pk_bf16_f32 v66, v68, v69
	v_cvt_pk_bf16_f32 v67, v70, v71
	v_cvt_pk_bf16_f32 v68, v72, v73
	v_cvt_pk_bf16_f32 v69, v74, v75
	v_cvt_pk_bf16_f32 v70, v76, v77
	v_cvt_pk_bf16_f32 v71, v78, v79
	v_permlane32_swap_b32_e32 v64, v66
	v_permlane32_swap_b32_e32 v65, v67
	v_permlane32_swap_b32_e32 v68, v70
	v_permlane32_swap_b32_e32 v69, v71
	s_waitcnt lgkmcnt(0)
	s_setprio 1
	v_mfma_f32_32x32x16_bf16 v[0:15], v[64:67], v[132:135], v[0:15]
	s_and_b64 vcc, exec, s[2:3]
	v_mfma_f32_32x32x16_bf16 v[48:63], v[64:67], v[140:143], v[48:63]
	v_mfma_f32_32x32x16_bf16 v[32:47], v[64:67], v[148:151], v[32:47]
	v_mfma_f32_32x32x16_bf16 v[16:31], v[64:67], v[156:159], v[16:31]
	v_mfma_f32_32x32x16_bf16 v[0:15], v[68:71], v[136:139], v[0:15]
	v_mfma_f32_32x32x16_bf16 v[48:63], v[68:71], v[144:147], v[48:63]
	v_mfma_f32_32x32x16_bf16 v[32:47], v[68:71], v[152:155], v[32:47]
	v_mfma_f32_32x32x16_bf16 v[16:31], v[68:71], v[162:165], v[16:31]
	s_waitcnt lgkmcnt(0)
	v_mfma_f32_32x32x16_bf16 v[64:79], v[100:103], v[92:95], 0
	v_mfma_f32_32x32x16_bf16 v[64:79], v[114:117], v[88:91], v[64:79]
	v_mfma_f32_32x32x16_bf16 v[64:79], v[118:121], v[84:87], v[64:79]
	v_mfma_f32_32x32x16_bf16 v[64:79], v[122:125], v[80:83], v[64:79]
	s_setprio 0
	s_cbranch_vccnz .LBB0_1938
	v_add3_u32 v97, s88, v97, v130
	v_add_u32_e32 v118, 0x408, v97
	v_add_u32_e32 v120, 0x420, v97
	v_add_u32_e32 v122, 0x428, v97
	v_add_u32_e32 v100, 0x440, v97
	v_add_u32_e32 v102, 0x448, v97
	v_add_u32_e32 v104, 0x460, v97
	v_add_u32_e32 v99, 0x400, v97
	v_add_u32_e32 v97, 0x468, v97
	ds_read2_b32 v[100:101], v100 offset1:1
	ds_read2_b32 v[102:103], v102 offset1:1
	ds_read2_b32 v[104:105], v104 offset1:1
	ds_read2_b32 v[114:115], v97 offset1:1
	ds_read2_b32 v[116:117], v99 offset1:1
	ds_read2_b32 v[118:119], v118 offset1:1
	ds_read2_b32 v[120:121], v120 offset1:1
	ds_read2_b32 v[122:123], v122 offset1:1
	s_waitcnt lgkmcnt(0)
	v_pk_add_f32 v[78:79], v[78:79], v[114:115]
	v_pk_add_f32 v[76:77], v[76:77], v[104:105]
	v_pk_add_f32 v[74:75], v[74:75], v[102:103]
	v_pk_add_f32 v[72:73], v[72:73], v[100:101]
	v_pk_add_f32 v[70:71], v[70:71], v[122:123]
	v_pk_add_f32 v[68:69], v[68:69], v[120:121]
	v_pk_add_f32 v[66:67], v[66:67], v[118:119]
	v_pk_add_f32 v[64:65], v[64:65], v[116:117]
.LBB0_1938:
	ds_read_b128 v[100:103], v107 offset:24576
	ds_read_b128 v[114:117], v108 offset:24576
	ds_read_b128 v[118:121], v109 offset:24576
	ds_read_b128 v[122:125], v110 offset:24576
	ds_read_b64_tr_b16 v[132:133], v98 offset:0x2000
	ds_read_b64_tr_b16 v[134:135], v98 offset:0x2800
	ds_read_b64_tr_b16 v[136:137], v98 offset:0x3000
	ds_read_b64_tr_b16 v[138:139], v98 offset:0x3800
	ds_read_b64_tr_b16 v[140:141], v98 offset:0x2200
	ds_read_b64_tr_b16 v[142:143], v98 offset:0x2a00
	ds_read_b64_tr_b16 v[144:145], v98 offset:0x3200
	ds_read_b64_tr_b16 v[146:147], v98 offset:0x3a00
	ds_read_b64_tr_b16 v[148:149], v98 offset:0x2400
	ds_read_b64_tr_b16 v[150:151], v98 offset:0x2c00
	ds_read_b64_tr_b16 v[152:153], v98 offset:0x3400
	ds_read_b64_tr_b16 v[154:155], v98 offset:0x3c00
	ds_read_b64_tr_b16 v[156:157], v98 offset:0x2600
	ds_read_b64_tr_b16 v[158:159], v98 offset:0x2e00
	ds_read_b64_tr_b16 v[162:163], v98 offset:0x3600
	ds_read_b64_tr_b16 v[164:165], v98 offset:0x3e00
	s_nop 6
	s_setprio 2
	v_exp_f32_e32 v64, v64
	v_exp_f32_e32 v65, v65
	v_exp_f32_e32 v66, v66
	v_exp_f32_e32 v67, v67
	v_exp_f32_e32 v68, v68
	v_exp_f32_e32 v69, v69
	v_add_f32_e32 v97, v65, v64
	v_exp_f32_e32 v70, v70
	v_add_f32_e32 v97, v66, v97
	v_exp_f32_e32 v71, v71
	v_add_f32_e32 v97, v67, v97
	v_exp_f32_e32 v72, v72
	v_add_f32_e32 v97, v68, v97
	v_exp_f32_e32 v73, v73
	v_add_f32_e32 v97, v69, v97
	v_exp_f32_e32 v74, v74
	v_add_f32_e32 v97, v70, v97
	v_exp_f32_e32 v75, v75
	v_add_f32_e32 v97, v71, v97
	v_exp_f32_e32 v76, v76
	v_add_f32_e32 v97, v72, v97
	v_exp_f32_e32 v77, v77
	v_add_f32_e32 v97, v73, v97
	v_exp_f32_e32 v78, v78
	v_add_f32_e32 v97, v74, v97
	v_exp_f32_e32 v79, v79
	v_add_f32_e32 v97, v75, v97
	v_add_f32_e32 v97, v76, v97
	v_add_f32_e32 v97, v77, v97
	v_add_f32_e32 v97, v78, v97
	v_add_f32_e32 v97, v79, v97
	v_add_f32_e32 v96, v96, v97
	v_cvt_pk_bf16_f32 v64, v64, v65
	v_cvt_pk_bf16_f32 v65, v66, v67
	v_cvt_pk_bf16_f32 v66, v68, v69
	v_cvt_pk_bf16_f32 v67, v70, v71
	v_cvt_pk_bf16_f32 v68, v72, v73
	v_cvt_pk_bf16_f32 v69, v74, v75
	v_cvt_pk_bf16_f32 v70, v76, v77
	v_cvt_pk_bf16_f32 v71, v78, v79
	v_permlane32_swap_b32_e32 v64, v66
	v_permlane32_swap_b32_e32 v65, v67
	v_permlane32_swap_b32_e32 v68, v70
	v_permlane32_swap_b32_e32 v69, v71
	s_waitcnt lgkmcnt(0)
	s_setprio 1
	s_cmp_lt_u32 s33, 0x100
	s_cbranch_scc1 .Lstg_d0_m62_15
	s_waitcnt vmcnt(0)
	s_barrier

; DI void expsum(f32x16& p, float& l_reg, bf16x8& pa0, bf16x8& pa1) {
; #pragma unroll
;     for (int r = 0; r < 16; ++r) p[r] = __builtin_amdgcn_exp2f(p[r]);
;     float ps = 0.f;
; #pragma unroll
;     for (int r = 0; r < 16; ++r) ps += p[r];
;     l_reg += ps; asm volatile("" : "+v"(l_reg));
;     ...
;     ATT_PK4(p, 0, pa0); ATT_PK4(p, 8, pa1);
;     ...
; }
.LBB0_1942:
	ds_read_b128 v[98:101], v107 offset:28672
	ds_read_b128 v[102:105], v108 offset:28672
	ds_read_b128 v[112:115], v109 offset:28672
	ds_read_b128 v[108:111], v110 offset:28672
	ds_read_b64_tr_b16 v[116:117], v106 offset:0
	ds_read_b64_tr_b16 v[118:119], v106 offset:0x800
	ds_read_b64_tr_b16 v[120:121], v106 offset:0x1000
	ds_read_b64_tr_b16 v[122:123], v106 offset:0x1800
	ds_read_b64_tr_b16 v[124:125], v106 offset:0x200
	ds_read_b64_tr_b16 v[126:127], v106 offset:0xa00
	ds_read_b64_tr_b16 v[132:133], v106 offset:0x1200
	ds_read_b64_tr_b16 v[134:135], v106 offset:0x1a00
	ds_read_b64_tr_b16 v[136:137], v106 offset:0x400
	ds_read_b64_tr_b16 v[138:139], v106 offset:0xc00
	ds_read_b64_tr_b16 v[140:141], v106 offset:0x1400
	ds_read_b64_tr_b16 v[142:143], v106 offset:0x1c00
	ds_read_b64_tr_b16 v[144:145], v106 offset:0x600
	ds_read_b64_tr_b16 v[146:147], v106 offset:0xe00
	ds_read_b64_tr_b16 v[148:149], v106 offset:0x1600
	ds_read_b64_tr_b16 v[150:151], v106 offset:0x1e00
	s_setprio 2
	v_exp_f32_e32 v64, v64
	v_exp_f32_e32 v65, v65
	v_exp_f32_e32 v66, v66
	v_exp_f32_e32 v67, v67
	v_exp_f32_e32 v68, v68
	v_exp_f32_e32 v69, v69
	v_add_f32_e32 v107, v65, v64
	v_exp_f32_e32 v70, v70
	v_add_f32_e32 v107, v66, v107
	v_exp_f32_e32 v71, v71
	v_add_f32_e32 v107, v67, v107
	v_exp_f32_e32 v72, v72
	v_add_f32_e32 v107, v68, v107
	v_exp_f32_e32 v73, v73
	v_add_f32_e32 v107, v69, v107
	v_exp_f32_e32 v74, v74
	v_add_f32_e32 v107, v70, v107
	v_exp_f32_e32 v75, v75
	v_add_f32_e32 v107, v71, v107
	v_exp_f32_e32 v76, v76
	v_add_f32_e32 v107, v72, v107
	v_exp_f32_e32 v77, v77
	v_add_f32_e32 v107, v73, v107
	v_exp_f32_e32 v78, v78
	v_add_f32_e32 v107, v74, v107
	v_exp_f32_e32 v79, v79
	v_add_f32_e32 v107, v75, v107
	v_add_f32_e32 v107, v76, v107
	v_add_f32_e32 v107, v77, v107
	v_add_f32_e32 v107, v78, v107
	v_add_f32_e32 v107, v79, v107
	v_add_f32_e32 v96, v107, v96
	v_cvt_pk_bf16_f32 v64, v64, v65
	v_cvt_pk_bf16_f32 v65, v66, v67
	v_cvt_pk_bf16_f32 v66, v68, v69
	v_cvt_pk_bf16_f32 v67, v70, v71
	v_cvt_pk_bf16_f32 v68, v72, v73
	v_cvt_pk_bf16_f32 v69, v74, v75
	v_cvt_pk_bf16_f32 v70, v76, v77
	v_cvt_pk_bf16_f32 v71, v78, v79
	v_permlane32_swap_b32_e32 v64, v66
	v_permlane32_swap_b32_e32 v65, v67
	v_permlane32_swap_b32_e32 v68, v70
	v_permlane32_swap_b32_e32 v69, v71
	s_waitcnt lgkmcnt(0)
	s_setprio 1
	v_mfma_f32_32x32x16_bf16 v[0:15], v[64:67], v[116:119], v[0:15]
	s_and_b64 vcc, exec, s[2:3]
	v_mfma_f32_32x32x16_bf16 v[48:63], v[64:67], v[124:127], v[48:63]
	v_mfma_f32_32x32x16_bf16 v[32:47], v[64:67], v[136:139], v[32:47]
	v_mfma_f32_32x32x16_bf16 v[16:31], v[64:67], v[144:147], v[16:31]
	v_mfma_f32_32x32x16_bf16 v[0:15], v[68:71], v[120:123], v[0:15]
	v_mfma_f32_32x32x16_bf16 v[48:63], v[68:71], v[132:135], v[48:63]
	v_mfma_f32_32x32x16_bf16 v[32:47], v[68:71], v[140:143], v[32:47]
	v_mfma_f32_32x32x16_bf16 v[16:31], v[68:71], v[148:151], v[16:31]
	s_waitcnt lgkmcnt(0)
	v_mfma_f32_32x32x16_bf16 v[64:79], v[98:101], v[92:95], 0
	v_mfma_f32_32x32x16_bf16 v[64:79], v[102:105], v[88:91], v[64:79]
	v_mfma_f32_32x32x16_bf16 v[64:79], v[112:115], v[84:87], v[64:79]
	v_mfma_f32_32x32x16_bf16 v[64:79], v[108:111], v[80:83], v[64:79]
	s_setprio 0
	s_cbranch_vccnz .LBB0_1944
	v_add3_u32 v80, s88, v97, v130
	v_add_u32_e32 v88, 0x400, v80
	v_add_u32_e32 v90, 0x408, v80
	v_add_u32_e32 v92, 0x420, v80
	v_add_u32_e32 v94, 0x428, v80
	v_add_u32_e32 v81, 0x440, v80
	v_add_u32_e32 v82, 0x448, v80
	v_add_u32_e32 v84, 0x460, v80
	v_add_u32_e32 v86, 0x468, v80
	ds_read2_b32 v[80:81], v81 offset1:1
	ds_read2_b32 v[82:83], v82 offset1:1
	ds_read2_b32 v[84:85], v84 offset1:1
	ds_read2_b32 v[86:87], v86 offset1:1
	ds_read2_b32 v[88:89], v88 offset1:1
	ds_read2_b32 v[90:91], v90 offset1:1
	ds_read2_b32 v[92:93], v92 offset1:1
	ds_read2_b32 v[94:95], v94 offset1:1
	s_waitcnt lgkmcnt(0)
	v_pk_add_f32 v[78:79], v[78:79], v[86:87]
	v_pk_add_f32 v[76:77], v[76:77], v[84:85]
	v_pk_add_f32 v[74:75], v[74:75], v[82:83]
	v_pk_add_f32 v[72:73], v[72:73], v[80:81]
	v_pk_add_f32 v[70:71], v[70:71], v[94:95]
	v_pk_add_f32 v[68:69], v[68:69], v[92:93]
	v_pk_add_f32 v[66:67], v[66:67], v[90:91]
	v_pk_add_f32 v[64:65], v[64:65], v[88:89]
.LBB0_1944:
	s_lshl_b32 s0, s54, 2
	s_add_i32 s0, s0, 0
	s_add_i32 s0, s0, 0x24000
	ds_read_b64_tr_b16 v[80:81], v106 offset:0x2000
	ds_read_b64_tr_b16 v[82:83], v106 offset:0x2800
	ds_read_b64_tr_b16 v[84:85], v106 offset:0x3000
	ds_read_b64_tr_b16 v[86:87], v106 offset:0x3800
	ds_read_b64_tr_b16 v[88:89], v106 offset:0x2200
	ds_read_b64_tr_b16 v[90:91], v106 offset:0x2a00
	ds_read_b64_tr_b16 v[92:93], v106 offset:0x3200
	ds_read_b64_tr_b16 v[94:95], v106 offset:0x3a00
	ds_read_b64_tr_b16 v[98:99], v106 offset:0x2400
	ds_read_b64_tr_b16 v[100:101], v106 offset:0x2c00
	ds_read_b64_tr_b16 v[102:103], v106 offset:0x3400
	ds_read_b64_tr_b16 v[104:105], v106 offset:0x3c00
	ds_read_b64_tr_b16 v[108:109], v106 offset:0x2600
	ds_read_b64_tr_b16 v[110:111], v106 offset:0x2e00
	ds_read_b64_tr_b16 v[112:113], v106 offset:0x3600
	ds_read_b64_tr_b16 v[114:115], v106 offset:0x3e00
	s_nop 7
	s_setprio 2
	v_exp_f32_e32 v97, v64
	v_exp_f32_e32 v65, v65
	v_exp_f32_e32 v106, v66
	v_exp_f32_e32 v67, v67
	v_exp_f32_e32 v68, v68
	v_exp_f32_e32 v69, v69
	v_add_f32_e32 v64, v65, v97
	v_exp_f32_e32 v70, v70
	v_add_f32_e32 v64, v106, v64
	v_exp_f32_e32 v71, v71
	v_add_f32_e32 v64, v67, v64
	v_exp_f32_e32 v72, v72
	v_add_f32_e32 v64, v68, v64
	v_exp_f32_e32 v73, v73
	v_add_f32_e32 v64, v69, v64
	v_exp_f32_e32 v74, v74
	v_add_f32_e32 v64, v70, v64
	v_exp_f32_e32 v75, v75
	v_add_f32_e32 v64, v71, v64
	v_exp_f32_e32 v76, v76
	v_add_f32_e32 v64, v72, v64
	v_exp_f32_e32 v77, v77
	v_add_f32_e32 v64, v73, v64
	v_exp_f32_e32 v78, v78
	v_add_f32_e32 v64, v74, v64
	v_exp_f32_e32 v79, v79
	v_add_f32_e32 v64, v75, v64
	v_add_f32_e32 v64, v76, v64
	v_add_f32_e32 v64, v77, v64
	v_add_f32_e32 v64, v78, v64
	v_add_f32_e32 v64, v79, v64
	v_add_f32_e32 v64, v96, v64
	v_cvt_pk_bf16_f32 v66, v97, v65
	v_cvt_pk_bf16_f32 v67, v106, v67
	v_cvt_pk_bf16_f32 v68, v68, v69
	v_cvt_pk_bf16_f32 v69, v70, v71
	v_cvt_pk_bf16_f32 v70, v72, v73
	v_cvt_pk_bf16_f32 v71, v74, v75
	v_cvt_pk_bf16_f32 v72, v76, v77
	v_cvt_pk_bf16_f32 v73, v78, v79
	v_permlane32_swap_b32_e32 v66, v68
	v_permlane32_swap_b32_e32 v67, v69
	v_permlane32_swap_b32_e32 v70, v72
	v_permlane32_swap_b32_e32 v71, v73
	s_waitcnt lgkmcnt(0)
; template <int TAG = 0> DI int fresh_tid(int wv) { int l; asm volatile("v_mbcnt_lo_u32_b32 %0, -1, 0\n\tv_mbcnt_hi_u32_b32 %0, -1, %0 ; site %1" : "=v"(l) : "n"(TAG)); return wv * 64 + l; }
; DI unsigned short f2bf(float x) { unsigned u = __float_as_uint(x); u += 0x7fffu + ((u >> 16) & 1u); return (unsigned short)(u >> 16); }
; DI int crow(int r, int hi) { return (r & 3) + 8 * (r >> 2) + 4 * hi; }
; DI float swap_sum(float v) { auto rr = __builtin_amdgcn_permlane32_swap(__float_as_uint(v), __float_as_uint(v), false, false); return __uint_as_float(rr[0]) + __uint_as_float(rr[1]); }
; template <int DQK, int MODE, int LDQ, int LDK, int LDV> ...
;     ...
;     __builtin_amdgcn_s_setprio(0);
;     ...
;     l_reg = swap_sum(l_reg);
;     { const int lane2 = fresh_tid<110 + MODE>(wv) & 63, r32 = lane2 & 31, hi = lane2 >> 5;
;     if (hi == 0) li_l[r32] = l_reg;
;     asm volatile("s_waitcnt lgkmcnt(0)" ::: "memory");
;     float s0v[MODE == 2 ? 16 : 1][4];
;     if constexpr (MODE == 2) {
; #pragma unroll
;         for (int r = 0; r < 16; ++r)
; #pragma unroll
;             for (int d0 = 0; d0 < 4; ++d0) s0v[r][d0] = S0[(size_t)(wid * 32 + crow(r, hi)) * 512 + d0 * 32 + r32];
;     }
; #pragma unroll
;     for (int r = 0; r < 16; ++r) { const int orow = wid * 32 + crow(r, hi); const float rl = __builtin_amdgcn_rcpf(li_l[crow(r, hi)]);
;         if constexpr (MODE == 0) {
; #pragma unroll
;             for (int d0 = 0; d0 < 4; ++d0) AOb[(size_t)orow * 1024 + d0 * 32 + r32] = f2bf(o[d0][r] * rl);
;         } else if constexpr (MODE == 1) {
; #pragma unroll
;             for (int d0 = 0; d0 < 4; ++d0) S0[(size_t)orow * 512 + d0 * 32 + r32] = o[d0][r] * rl;
	s_setprio 1
	v_mfma_f32_32x32x16_bf16 v[0:15], v[66:69], v[80:83], v[0:15]
	v_mfma_f32_32x32x16_bf16 v[48:63], v[66:69], v[88:91], v[48:63]
	v_mfma_f32_32x32x16_bf16 v[32:47], v[66:69], v[98:101], v[32:47]
	v_mfma_f32_32x32x16_bf16 v[16:31], v[66:69], v[108:111], v[16:31]
	v_mfma_f32_32x32x16_bf16 v[0:15], v[70:73], v[84:87], v[0:15]
	v_mfma_f32_32x32x16_bf16 v[48:63], v[70:73], v[92:95], v[48:63]
	v_mfma_f32_32x32x16_bf16 v[32:47], v[70:73], v[102:105], v[32:47]
	v_mfma_f32_32x32x16_bf16 v[16:31], v[70:73], v[112:115], v[16:31]
	s_setprio 0
	v_mbcnt_lo_u32_b32 v66, -1, 0
	v_mbcnt_hi_u32_b32 v66, -1, v66
	v_mov_b32_e32 v67, v64
	v_and_b32_e32 v65, 31, v66
	v_bfe_u32 v66, v66, 5, 1
	v_permlane32_swap_b32_e32 v64, v67
	v_cmp_eq_u32_e32 vcc, 0, v66
	s_and_saveexec_b64 s[2:3], vcc
	v_lshl_add_u32 v68, v65, 2, s0
	v_add_f32_e32 v64, v64, v67
	ds_write_b32 v68, v64
	s_or_b64 exec, exec, s[2:3]
	s_waitcnt lgkmcnt(0)
	v_lshl_add_u32 v68, v66, 4, s0
	ds_read_b128 v[70:73], v68
	ds_read_b128 v[74:77], v68 offset:32
	s_lshl_b64 s[58:59], s[40:41], 11
	v_readlane_b32 s1, v255, 2
	s_add_u32 s1, s1, s58
	v_readlane_b32 s2, v255, 0
	s_addc_u32 s2, s2, s59
	s_lshl_b32 s3, s87, 2
	s_waitcnt lgkmcnt(0)
	v_rcp_f32_e32 v69, v70
	s_add_u32 s54, s1, s3
	v_lshl_or_b32 v66, v66, 2, s94
	s_addc_u32 s55, s2, 0
	v_lshlrev_b32_e32 v130, 2, v65
	v_ashrrev_i32_e32 v67, 31, v66
	v_lshl_add_u64 v[64:65], s[54:55], 0, v[130:131]
	v_lshlrev_b64 v[78:79], 11, v[66:67]
	v_lshl_add_u64 v[78:79], v[64:65], 0, v[78:79]
	v_mul_f32_e32 v0, v0, v69
	global_store_dword v[78:79], v0, off
	v_mul_f32_e32 v0, v48, v69
	global_store_dword v[78:79], v0, off offset:128
	v_mul_f32_e32 v0, v32, v69
	global_store_dword v[78:79], v0, off offset:256
	v_mul_f32_e32 v0, v16, v69
	global_store_dword v[78:79], v0, off offset:384
	v_rcp_f32_e32 v0, v71
	v_or_b32_e32 v70, 1, v66
	v_ashrrev_i32_e32 v71, 31, v70
	v_lshlrev_b64 v[70:71], 11, v[70:71]
	v_lshl_add_u64 v[70:71], v[64:65], 0, v[70:71]
	v_mul_f32_e32 v1, v1, v0
	global_store_dword v[70:71], v1, off
	v_mul_f32_e32 v1, v49, v0
	global_store_dword v[70:71], v1, off offset:128
	v_mul_f32_e32 v1, v33, v0
	v_mul_f32_e32 v0, v17, v0
	v_rcp_f32_e32 v16, v72
	global_store_dword v[70:71], v0, off offset:384
	v_or_b32_e32 v0, 2, v66
	global_store_dword v[70:71], v1, off offset:256
	v_ashrrev_i32_e32 v1, 31, v0
	v_lshlrev_b64 v[0:1], 11, v[0:1]
	v_lshl_add_u64 v[0:1], v[64:65], 0, v[0:1]
	v_mul_f32_e32 v2, v2, v16
	global_store_dword v[0:1], v2, off
	v_mul_f32_e32 v2, v50, v16
	global_store_dword v[0:1], v2, off offset:128
	v_mul_f32_e32 v2, v34, v16
	global_store_dword v[0:1], v2, off offset:256
	v_mul_f32_e32 v2, v18, v16
	global_store_dword v[0:1], v2, off offset:384
	v_rcp_f32_e32 v2, v73
	v_or_b32_e32 v0, 3, v66
	v_ashrrev_i32_e32 v1, 31, v0
	v_lshlrev_b64 v[0:1], 11, v[0:1]
	v_lshl_add_u64 v[0:1], v[64:65], 0, v[0:1]
	v_mul_f32_e32 v3, v3, v2
	global_store_dword v[0:1], v3, off
	v_mul_f32_e32 v3, v51, v2
	global_store_dword v[0:1], v3, off offset:128
	v_mul_f32_e32 v3, v35, v2
	v_mul_f32_e32 v2, v19, v2
	global_store_dword v[0:1], v2, off offset:384
	v_rcp_f32_e32 v2, v74
	global_store_dword v[0:1], v3, off offset:256
	v_or_b32_e32 v0, 8, v66
	v_ashrrev_i32_e32 v1, 31, v0
	v_lshlrev_b64 v[0:1], 11, v[0:1]
	v_lshl_add_u64 v[0:1], v[64:65], 0, v[0:1]
	v_mul_f32_e32 v3, v4, v2
	global_store_dword v[0:1], v3, off
	v_mul_f32_e32 v3, v52, v2
	global_store_dword v[0:1], v3, off offset:128
	v_mul_f32_e32 v3, v36, v2
	v_mul_f32_e32 v2, v20, v2
	global_store_dword v[0:1], v2, off offset:384
	v_rcp_f32_e32 v2, v75
	global_store_dword v[0:1], v3, off offset:256
	v_or_b32_e32 v0, 9, v66
	v_ashrrev_i32_e32 v1, 31, v0
	v_lshlrev_b64 v[0:1], 11, v[0:1]
	v_lshl_add_u64 v[0:1], v[64:65], 0, v[0:1]
	v_mul_f32_e32 v3, v5, v2
	global_store_dword v[0:1], v3, off
	v_mul_f32_e32 v3, v53, v2
	global_store_dword v[0:1], v3, off offset:128
	v_mul_f32_e32 v3, v37, v2
	v_mul_f32_e32 v2, v21, v2
	global_store_dword v[0:1], v2, off offset:384
	v_rcp_f32_e32 v2, v76
	global_store_dword v[0:1], v3, off offset:256
	v_or_b32_e32 v0, 10, v66
	v_ashrrev_i32_e32 v1, 31, v0
	v_lshlrev_b64 v[0:1], 11, v[0:1]
	v_lshl_add_u64 v[0:1], v[64:65], 0, v[0:1]
	v_mul_f32_e32 v3, v6, v2
	global_store_dword v[0:1], v3, off
	v_mul_f32_e32 v3, v54, v2
	global_store_dword v[0:1], v3, off offset:128
	v_mul_f32_e32 v3, v38, v2
	v_mul_f32_e32 v2, v22, v2
	v_rcp_f32_e32 v6, v77
	global_store_dword v[0:1], v3, off offset:256
	global_store_dword v[0:1], v2, off offset:384
	v_or_b32_e32 v0, 11, v66
	v_ashrrev_i32_e32 v1, 31, v0
	v_lshlrev_b64 v[0:1], 11, v[0:1]
	v_lshl_add_u64 v[4:5], v[64:65], 0, v[0:1]
	v_mul_f32_e32 v0, v7, v6
	global_store_dword v[4:5], v0, off
	v_mul_f32_e32 v0, v55, v6
	global_store_dword v[4:5], v0, off offset:128
	v_mul_f32_e32 v0, v39, v6
	global_store_dword v[4:5], v0, off offset:256
	ds_read_b128 v[0:3], v68 offset:64
	v_mul_f32_e32 v6, v23, v6
	global_store_dword v[4:5], v6, off offset:384
	ds_read_b128 v[4:7], v68 offset:96
	v_or_b32_e32 v16, 16, v66
	s_waitcnt lgkmcnt(0)
; DI unsigned short f2bf(float x) { unsigned u = __float_as_uint(x); u += 0x7fffu + ((u >> 16) & 1u); return (unsigned short)(u >> 16); }
; DI int crow(int r, int hi) { return (r & 3) + 8 * (r >> 2) + 4 * hi; }
; template <int DQK, int MODE, int LDQ, int LDK, int LDV> ...
;     ...
;     for (int r = 0; r < 16; ++r) { const int orow = wid * 32 + crow(r, hi); const float rl = __builtin_amdgcn_rcpf(li_l[crow(r, hi)]);
;         if constexpr (MODE == 0) {
; #pragma unroll
;             for (int d0 = 0; d0 < 4; ++d0) AOb[(size_t)orow * 1024 + d0 * 32 + r32] = f2bf(o[d0][r] * rl);
;         } else if constexpr (MODE == 1) {
; #pragma unroll
;             for (int d0 = 0; d0 < 4; ++d0) S0[(size_t)orow * 512 + d0 * 32 + r32] = o[d0][r] * rl;
; DI void phase4(const Params& p, LAS unsigned char* lds, int wv) {
;     ...
;             __syncthreads();
	v_rcp_f32_e32 v0, v0
	v_ashrrev_i32_e32 v17, 31, v16
	v_lshlrev_b64 v[16:17], 11, v[16:17]
	v_lshl_add_u64 v[16:17], v[64:65], 0, v[16:17]
	v_mul_f32_e32 v8, v8, v0
	global_store_dword v[16:17], v8, off
	v_mul_f32_e32 v8, v56, v0
	global_store_dword v[16:17], v8, off offset:128
	v_mul_f32_e32 v8, v40, v0
	global_store_dword v[16:17], v8, off offset:256
	v_mul_f32_e32 v0, v24, v0
	v_rcp_f32_e32 v8, v1
	global_store_dword v[16:17], v0, off offset:384
	v_or_b32_e32 v0, 17, v66
	v_ashrrev_i32_e32 v1, 31, v0
	v_lshlrev_b64 v[0:1], 11, v[0:1]
	v_lshl_add_u64 v[0:1], v[64:65], 0, v[0:1]
	v_mul_f32_e32 v9, v9, v8
	global_store_dword v[0:1], v9, off
	v_mul_f32_e32 v9, v57, v8
	global_store_dword v[0:1], v9, off offset:128
	v_mul_f32_e32 v9, v41, v8
	v_mul_f32_e32 v8, v25, v8
	v_rcp_f32_e32 v2, v2
	global_store_dword v[0:1], v9, off offset:256
	global_store_dword v[0:1], v8, off offset:384
	v_or_b32_e32 v0, 18, v66
	v_ashrrev_i32_e32 v1, 31, v0
	v_lshlrev_b64 v[0:1], 11, v[0:1]
	v_lshl_add_u64 v[0:1], v[64:65], 0, v[0:1]
	v_mul_f32_e32 v8, v10, v2
	global_store_dword v[0:1], v8, off
	v_mul_f32_e32 v8, v58, v2
	global_store_dword v[0:1], v8, off offset:128
	v_mul_f32_e32 v8, v42, v2
	v_mul_f32_e32 v2, v26, v2
	global_store_dword v[0:1], v2, off offset:384
	v_rcp_f32_e32 v2, v3
	global_store_dword v[0:1], v8, off offset:256
	v_or_b32_e32 v0, 19, v66
	v_ashrrev_i32_e32 v1, 31, v0
	v_lshlrev_b64 v[0:1], 11, v[0:1]
	v_lshl_add_u64 v[0:1], v[64:65], 0, v[0:1]
	v_mul_f32_e32 v3, v11, v2
	global_store_dword v[0:1], v3, off
	v_mul_f32_e32 v3, v59, v2
	global_store_dword v[0:1], v3, off offset:128
	v_mul_f32_e32 v3, v43, v2
	v_mul_f32_e32 v2, v27, v2
	global_store_dword v[0:1], v2, off offset:384
	v_rcp_f32_e32 v2, v4
	global_store_dword v[0:1], v3, off offset:256
	v_or_b32_e32 v0, 24, v66
	v_ashrrev_i32_e32 v1, 31, v0
	v_lshlrev_b64 v[0:1], 11, v[0:1]
	v_lshl_add_u64 v[0:1], v[64:65], 0, v[0:1]
	v_mul_f32_e32 v3, v12, v2
	global_store_dword v[0:1], v3, off
	v_mul_f32_e32 v3, v60, v2
	global_store_dword v[0:1], v3, off offset:128
	v_mul_f32_e32 v3, v44, v2
	v_mul_f32_e32 v2, v28, v2
	global_store_dword v[0:1], v2, off offset:384
	v_rcp_f32_e32 v2, v5
	global_store_dword v[0:1], v3, off offset:256
	v_or_b32_e32 v0, 25, v66
	v_ashrrev_i32_e32 v1, 31, v0
	v_lshlrev_b64 v[0:1], 11, v[0:1]
	v_lshl_add_u64 v[0:1], v[64:65], 0, v[0:1]
	v_mul_f32_e32 v3, v13, v2
	global_store_dword v[0:1], v3, off
	v_mul_f32_e32 v3, v61, v2
	global_store_dword v[0:1], v3, off offset:128
	v_mul_f32_e32 v3, v45, v2
	v_mul_f32_e32 v2, v29, v2
	global_store_dword v[0:1], v2, off offset:384
	v_rcp_f32_e32 v2, v6
	global_store_dword v[0:1], v3, off offset:256
	v_or_b32_e32 v0, 26, v66
	v_ashrrev_i32_e32 v1, 31, v0
	v_lshlrev_b64 v[0:1], 11, v[0:1]
	v_lshl_add_u64 v[0:1], v[64:65], 0, v[0:1]
	v_mul_f32_e32 v3, v14, v2
	global_store_dword v[0:1], v3, off
	v_mul_f32_e32 v3, v62, v2
	global_store_dword v[0:1], v3, off offset:128
	v_mul_f32_e32 v3, v46, v2
	v_mul_f32_e32 v2, v30, v2
	global_store_dword v[0:1], v2, off offset:384
	v_rcp_f32_e32 v2, v7
	global_store_dword v[0:1], v3, off offset:256
	v_or_b32_e32 v0, 27, v66
	v_ashrrev_i32_e32 v1, 31, v0
	v_lshlrev_b64 v[0:1], 11, v[0:1]
	v_lshl_add_u64 v[0:1], v[64:65], 0, v[0:1]
	v_mul_f32_e32 v3, v15, v2
	global_store_dword v[0:1], v3, off
	v_mul_f32_e32 v3, v63, v2
	global_store_dword v[0:1], v3, off offset:128
	v_mul_f32_e32 v3, v47, v2
	v_mul_f32_e32 v2, v31, v2
	global_store_dword v[0:1], v3, off offset:256
	global_store_dword v[0:1], v2, off offset:384
	s_waitcnt vmcnt(0)
	s_barrier
; DI float bf2f(unsigned short h) { return __uint_as_float((unsigned)h << 16); }
; template <int DQK, int MODE, int LDQ, int LDK, int LDV> ...
;     ...
;     int kgo[NKP], vgo[2];
; #pragma unroll
;     for (int i = 0; i < NKP; ++i) { const int L = (wid + 8 * i) * 64 + lane, row = L / CPR, slot = L % CPR, cc = (slot & ~7) | ((slot & 7) ^ ((row >> 1) & 7)); kgo[i] = row * LDK + cc * 8; }
; #pragma unroll
;     for (int i = 0; i < 2; ++i) { const int L = (2 * wid + i) * 64 + lane, st = L >> 5, w5 = L & 31, kk = (st >> 2) * 8 + (w5 >> 2), c = (st & 3) * 32 + (w5 & 3) * 8;
;         const int k = (kk & ~0xC) | ((kk & 4) << 1) | ((kk & 8) >> 1); vgo[i] = k * LDV + c; }
;     ...
;     ATT_DMA_K(0); ATT_DMA_K(1); ATT_DMA_V(0, 0); ATT_DMA_K(2); ATT_DMA_V(1, 1);
;     bf16x8 qr[ND0];
;     { const bf16_t* Qw = Qb + (size_t)(wid * 32 + r32) * LDQ + hi * 8;
; #pragma unroll
;       for (int d0 = 0; d0 < ND0; ++d0) qr[d0] = *(const bf16x8*)(Qw + d0 * 16);
;       if constexpr (MODE == 0) {
;           float ss = 0.f;
; #pragma unroll
;           for (int d0 = 0; d0 < ND0; ++d0)
; #pragma unroll
;               for (int j = 0; j < 8; ++j) { const float f = bf2f((unsigned short)qr[d0][j]); ss += f * f; }
;           ss = swap_sum(ss);
;           const float rstd = rsqrtf(ss * (1.f / DQK) + EPS) * C;
; #pragma unroll
;           for (int d0 = 0; d0 < ND0; ++d0) { const float* g = gq + d0 * 16 + hi * 8;
;               { float f[8]; _Pragma("unroll") for (int j = 0; j < 8; ++j) f[j] = bf2f((unsigned short)qr[d0][j]) * rstd * g[j];
;                 u32x4 w = {cvtpk(f[0], f[1]), cvtpk(f[2], f[3]), cvtpk(f[4], f[5]), cvtpk(f[6], f[7])}; qr[d0] = __builtin_bit_cast(bf16x8, w); asm volatile("" ::: "memory"); } }
;       } }
;     const int qlo = q0 + wid * 32, qpos = qlo + r32;
;     const int tL = MODE == 0 ? 0 : (qlo >= 191 ? (qlo - 127) >> 6 : 0), tR = MODE == 0 ? NT : min(NT, (qlo + 222) >> 6);
;     float fL = 1.f, fR = 1.f; if constexpr (MODE != 0) { fL = __builtin_amdgcn_exp2f(bt[0]); fR = __builtin_amdgcn_exp2f(-bt[448]); }
;     ...
;     const int vbase = (int)(unsigned)(size_t)lds + V_OFF + v_rd_base(lane);
;     ...
;     constexpr int NDA = ND0 > 6 ? 6 : ND0;
;     ...
;     f32x16 pA, pB; bf16x8 pa0, pa1;
;     int v0 = 0, v1 = 1, v2 = 2;
;     ATT_TOP(NKP + 2);
;     { bf16x8 kf[NDA]; k_reads<DQK, 0, NDA>(kf, lds, 0, r32, hi); ATT_LGKM0(); qk_mma<0, NDA>(pA, kf, qr);
	v_mbcnt_lo_u32_b32 v7, -1, 0
	v_mbcnt_hi_u32_b32 v7, -1, v7
	s_mov_b64 s[4:5], 0x880
	v_add_u32_e32 v0, s33, v7
	v_bfe_u32 v4, v0, 2, 2
	v_readfirstlane_b32 s0, v0
	s_ashr_i32 s2, s0, 31
	s_ashr_i32 s1, s0, 6
	v_mov_b32_e32 v1, s0
	v_bfi_b32 v1, s63, v1, v7
	s_lshr_b32 s2, s2, 29
	v_add_u32_e32 v3, s2, v1
	s_lshl_b32 s2, s1, 7
	v_ashrrev_i32_e32 v9, 3, v3
	v_and_b32_e32 v3, 0x1ffffff8, v3
	s_ashr_i32 s3, s2, 4
	v_lshrrev_b32_e32 v0, 1, v0
	v_sub_u32_e32 v1, v1, v3
	v_lshrrev_b32_e32 v3, 1, v9
	v_lshlrev_b32_e32 v18, 3, v7
	s_and_b32 s2, s3, -16
	v_and_b32_e32 v6, 8, v0
	s_lshr_b32 s3, s3, 1
	v_bitop3_b32 v1, v3, v1, 7 bitop3:0x6c
	v_and_b32_e32 v3, 32, v7
	v_and_b32_e32 v5, 24, v18
	s_and_b32 s3, s3, 4
	v_or3_b32 v0, v6, v4, s2
	v_or_b32_e32 v10, v3, v5
	v_or_b32_e32 v0, s3, v0
	v_lshl_or_b32 v96, v0, 11, v10
	v_lshlrev_b32_e32 v0, 11, v9
	v_lshl_add_u32 v0, v1, 3, v0
	v_ashrrev_i32_e32 v1, 31, v0
	v_lshlrev_b64 v[10:11], 1, v[0:1]
	v_lshl_add_u64 v[12:13], s[46:47], 0, v[10:11]
	v_lshl_add_u64 v[12:13], v[12:13], 0, s[4:5]
	s_lshl_b32 s4, s1, 10
	s_add_i32 s94, s4, 0
	s_mov_b32 m0, s94
	v_lshl_add_u64 v[10:11], s[48:49], 0, v[10:11]
	s_mov_b64 s[4:5], 0x40080
	global_load_lds_dwordx4 v[12:13], off
	v_lshl_add_u64 v[12:13], v[10:11], 0, s[4:5]
	s_add_i32 m0, s94, 0x2000
	s_lshl_b32 s4, s1, 11
	v_ashrrev_i32_e32 v97, 31, v96
	global_load_lds_dwordx4 v[12:13], off
	s_add_i32 s6, s4, 0
	v_lshlrev_b64 v[12:13], 1, v[96:97]
	s_add_i32 s48, s6, 0x18000
	v_lshl_add_u64 v[14:15], s[46:47], 0, v[12:13]
	v_lshl_add_u64 v[16:17], v[14:15], 0, s[96:97]
	s_mov_b32 m0, s48
	s_mov_b64 s[4:5], 0xc80
	global_load_lds_dwordx4 v[16:17], off
	v_lshl_add_u64 v[14:15], v[14:15], 0, s[4:5]
	s_add_i32 m0, s6, 0x18400
	s_mov_b64 s[4:5], 0x80080
	v_or_b32_e32 v98, 64, v96
	global_load_lds_dwordx4 v[14:15], off
	v_lshl_add_u64 v[10:11], v[10:11], 0, s[4:5]
	s_add_i32 m0, s94, 0x4000
	v_ashrrev_i32_e32 v99, 31, v98
	global_load_lds_dwordx4 v[10:11], off
	s_add_i32 m0, s6, 0x1c000
	v_lshl_add_u64 v[10:11], s[52:53], 0, v[12:13]
	v_and_b32_e32 v2, 31, v7
	global_load_lds_dwordx4 v[10:11], off
	v_lshl_add_u64 v[10:11], v[98:99], 1, s[52:53]
	s_add_i32 m0, s6, 0x1c400
	s_lshl_b32 s46, s1, 5
	global_load_lds_dwordx4 v[10:11], off
	v_or_b32_e32 v10, s46, v2
	v_ashrrev_i32_e32 v11, 31, v10
	v_bfe_u32 v8, v7, 5, 1
	v_lshlrev_b64 v[10:11], 12, v[10:11]
	v_lshl_add_u64 v[10:11], s[44:45], 0, v[10:11]
	v_lshlrev_b32_e32 v130, 4, v8
	v_lshl_add_u64 v[10:11], v[10:11], 0, v[130:131]
	global_load_dwordx4 v[92:95], v[10:11], off offset:1152
	global_load_dwordx4 v[88:91], v[10:11], off offset:1184
	global_load_dwordx4 v[84:87], v[10:11], off offset:1216
	global_load_dwordx4 v[80:83], v[10:11], off offset:1248
	v_and_b32_e32 v11, 0x70, v18
	v_mov_b32_e32 v9, s88
	v_mov_b32_e32 v10, s81
	v_lshl_add_u32 v114, v2, 7, 0
	v_bitop3_b32 v115, v130, v18, s64 bitop3:0x78
	v_bitop3_b32 v117, v130, v11, 64 bitop3:0x36
	s_add_i32 s4, s46, s89
	ds_read_b32 v9, v9
	ds_read_b32 v10, v10
	s_waitcnt vmcnt(3)
	s_barrier
	v_add_u32_e32 v107, v114, v115
	v_bitop3_b32 v116, v130, v11, 32 bitop3:0x36
	v_add_u32_e32 v109, v114, v117
	v_bitop3_b32 v118, v130, v11, s65 bitop3:0x36
	s_add_i32 s5, s4, 0xffffff81
	v_add_u32_e32 v108, v114, v116
	ds_read_b128 v[12:15], v107
	ds_read_b128 v[16:19], v108
	v_add_u32_e32 v110, v114, v118
	ds_read_b128 v[20:23], v109
	ds_read_b128 v[24:27], v110
	s_ashr_i32 s5, s5, 6
	s_cmpk_gt_i32 s4, 0xbe
	v_or_b32_e32 v111, s4, v2
	s_cselect_b32 s47, s5, 0
	s_addk_i32 s4, 0xde
	s_ashr_i32 s45, s4, 6
	s_waitcnt lgkmcnt(0)
	s_waitcnt vmcnt(0) lgkmcnt(0)
	v_mfma_f32_32x32x16_bf16 v[64:79], v[12:15], v[92:95], 0
	s_cmp_gt_i32 s47, 0
	s_cselect_b64 s[4:5], -1, 0
	s_cmp_lt_i32 s45, 1
	s_cselect_b64 s[6:7], -1, 0
	s_or_b64 s[4:5], s[6:7], s[4:5]
	s_and_b64 vcc, exec, s[4:5]
	v_mfma_f32_32x32x16_bf16 v[64:79], v[16:19], v[88:91], v[64:79]
	v_mfma_f32_32x32x16_bf16 v[64:79], v[20:23], v[84:87], v[64:79]
	v_mfma_f32_32x32x16_bf16 v[64:79], v[24:27], v[80:83], v[64:79]
	s_cbranch_vccnz .LBB0_1948
	v_lshlrev_b32_e32 v8, 2, v8
	v_sub_u32_e32 v8, v8, v111
	v_lshl_add_u32 v8, v8, 2, s88
	ds_read2_b32 v[12:13], v8 offset0:240 offset1:241
	ds_read2_b32 v[14:15], v8 offset0:242 offset1:243
	ds_read2_b32 v[16:17], v8 offset0:248 offset1:249
	ds_read2_b32 v[18:19], v8 offset0:250 offset1:251
	ds_read2_b32 v[20:21], v8 offset0:224 offset1:225
	ds_read2_b32 v[22:23], v8 offset0:226 offset1:227
	ds_read2_b32 v[24:25], v8 offset0:232 offset1:233
	ds_read2_b32 v[26:27], v8 offset0:234 offset1:235
	s_waitcnt lgkmcnt(4)
	v_pk_add_f32 v[78:79], v[78:79], v[18:19]
	v_pk_add_f32 v[76:77], v[76:77], v[16:17]
	v_pk_add_f32 v[74:75], v[74:75], v[14:15]
	v_pk_add_f32 v[72:73], v[72:73], v[12:13]
	s_waitcnt lgkmcnt(0)
	v_pk_add_f32 v[70:71], v[70:71], v[26:27]
	v_pk_add_f32 v[68:69], v[68:69], v[24:25]
	v_pk_add_f32 v[66:67], v[66:67], v[22:23]
	v_pk_add_f32 v[64:65], v[64:65], v[20:21]

; DI int v_rd_base(int lane) { return ((lane & 3) << 3) | (((lane >> 2) & 3) << 6) | (((lane >> 4) & 1) << 5) | (((lane >> 5) & 1) << 8); }
; DI void expsum(f32x16& p, float& l_reg, bf16x8& pa0, bf16x8& pa1) {
; #pragma unroll
;     for (int r = 0; r < 16; ++r) p[r] = __builtin_amdgcn_exp2f(p[r]);
;     float ps = 0.f;
; #pragma unroll
;     for (int r = 0; r < 16; ++r) ps += p[r];
;     l_reg += ps; asm volatile("" : "+v"(l_reg));
;     ...
;     ATT_PK4(p, 0, pa0); ATT_PK4(p, 8, pa1);
;     ...
; }
; template <int DQK, int MODE, int LDQ, int LDK, int LDV> ...
;     ...
;     const int vbase = (int)(unsigned)(size_t)lds + V_OFF + v_rd_base(lane);
;     ...
;     constexpr int NDA = ND0 > 6 ? 6 : ND0;
.LBB0_1953:
	s_add_i32 s3, s0, -1
	s_add_i32 s2, s22, 0xffffa000
	s_and_b32 s2, s2, 0x6000
	v_add_u32_e32 v121, s2, v114
	v_add_u32_e32 v122, v121, v115
	v_add_u32_e32 v126, v121, v116
	ds_read_b128 v[122:125], v122 offset:4096
	ds_read_b128 v[132:135], v126 offset:4096
	v_add_u32_e32 v126, v121, v117
	v_add_u32_e32 v121, v121, v118
	s_lshl_b32 s2, s23, 14
	ds_read_b128 v[136:139], v126 offset:4096
	ds_read_b128 v[140:143], v121 offset:4096
	v_add_u32_e32 v121, s2, v106
	ds_read_b64_tr_b16 v[144:145], v121 offset:0
	ds_read_b64_tr_b16 v[146:147], v121 offset:0x800
	ds_read_b64_tr_b16 v[148:149], v121 offset:0x1000
	ds_read_b64_tr_b16 v[150:151], v121 offset:0x1800
	ds_read_b64_tr_b16 v[152:153], v121 offset:0x200
	ds_read_b64_tr_b16 v[154:155], v121 offset:0xa00
	ds_read_b64_tr_b16 v[156:157], v121 offset:0x1200
	ds_read_b64_tr_b16 v[158:159], v121 offset:0x1a00
	ds_read_b64_tr_b16 v[162:163], v121 offset:0x400
	ds_read_b64_tr_b16 v[164:165], v121 offset:0xc00
	ds_read_b64_tr_b16 v[166:167], v121 offset:0x1400
	ds_read_b64_tr_b16 v[168:169], v121 offset:0x1c00
	ds_read_b64_tr_b16 v[170:171], v121 offset:0x600
	ds_read_b64_tr_b16 v[172:173], v121 offset:0xe00
	ds_read_b64_tr_b16 v[174:175], v121 offset:0x1600
	ds_read_b64_tr_b16 v[176:177], v121 offset:0x1e00
	s_setprio 2
	v_exp_f32_e32 v64, v64
	v_exp_f32_e32 v65, v65
	v_exp_f32_e32 v66, v66
	v_exp_f32_e32 v67, v67
	v_exp_f32_e32 v68, v68
	v_exp_f32_e32 v69, v69
	v_add_f32_e32 v126, v65, v64
	v_exp_f32_e32 v70, v70
	v_add_f32_e32 v126, v66, v126
	v_exp_f32_e32 v71, v71
	v_add_f32_e32 v126, v67, v126
	v_exp_f32_e32 v72, v72
	v_add_f32_e32 v126, v68, v126
	v_exp_f32_e32 v73, v73
	v_add_f32_e32 v126, v69, v126
	v_exp_f32_e32 v74, v74
	v_add_f32_e32 v126, v70, v126
	v_exp_f32_e32 v75, v75
	v_add_f32_e32 v126, v71, v126
	v_exp_f32_e32 v76, v76
	v_add_f32_e32 v126, v72, v126
	v_exp_f32_e32 v77, v77
	v_add_f32_e32 v126, v73, v126
	v_exp_f32_e32 v78, v78
	v_add_f32_e32 v126, v74, v126
	v_exp_f32_e32 v79, v79
	v_add_f32_e32 v126, v75, v126
	v_add_f32_e32 v126, v76, v126
	v_add_f32_e32 v126, v77, v126
	v_add_f32_e32 v126, v78, v126
	v_add_f32_e32 v126, v79, v126
	v_add_f32_e32 v120, v126, v120
	v_cvt_pk_bf16_f32 v64, v64, v65
	v_cvt_pk_bf16_f32 v65, v66, v67
	v_cvt_pk_bf16_f32 v66, v68, v69
	v_cvt_pk_bf16_f32 v67, v70, v71
	v_cvt_pk_bf16_f32 v68, v72, v73
	v_cvt_pk_bf16_f32 v69, v74, v75
	v_cvt_pk_bf16_f32 v70, v76, v77
	v_cvt_pk_bf16_f32 v71, v78, v79
	v_permlane32_swap_b32_e32 v64, v66
	v_permlane32_swap_b32_e32 v65, v67
	v_permlane32_swap_b32_e32 v68, v70
	v_permlane32_swap_b32_e32 v69, v71
	s_waitcnt lgkmcnt(0)
	s_setprio 1
	v_mfma_f32_32x32x16_bf16 v[0:15], v[64:67], v[144:147], v[0:15]
	s_cmp_lt_i32 s3, s47
	s_cselect_b64 s[74:75], -1, 0
	s_cmp_ge_i32 s3, s52
	s_cselect_b64 s[90:91], -1, 0
	s_or_b64 s[74:75], s[74:75], s[90:91]
	s_and_b64 vcc, exec, s[74:75]
	v_mfma_f32_32x32x16_bf16 v[48:63], v[64:67], v[152:155], v[48:63]
	v_mfma_f32_32x32x16_bf16 v[16:31], v[64:67], v[162:165], v[16:31]
	v_mfma_f32_32x32x16_bf16 v[32:47], v[64:67], v[170:173], v[32:47]
	v_mfma_f32_32x32x16_bf16 v[0:15], v[68:71], v[148:151], v[0:15]
	v_mfma_f32_32x32x16_bf16 v[48:63], v[68:71], v[156:159], v[48:63]
	v_mfma_f32_32x32x16_bf16 v[16:31], v[68:71], v[166:169], v[16:31]
	v_mfma_f32_32x32x16_bf16 v[32:47], v[68:71], v[174:177], v[32:47]
	v_mfma_f32_32x32x16_bf16 v[64:79], v[122:125], v[92:95], 0
	v_mfma_f32_32x32x16_bf16 v[64:79], v[132:135], v[88:91], v[64:79]
	v_mfma_f32_32x32x16_bf16 v[64:79], v[136:139], v[84:87], v[64:79]
	v_mfma_f32_32x32x16_bf16 v[64:79], v[140:143], v[80:83], v[64:79]
	s_setprio 0
	v_add_u32_e32 v122, s7, v119
	s_cbranch_vccnz .LBB0_1955
	v_add_u32_e32 v138, 0x28908, v122
	v_add_u32_e32 v140, 0x28920, v122
	v_add_u32_e32 v142, 0x28928, v122
	v_add_u32_e32 v124, 0x28940, v122
	v_add_u32_e32 v126, 0x28948, v122
	v_add_u32_e32 v132, 0x28960, v122
	v_add_u32_e32 v134, 0x28968, v122
	v_add_u32_e32 v123, 0x28900, v122
	ds_read2_b32 v[124:125], v124 offset1:1
	ds_read2_b32 v[126:127], v126 offset1:1
	ds_read2_b32 v[132:133], v132 offset1:1
	ds_read2_b32 v[134:135], v134 offset1:1
	ds_read2_b32 v[136:137], v123 offset1:1
	ds_read2_b32 v[138:139], v138 offset1:1
	ds_read2_b32 v[140:141], v140 offset1:1
	ds_read2_b32 v[142:143], v142 offset1:1
	s_waitcnt lgkmcnt(0)
	v_pk_add_f32 v[78:79], v[78:79], v[134:135]
	v_pk_add_f32 v[76:77], v[76:77], v[132:133]
	v_pk_add_f32 v[74:75], v[74:75], v[126:127]
	v_pk_add_f32 v[72:73], v[72:73], v[124:125]
	v_pk_add_f32 v[70:71], v[70:71], v[142:143]
	v_pk_add_f32 v[68:69], v[68:69], v[140:141]
	v_pk_add_f32 v[66:67], v[66:67], v[138:139]
	v_pk_add_f32 v[64:65], v[64:65], v[136:137]

; DI void expsum(f32x16& p, float& l_reg, bf16x8& pa0, bf16x8& pa1) {
; #pragma unroll
;     for (int r = 0; r < 16; ++r) p[r] = __builtin_amdgcn_exp2f(p[r]);
;     float ps = 0.f;
; #pragma unroll
;     for (int r = 0; r < 16; ++r) ps += p[r];
;     l_reg += ps; asm volatile("" : "+v"(l_reg));
;     ...
;     ATT_PK4(p, 0, pa0); ATT_PK4(p, 8, pa1);
;     ...
; }
.LBB0_1961:
	ds_read_b128 v[98:101], v107 offset:12288
	ds_read_b128 v[102:105], v108 offset:12288
	ds_read_b128 v[114:117], v109 offset:12288
	ds_read_b128 v[122:125], v110 offset:12288
	v_lshl_add_u32 v96, s49, 14, v106
	ds_read_b64_tr_b16 v[132:133], v96 offset:0
	ds_read_b64_tr_b16 v[134:135], v96 offset:0x800
	ds_read_b64_tr_b16 v[136:137], v96 offset:0x1000
	ds_read_b64_tr_b16 v[138:139], v96 offset:0x1800
	ds_read_b64_tr_b16 v[140:141], v96 offset:0x200
	ds_read_b64_tr_b16 v[142:143], v96 offset:0xa00
	ds_read_b64_tr_b16 v[144:145], v96 offset:0x1200
	ds_read_b64_tr_b16 v[146:147], v96 offset:0x1a00
	ds_read_b64_tr_b16 v[148:149], v96 offset:0x400
	ds_read_b64_tr_b16 v[150:151], v96 offset:0xc00
	ds_read_b64_tr_b16 v[152:153], v96 offset:0x1400
	ds_read_b64_tr_b16 v[154:155], v96 offset:0x1c00
	ds_read_b64_tr_b16 v[156:157], v96 offset:0x600
	ds_read_b64_tr_b16 v[158:159], v96 offset:0xe00
	ds_read_b64_tr_b16 v[162:163], v96 offset:0x1600
	ds_read_b64_tr_b16 v[164:165], v96 offset:0x1e00
	s_setprio 2
	v_exp_f32_e32 v64, v64
	v_exp_f32_e32 v65, v65
	v_exp_f32_e32 v66, v66
	v_exp_f32_e32 v67, v67
	v_exp_f32_e32 v68, v68
	v_exp_f32_e32 v69, v69
	v_add_f32_e32 v97, v65, v64
	v_exp_f32_e32 v70, v70
	v_add_f32_e32 v97, v66, v97
	v_exp_f32_e32 v71, v71
	v_add_f32_e32 v97, v67, v97
	v_exp_f32_e32 v72, v72
	v_add_f32_e32 v97, v68, v97
	v_exp_f32_e32 v73, v73
	v_add_f32_e32 v97, v69, v97
	v_exp_f32_e32 v74, v74
	v_add_f32_e32 v97, v70, v97
	v_exp_f32_e32 v75, v75
	v_add_f32_e32 v97, v71, v97
	v_exp_f32_e32 v76, v76
	v_add_f32_e32 v97, v72, v97
	v_exp_f32_e32 v77, v77
	v_add_f32_e32 v97, v73, v97
	v_exp_f32_e32 v78, v78
	v_add_f32_e32 v97, v74, v97
	v_exp_f32_e32 v79, v79
	v_add_f32_e32 v97, v75, v97
	v_add_f32_e32 v97, v76, v97
	v_add_f32_e32 v97, v77, v97
	v_add_f32_e32 v97, v78, v97
	v_add_f32_e32 v97, v79, v97
	v_add_f32_e32 v97, v97, v120
	v_cvt_pk_bf16_f32 v64, v64, v65
	v_cvt_pk_bf16_f32 v65, v66, v67
	v_cvt_pk_bf16_f32 v66, v68, v69
	v_cvt_pk_bf16_f32 v67, v70, v71
	v_cvt_pk_bf16_f32 v68, v72, v73
	v_cvt_pk_bf16_f32 v69, v74, v75
	v_cvt_pk_bf16_f32 v70, v76, v77
	v_cvt_pk_bf16_f32 v71, v78, v79
	v_permlane32_swap_b32_e32 v64, v66
	v_permlane32_swap_b32_e32 v65, v67
	v_permlane32_swap_b32_e32 v68, v70
	v_permlane32_swap_b32_e32 v69, v71
	s_waitcnt lgkmcnt(0)
	s_setprio 1
	v_mfma_f32_32x32x16_bf16 v[0:15], v[64:67], v[132:135], v[0:15]
	s_cmp_gt_i32 s47, 61
	s_cselect_b64 s[0:1], -1, 0
	s_cmp_lt_i32 s45, 62
	s_cselect_b64 s[2:3], -1, 0
	s_or_b64 s[0:1], s[0:1], s[2:3]
	s_and_b64 vcc, exec, s[0:1]
	v_mfma_f32_32x32x16_bf16 v[48:63], v[64:67], v[140:143], v[48:63]
	v_mfma_f32_32x32x16_bf16 v[16:31], v[64:67], v[148:151], v[16:31]
	v_mfma_f32_32x32x16_bf16 v[32:47], v[64:67], v[156:159], v[32:47]
	v_mfma_f32_32x32x16_bf16 v[0:15], v[68:71], v[136:139], v[0:15]
	v_mfma_f32_32x32x16_bf16 v[48:63], v[68:71], v[144:147], v[48:63]
	v_mfma_f32_32x32x16_bf16 v[16:31], v[68:71], v[152:155], v[16:31]
	v_mfma_f32_32x32x16_bf16 v[32:47], v[68:71], v[162:165], v[32:47]
	s_waitcnt lgkmcnt(0)
	v_mfma_f32_32x32x16_bf16 v[64:79], v[98:101], v[92:95], 0
	v_mfma_f32_32x32x16_bf16 v[64:79], v[102:105], v[88:91], v[64:79]
	v_mfma_f32_32x32x16_bf16 v[64:79], v[114:117], v[84:87], v[64:79]
	v_mfma_f32_32x32x16_bf16 v[64:79], v[122:125], v[80:83], v[64:79]
	s_setprio 0
	s_cbranch_vccnz .LBB0_1963
	v_sub_u32_e32 v98, 0xf40, v111
	v_lshlrev_b32_e32 v98, 2, v98
	v_add3_u32 v98, s88, v98, v130
	v_add_u32_e32 v114, 0x400, v98
	v_add_u32_e32 v116, 0x408, v98
	v_add_u32_e32 v118, 0x420, v98
	v_add_u32_e32 v120, 0x428, v98
	v_add_u32_e32 v99, 0x440, v98
	v_add_u32_e32 v100, 0x448, v98
	v_add_u32_e32 v102, 0x460, v98
	v_add_u32_e32 v104, 0x468, v98
	ds_read2_b32 v[98:99], v99 offset1:1
	ds_read2_b32 v[100:101], v100 offset1:1
	ds_read2_b32 v[102:103], v102 offset1:1
	ds_read2_b32 v[104:105], v104 offset1:1
	ds_read2_b32 v[114:115], v114 offset1:1
	ds_read2_b32 v[116:117], v116 offset1:1
	ds_read2_b32 v[118:119], v118 offset1:1
	ds_read2_b32 v[120:121], v120 offset1:1
	s_waitcnt lgkmcnt(0)
	v_pk_add_f32 v[78:79], v[78:79], v[104:105]
	v_pk_add_f32 v[76:77], v[76:77], v[102:103]
	v_pk_add_f32 v[74:75], v[74:75], v[100:101]
	v_pk_add_f32 v[72:73], v[72:73], v[98:99]
	v_pk_add_f32 v[70:71], v[70:71], v[120:121]
	v_pk_add_f32 v[68:69], v[68:69], v[118:119]
	v_pk_add_f32 v[66:67], v[66:67], v[116:117]
	v_pk_add_f32 v[64:65], v[64:65], v[114:115]
.LBB0_1963:
	ds_read_b128 v[98:101], v107 offset:16384
	ds_read_b128 v[102:105], v108 offset:16384
	ds_read_b128 v[114:117], v109 offset:16384
	ds_read_b128 v[118:121], v110 offset:16384
	ds_read_b64_tr_b16 v[122:123], v96 offset:0x2000
	ds_read_b64_tr_b16 v[124:125], v96 offset:0x2800
	ds_read_b64_tr_b16 v[132:133], v96 offset:0x3000
	ds_read_b64_tr_b16 v[134:135], v96 offset:0x3800
	ds_read_b64_tr_b16 v[136:137], v96 offset:0x2200
	ds_read_b64_tr_b16 v[138:139], v96 offset:0x2a00
	ds_read_b64_tr_b16 v[140:141], v96 offset:0x3200
	ds_read_b64_tr_b16 v[142:143], v96 offset:0x3a00
	ds_read_b64_tr_b16 v[144:145], v96 offset:0x2400
	ds_read_b64_tr_b16 v[146:147], v96 offset:0x2c00
	ds_read_b64_tr_b16 v[148:149], v96 offset:0x3400
	ds_read_b64_tr_b16 v[150:151], v96 offset:0x3c00
	ds_read_b64_tr_b16 v[152:153], v96 offset:0x2600
	ds_read_b64_tr_b16 v[154:155], v96 offset:0x2e00
	ds_read_b64_tr_b16 v[156:157], v96 offset:0x3600
	ds_read_b64_tr_b16 v[158:159], v96 offset:0x3e00
	s_nop 6
	s_setprio 2
	v_exp_f32_e32 v64, v64
	v_exp_f32_e32 v65, v65
	v_exp_f32_e32 v66, v66
	v_exp_f32_e32 v67, v67
	v_exp_f32_e32 v68, v68
	v_exp_f32_e32 v69, v69
	v_add_f32_e32 v96, v65, v64
	v_exp_f32_e32 v70, v70
	v_add_f32_e32 v96, v66, v96
	v_exp_f32_e32 v71, v71
	v_add_f32_e32 v96, v67, v96
	v_exp_f32_e32 v72, v72
	v_add_f32_e32 v96, v68, v96
	v_exp_f32_e32 v73, v73
	v_add_f32_e32 v96, v69, v96
	v_exp_f32_e32 v74, v74
	v_add_f32_e32 v96, v70, v96
	v_exp_f32_e32 v75, v75
	v_add_f32_e32 v96, v71, v96
	v_exp_f32_e32 v76, v76
	v_add_f32_e32 v96, v72, v96
	v_exp_f32_e32 v77, v77
	v_add_f32_e32 v96, v73, v96
	v_exp_f32_e32 v78, v78
	v_add_f32_e32 v96, v74, v96
	v_exp_f32_e32 v79, v79
	v_add_f32_e32 v96, v75, v96
	v_add_f32_e32 v96, v76, v96
	v_add_f32_e32 v96, v77, v96
	v_add_f32_e32 v96, v78, v96
	v_add_f32_e32 v96, v79, v96
	v_add_f32_e32 v96, v97, v96
	v_cvt_pk_bf16_f32 v64, v64, v65
	v_cvt_pk_bf16_f32 v65, v66, v67
	v_cvt_pk_bf16_f32 v66, v68, v69
	v_cvt_pk_bf16_f32 v67, v70, v71
	v_cvt_pk_bf16_f32 v68, v72, v73
	v_cvt_pk_bf16_f32 v69, v74, v75
	v_cvt_pk_bf16_f32 v70, v76, v77
	v_cvt_pk_bf16_f32 v71, v78, v79
	v_permlane32_swap_b32_e32 v64, v66
	v_permlane32_swap_b32_e32 v65, v67
	v_permlane32_swap_b32_e32 v68, v70
	v_permlane32_swap_b32_e32 v69, v71
	s_waitcnt lgkmcnt(0)
	s_setprio 1
	s_cmp_lt_u32 s33, 0x100
	s_cbranch_scc1 .Lstg_d1_m61_21
	s_waitcnt vmcnt(0)
	s_barrier

; DI void expsum(f32x16& p, float& l_reg, bf16x8& pa0, bf16x8& pa1) {
; #pragma unroll
;     for (int r = 0; r < 16; ++r) p[r] = __builtin_amdgcn_exp2f(p[r]);
;     float ps = 0.f;
; #pragma unroll
;     for (int r = 0; r < 16; ++r) ps += p[r];
;     l_reg += ps; asm volatile("" : "+v"(l_reg));
;     ...
;     ATT_PK4(p, 0, pa0); ATT_PK4(p, 8, pa1);
;     ...
; }
.LBB0_1967:
	ds_read_b128 v[100:103], v107 offset:20480
	ds_read_b128 v[114:117], v108 offset:20480
	ds_read_b128 v[118:121], v109 offset:20480
	ds_read_b128 v[122:125], v110 offset:20480
	v_add_u32_e32 v98, 0x8000, v106
	ds_read_b64_tr_b16 v[132:133], v98 offset:0
	ds_read_b64_tr_b16 v[134:135], v98 offset:0x800
	ds_read_b64_tr_b16 v[136:137], v98 offset:0x1000
	ds_read_b64_tr_b16 v[138:139], v98 offset:0x1800
	ds_read_b64_tr_b16 v[140:141], v98 offset:0x200
	ds_read_b64_tr_b16 v[142:143], v98 offset:0xa00
	ds_read_b64_tr_b16 v[144:145], v98 offset:0x1200
	ds_read_b64_tr_b16 v[146:147], v98 offset:0x1a00
	ds_read_b64_tr_b16 v[148:149], v98 offset:0x400
	ds_read_b64_tr_b16 v[150:151], v98 offset:0xc00
	ds_read_b64_tr_b16 v[152:153], v98 offset:0x1400
	ds_read_b64_tr_b16 v[154:155], v98 offset:0x1c00
	ds_read_b64_tr_b16 v[156:157], v98 offset:0x600
	ds_read_b64_tr_b16 v[158:159], v98 offset:0xe00
	ds_read_b64_tr_b16 v[162:163], v98 offset:0x1600
	ds_read_b64_tr_b16 v[164:165], v98 offset:0x1e00
	s_setprio 2
	v_exp_f32_e32 v64, v64
	v_exp_f32_e32 v65, v65
	v_exp_f32_e32 v66, v66
	v_exp_f32_e32 v67, v67
	v_exp_f32_e32 v68, v68
	v_exp_f32_e32 v69, v69
	v_add_f32_e32 v99, v65, v64
	v_exp_f32_e32 v70, v70
	v_add_f32_e32 v99, v66, v99
	v_exp_f32_e32 v71, v71
	v_add_f32_e32 v99, v67, v99
	v_exp_f32_e32 v72, v72
	v_add_f32_e32 v99, v68, v99
	v_exp_f32_e32 v73, v73
	v_add_f32_e32 v99, v69, v99
	v_exp_f32_e32 v74, v74
	v_add_f32_e32 v99, v70, v99
	v_exp_f32_e32 v75, v75
	v_add_f32_e32 v99, v71, v99
	v_exp_f32_e32 v76, v76
	v_add_f32_e32 v99, v72, v99
	v_exp_f32_e32 v77, v77
	v_add_f32_e32 v99, v73, v99
	v_exp_f32_e32 v78, v78
	v_add_f32_e32 v99, v74, v99
	v_exp_f32_e32 v79, v79
	v_add_f32_e32 v99, v75, v99
	v_add_f32_e32 v99, v76, v99
	v_add_f32_e32 v99, v77, v99
	v_add_f32_e32 v99, v78, v99
	v_add_f32_e32 v99, v79, v99
	v_add_f32_e32 v96, v99, v96
	v_cvt_pk_bf16_f32 v64, v64, v65
	v_cvt_pk_bf16_f32 v65, v66, v67
	v_cvt_pk_bf16_f32 v66, v68, v69
	v_cvt_pk_bf16_f32 v67, v70, v71
	v_cvt_pk_bf16_f32 v68, v72, v73
	v_cvt_pk_bf16_f32 v69, v74, v75
	v_cvt_pk_bf16_f32 v70, v76, v77
	v_cvt_pk_bf16_f32 v71, v78, v79
	v_permlane32_swap_b32_e32 v64, v66
	v_permlane32_swap_b32_e32 v65, v67
	v_permlane32_swap_b32_e32 v68, v70
	v_permlane32_swap_b32_e32 v69, v71
	s_waitcnt lgkmcnt(0)
	s_setprio 1
	v_mfma_f32_32x32x16_bf16 v[0:15], v[64:67], v[132:135], v[0:15]
	s_and_b64 vcc, exec, s[2:3]
	v_mfma_f32_32x32x16_bf16 v[48:63], v[64:67], v[140:143], v[48:63]
	v_mfma_f32_32x32x16_bf16 v[16:31], v[64:67], v[148:151], v[16:31]
	v_mfma_f32_32x32x16_bf16 v[32:47], v[64:67], v[156:159], v[32:47]
	v_mfma_f32_32x32x16_bf16 v[0:15], v[68:71], v[136:139], v[0:15]
	v_mfma_f32_32x32x16_bf16 v[48:63], v[68:71], v[144:147], v[48:63]
	v_mfma_f32_32x32x16_bf16 v[16:31], v[68:71], v[152:155], v[16:31]
	v_mfma_f32_32x32x16_bf16 v[32:47], v[68:71], v[162:165], v[32:47]
	s_waitcnt lgkmcnt(0)
	v_mfma_f32_32x32x16_bf16 v[64:79], v[100:103], v[92:95], 0
	v_mfma_f32_32x32x16_bf16 v[64:79], v[114:117], v[88:91], v[64:79]
	v_mfma_f32_32x32x16_bf16 v[64:79], v[118:121], v[84:87], v[64:79]
	v_mfma_f32_32x32x16_bf16 v[64:79], v[122:125], v[80:83], v[64:79]
	s_setprio 0
	s_cbranch_vccnz .LBB0_1969
	v_add3_u32 v97, s88, v97, v130
	v_add_u32_e32 v118, 0x408, v97
	v_add_u32_e32 v120, 0x420, v97
	v_add_u32_e32 v122, 0x428, v97
	v_add_u32_e32 v100, 0x440, v97
	v_add_u32_e32 v102, 0x448, v97
	v_add_u32_e32 v104, 0x460, v97
	v_add_u32_e32 v99, 0x400, v97
	v_add_u32_e32 v97, 0x468, v97
	ds_read2_b32 v[100:101], v100 offset1:1
	ds_read2_b32 v[102:103], v102 offset1:1
	ds_read2_b32 v[104:105], v104 offset1:1
	ds_read2_b32 v[114:115], v97 offset1:1
	ds_read2_b32 v[116:117], v99 offset1:1
	ds_read2_b32 v[118:119], v118 offset1:1
	ds_read2_b32 v[120:121], v120 offset1:1
	ds_read2_b32 v[122:123], v122 offset1:1
	s_waitcnt lgkmcnt(0)
	v_pk_add_f32 v[78:79], v[78:79], v[114:115]
	v_pk_add_f32 v[76:77], v[76:77], v[104:105]
	v_pk_add_f32 v[74:75], v[74:75], v[102:103]
	v_pk_add_f32 v[72:73], v[72:73], v[100:101]
	v_pk_add_f32 v[70:71], v[70:71], v[122:123]
	v_pk_add_f32 v[68:69], v[68:69], v[120:121]
	v_pk_add_f32 v[66:67], v[66:67], v[118:119]
	v_pk_add_f32 v[64:65], v[64:65], v[116:117]

; DI void expsum(f32x16& p, float& l_reg, bf16x8& pa0, bf16x8& pa1) {
; #pragma unroll
;     for (int r = 0; r < 16; ++r) p[r] = __builtin_amdgcn_exp2f(p[r]);
;     float ps = 0.f;
; #pragma unroll
;     for (int r = 0; r < 16; ++r) ps += p[r];
;     l_reg += ps; asm volatile("" : "+v"(l_reg));
;     ...
;     ATT_PK4(p, 0, pa0); ATT_PK4(p, 8, pa1);
;     ...
; }
.LBB0_1973:
	ds_read_b128 v[98:101], v107 offset:28672
	ds_read_b128 v[102:105], v108 offset:28672
	ds_read_b128 v[112:115], v109 offset:28672
	ds_read_b128 v[108:111], v110 offset:28672
	ds_read_b64_tr_b16 v[116:117], v106 offset:0
	ds_read_b64_tr_b16 v[118:119], v106 offset:0x800
	ds_read_b64_tr_b16 v[120:121], v106 offset:0x1000
	ds_read_b64_tr_b16 v[122:123], v106 offset:0x1800
	ds_read_b64_tr_b16 v[124:125], v106 offset:0x200
	ds_read_b64_tr_b16 v[126:127], v106 offset:0xa00
	ds_read_b64_tr_b16 v[132:133], v106 offset:0x1200
	ds_read_b64_tr_b16 v[134:135], v106 offset:0x1a00
	ds_read_b64_tr_b16 v[136:137], v106 offset:0x400
	ds_read_b64_tr_b16 v[138:139], v106 offset:0xc00
	ds_read_b64_tr_b16 v[140:141], v106 offset:0x1400
	ds_read_b64_tr_b16 v[142:143], v106 offset:0x1c00
	ds_read_b64_tr_b16 v[144:145], v106 offset:0x600
	ds_read_b64_tr_b16 v[146:147], v106 offset:0xe00
	ds_read_b64_tr_b16 v[148:149], v106 offset:0x1600
	ds_read_b64_tr_b16 v[150:151], v106 offset:0x1e00
	s_setprio 2
	v_exp_f32_e32 v64, v64
	v_exp_f32_e32 v65, v65
	v_exp_f32_e32 v66, v66
	v_exp_f32_e32 v67, v67
	v_exp_f32_e32 v68, v68
	v_exp_f32_e32 v69, v69
	v_add_f32_e32 v107, v65, v64
	v_exp_f32_e32 v70, v70
	v_add_f32_e32 v107, v66, v107
	v_exp_f32_e32 v71, v71
	v_add_f32_e32 v107, v67, v107
	v_exp_f32_e32 v72, v72
	v_add_f32_e32 v107, v68, v107
	v_exp_f32_e32 v73, v73
	v_add_f32_e32 v107, v69, v107
	v_exp_f32_e32 v74, v74
	v_add_f32_e32 v107, v70, v107
	v_exp_f32_e32 v75, v75
	v_add_f32_e32 v107, v71, v107
	v_exp_f32_e32 v76, v76
	v_add_f32_e32 v107, v72, v107
	v_exp_f32_e32 v77, v77
	v_add_f32_e32 v107, v73, v107
	v_exp_f32_e32 v78, v78
	v_add_f32_e32 v107, v74, v107
	v_exp_f32_e32 v79, v79
	v_add_f32_e32 v107, v75, v107
	v_add_f32_e32 v107, v76, v107
	v_add_f32_e32 v107, v77, v107
	v_add_f32_e32 v107, v78, v107
	v_add_f32_e32 v107, v79, v107
	v_add_f32_e32 v96, v107, v96
	v_cvt_pk_bf16_f32 v64, v64, v65
	v_cvt_pk_bf16_f32 v65, v66, v67
	v_cvt_pk_bf16_f32 v66, v68, v69
	v_cvt_pk_bf16_f32 v67, v70, v71
	v_cvt_pk_bf16_f32 v68, v72, v73
	v_cvt_pk_bf16_f32 v69, v74, v75
	v_cvt_pk_bf16_f32 v70, v76, v77
	v_cvt_pk_bf16_f32 v71, v78, v79
	v_permlane32_swap_b32_e32 v64, v66
	v_permlane32_swap_b32_e32 v65, v67
	v_permlane32_swap_b32_e32 v68, v70
	v_permlane32_swap_b32_e32 v69, v71
	s_waitcnt lgkmcnt(0)
	s_setprio 1
	v_mfma_f32_32x32x16_bf16 v[0:15], v[64:67], v[116:119], v[0:15]
	s_and_b64 vcc, exec, s[2:3]
	v_mfma_f32_32x32x16_bf16 v[48:63], v[64:67], v[124:127], v[48:63]
	v_mfma_f32_32x32x16_bf16 v[16:31], v[64:67], v[136:139], v[16:31]
	v_mfma_f32_32x32x16_bf16 v[32:47], v[64:67], v[144:147], v[32:47]
	v_mfma_f32_32x32x16_bf16 v[0:15], v[68:71], v[120:123], v[0:15]
	v_mfma_f32_32x32x16_bf16 v[48:63], v[68:71], v[132:135], v[48:63]
	v_mfma_f32_32x32x16_bf16 v[16:31], v[68:71], v[140:143], v[16:31]
	v_mfma_f32_32x32x16_bf16 v[32:47], v[68:71], v[148:151], v[32:47]
	s_waitcnt lgkmcnt(0)
	v_mfma_f32_32x32x16_bf16 v[64:79], v[98:101], v[92:95], 0
	v_mfma_f32_32x32x16_bf16 v[64:79], v[102:105], v[88:91], v[64:79]
	v_mfma_f32_32x32x16_bf16 v[64:79], v[112:115], v[84:87], v[64:79]
	v_mfma_f32_32x32x16_bf16 v[64:79], v[108:111], v[80:83], v[64:79]
	s_setprio 0
	s_cbranch_vccnz .LBB0_1975
	v_add3_u32 v80, s88, v97, v130
	v_add_u32_e32 v88, 0x400, v80
	v_add_u32_e32 v90, 0x408, v80
	v_add_u32_e32 v92, 0x420, v80
	v_add_u32_e32 v94, 0x428, v80
	v_add_u32_e32 v81, 0x440, v80
	v_add_u32_e32 v82, 0x448, v80
	v_add_u32_e32 v84, 0x460, v80
	v_add_u32_e32 v86, 0x468, v80
	ds_read2_b32 v[80:81], v81 offset1:1
	ds_read2_b32 v[82:83], v82 offset1:1
	ds_read2_b32 v[84:85], v84 offset1:1
	ds_read2_b32 v[86:87], v86 offset1:1
	ds_read2_b32 v[88:89], v88 offset1:1
	ds_read2_b32 v[90:91], v90 offset1:1
	ds_read2_b32 v[92:93], v92 offset1:1
	ds_read2_b32 v[94:95], v94 offset1:1
	s_waitcnt lgkmcnt(0)
	v_pk_add_f32 v[78:79], v[78:79], v[86:87]
	v_pk_add_f32 v[76:77], v[76:77], v[84:85]
	v_pk_add_f32 v[74:75], v[74:75], v[82:83]
	v_pk_add_f32 v[72:73], v[72:73], v[80:81]
	v_pk_add_f32 v[70:71], v[70:71], v[94:95]
	v_pk_add_f32 v[68:69], v[68:69], v[92:93]
	v_pk_add_f32 v[66:67], v[66:67], v[90:91]
	v_pk_add_f32 v[64:65], v[64:65], v[88:89]
.LBB0_1975:
	s_lshl_b32 s0, s44, 2
	s_add_i32 s0, s0, 0
	s_add_i32 s0, s0, 0x24000
	ds_read_b64_tr_b16 v[80:81], v106 offset:0x2000
	ds_read_b64_tr_b16 v[82:83], v106 offset:0x2800
	ds_read_b64_tr_b16 v[84:85], v106 offset:0x3000
	ds_read_b64_tr_b16 v[86:87], v106 offset:0x3800
	ds_read_b64_tr_b16 v[88:89], v106 offset:0x2200
	ds_read_b64_tr_b16 v[90:91], v106 offset:0x2a00
	ds_read_b64_tr_b16 v[92:93], v106 offset:0x3200
	ds_read_b64_tr_b16 v[94:95], v106 offset:0x3a00
	ds_read_b64_tr_b16 v[98:99], v106 offset:0x2400
	ds_read_b64_tr_b16 v[100:101], v106 offset:0x2c00
	ds_read_b64_tr_b16 v[102:103], v106 offset:0x3400
	ds_read_b64_tr_b16 v[104:105], v106 offset:0x3c00
	ds_read_b64_tr_b16 v[108:109], v106 offset:0x2600
	ds_read_b64_tr_b16 v[110:111], v106 offset:0x2e00
	ds_read_b64_tr_b16 v[112:113], v106 offset:0x3600
	ds_read_b64_tr_b16 v[114:115], v106 offset:0x3e00
	s_nop 7
	s_setprio 2
	v_exp_f32_e32 v97, v64
	v_exp_f32_e32 v65, v65
	v_exp_f32_e32 v106, v66
	v_exp_f32_e32 v67, v67
	v_exp_f32_e32 v68, v68
	v_exp_f32_e32 v69, v69
	v_add_f32_e32 v64, v65, v97
	v_exp_f32_e32 v70, v70
	v_add_f32_e32 v64, v106, v64
	v_exp_f32_e32 v71, v71
	v_add_f32_e32 v64, v67, v64
	v_exp_f32_e32 v72, v72
	v_add_f32_e32 v64, v68, v64
	v_exp_f32_e32 v73, v73
	v_add_f32_e32 v64, v69, v64
	v_exp_f32_e32 v74, v74
	v_add_f32_e32 v64, v70, v64
	v_exp_f32_e32 v75, v75
	v_add_f32_e32 v64, v71, v64
	v_exp_f32_e32 v76, v76
	v_add_f32_e32 v64, v72, v64
	v_exp_f32_e32 v77, v77
	v_add_f32_e32 v64, v73, v64
	v_exp_f32_e32 v78, v78
	v_add_f32_e32 v64, v74, v64
	v_exp_f32_e32 v79, v79
	v_add_f32_e32 v64, v75, v64
	v_add_f32_e32 v64, v76, v64
	v_add_f32_e32 v64, v77, v64
	v_add_f32_e32 v64, v78, v64
	v_add_f32_e32 v64, v79, v64
	v_add_f32_e32 v64, v96, v64
	v_cvt_pk_bf16_f32 v66, v97, v65
	v_cvt_pk_bf16_f32 v67, v106, v67
	v_cvt_pk_bf16_f32 v68, v68, v69
	v_cvt_pk_bf16_f32 v69, v70, v71
	v_cvt_pk_bf16_f32 v70, v72, v73
	v_cvt_pk_bf16_f32 v71, v74, v75
	v_cvt_pk_bf16_f32 v72, v76, v77
	v_cvt_pk_bf16_f32 v73, v78, v79
	v_permlane32_swap_b32_e32 v66, v68
	v_permlane32_swap_b32_e32 v67, v69
	v_permlane32_swap_b32_e32 v70, v72
	v_permlane32_swap_b32_e32 v71, v73
	s_waitcnt lgkmcnt(0)
; template <int TAG = 0> DI int fresh_tid(int wv) { int l; asm volatile("v_mbcnt_lo_u32_b32 %0, -1, 0\n\tv_mbcnt_hi_u32_b32 %0, -1, %0 ; site %1" : "=v"(l) : "n"(TAG)); return wv * 64 + l; }
; DI int crow(int r, int hi) { return (r & 3) + 8 * (r >> 2) + 4 * hi; }
; DI float swap_sum(float v) { auto rr = __builtin_amdgcn_permlane32_swap(__float_as_uint(v), __float_as_uint(v), false, false); return __uint_as_float(rr[0]) + __uint_as_float(rr[1]); }
; template <int DQK, int MODE, int LDQ, int LDK, int LDV> ...
;     ...
;     l_reg = swap_sum(l_reg);
;     { const int lane2 = fresh_tid<110 + MODE>(wv) & 63, r32 = lane2 & 31, hi = lane2 >> 5;
;     if (hi == 0) li_l[r32] = l_reg;
;     asm volatile("s_waitcnt lgkmcnt(0)" ::: "memory");
;     float s0v[MODE == 2 ? 16 : 1][4];
;     if constexpr (MODE == 2) {
; #pragma unroll
;         for (int r = 0; r < 16; ++r)
; #pragma unroll
;             for (int d0 = 0; d0 < 4; ++d0) s0v[r][d0] = S0[(size_t)(wid * 32 + crow(r, hi)) * 512 + d0 * 32 + r32];
	s_setprio 1
	v_mfma_f32_32x32x16_bf16 v[0:15], v[66:69], v[80:83], v[0:15]
	v_mfma_f32_32x32x16_bf16 v[48:63], v[66:69], v[88:91], v[48:63]
	v_mfma_f32_32x32x16_bf16 v[16:31], v[66:69], v[98:101], v[16:31]
	v_mfma_f32_32x32x16_bf16 v[32:47], v[66:69], v[108:111], v[32:47]
	v_mfma_f32_32x32x16_bf16 v[0:15], v[70:73], v[84:87], v[0:15]
	v_mfma_f32_32x32x16_bf16 v[48:63], v[70:73], v[92:95], v[48:63]
	v_mfma_f32_32x32x16_bf16 v[16:31], v[70:73], v[102:105], v[16:31]
	v_mfma_f32_32x32x16_bf16 v[32:47], v[70:73], v[112:115], v[32:47]
	s_setprio 0
	v_mov_b32_e32 v66, v64
	v_mbcnt_lo_u32_b32 v65, -1, 0
	v_mbcnt_hi_u32_b32 v65, -1, v65
	s_nop 1
	v_permlane32_swap_b32_e32 v64, v66
	v_and_b32_e32 v114, 63, v65
	v_and_b32_e32 v170, 31, v65
	v_cmp_gt_u32_e32 vcc, 32, v114
	s_and_saveexec_b64 s[2:3], vcc
	v_lshl_add_u32 v67, v170, 2, s0
	v_add_f32_e32 v64, v64, v66
	ds_write_b32 v67, v64
	s_or_b64 exec, exec, s[2:3]
	v_lshrrev_b32_e32 v64, 3, v65
	v_and_b32_e32 v69, 4, v64
	v_or_b32_e32 v102, s46, v69
	v_lshlrev_b32_e32 v130, 2, v170
	v_ashrrev_i32_e32 v103, 31, v102
	v_or_b32_e32 v66, 1, v102
	v_lshl_add_u64 v[92:93], s[54:55], 0, v[130:131]
	v_lshlrev_b64 v[156:157], 11, v[102:103]
	v_ashrrev_i32_e32 v67, 31, v66
	s_waitcnt lgkmcnt(0)
	v_lshl_add_u64 v[64:65], v[92:93], 0, v[156:157]
	v_lshlrev_b64 v[148:149], 11, v[66:67]
	v_lshl_add_u64 v[66:67], v[92:93], 0, v[148:149]
	global_load_dword v110, v[64:65], off
	global_load_dword v111, v[64:65], off offset:128
	global_load_dword v109, v[64:65], off offset:256
	global_load_dword v108, v[64:65], off offset:384
	global_load_dword v106, v[66:67], off
	global_load_dword v107, v[66:67], off offset:128
	global_load_dword v105, v[66:67], off offset:256
	global_load_dword v104, v[66:67], off offset:384
	v_or_b32_e32 v64, 2, v102
	v_or_b32_e32 v66, 3, v102
	v_ashrrev_i32_e32 v65, 31, v64
	v_ashrrev_i32_e32 v67, 31, v66
	v_lshlrev_b64 v[146:147], 11, v[64:65]
	v_lshlrev_b64 v[136:137], 11, v[66:67]
	v_lshl_add_u64 v[64:65], v[92:93], 0, v[146:147]
	v_lshl_add_u64 v[66:67], v[92:93], 0, v[136:137]
	global_load_dword v158, v[64:65], off
	global_load_dword v159, v[64:65], off offset:128
	global_load_dword v155, v[64:65], off offset:256
	global_load_dword v154, v[64:65], off offset:384
	global_load_dword v152, v[66:67], off
	global_load_dword v153, v[66:67], off offset:128
	global_load_dword v151, v[66:67], off offset:256
	global_load_dword v150, v[66:67], off offset:384
	v_or_b32_e32 v64, 8, v102
	v_or_b32_e32 v66, 9, v102
	v_ashrrev_i32_e32 v65, 31, v64
	v_ashrrev_i32_e32 v67, 31, v66
	v_lshlrev_b64 v[134:135], 11, v[64:65]
	v_lshlrev_b64 v[120:121], 11, v[66:67]
	v_lshl_add_u64 v[64:65], v[92:93], 0, v[134:135]
	v_lshl_add_u64 v[66:67], v[92:93], 0, v[120:121]
	global_load_dword v144, v[64:65], off
	global_load_dword v145, v[64:65], off offset:128
	global_load_dword v143, v[64:65], off offset:256
	global_load_dword v142, v[64:65], off offset:384
	global_load_dword v140, v[66:67], off
	global_load_dword v141, v[66:67], off offset:128
	global_load_dword v139, v[66:67], off offset:256
	global_load_dword v138, v[66:67], off offset:384
	v_or_b32_e32 v64, 10, v102
	v_or_b32_e32 v66, 11, v102
	v_ashrrev_i32_e32 v65, 31, v64
	v_ashrrev_i32_e32 v67, 31, v66
	v_lshlrev_b64 v[118:119], 11, v[64:65]
	v_lshlrev_b64 v[90:91], 11, v[66:67]
	v_lshl_add_u64 v[64:65], v[92:93], 0, v[118:119]
	v_lshl_add_u64 v[66:67], v[92:93], 0, v[90:91]
	global_load_dword v132, v[64:65], off
	global_load_dword v133, v[64:65], off offset:128
	global_load_dword v127, v[64:65], off offset:256
	global_load_dword v126, v[64:65], off offset:384
	global_load_dword v124, v[66:67], off
	global_load_dword v125, v[66:67], off offset:128
	global_load_dword v123, v[66:67], off offset:256
	global_load_dword v122, v[66:67], off offset:384
	v_or_b32_e32 v64, 16, v102
	v_or_b32_e32 v66, 17, v102
	v_ashrrev_i32_e32 v65, 31, v64
	v_ashrrev_i32_e32 v67, 31, v66
	v_lshlrev_b64 v[86:87], 11, v[64:65]
	v_lshlrev_b64 v[78:79], 11, v[66:67]
	v_lshl_add_u64 v[64:65], v[92:93], 0, v[86:87]
	v_lshl_add_u64 v[66:67], v[92:93], 0, v[78:79]
	global_load_dword v100, v[64:65], off
	global_load_dword v101, v[64:65], off offset:128
	global_load_dword v99, v[64:65], off offset:256
	global_load_dword v98, v[64:65], off offset:384
	global_load_dword v96, v[66:67], off
	global_load_dword v97, v[66:67], off offset:128
	global_load_dword v95, v[66:67], off offset:256
	global_load_dword v94, v[66:67], off offset:384
	v_or_b32_e32 v64, 18, v102
	v_or_b32_e32 v66, 19, v102
	v_ashrrev_i32_e32 v65, 31, v64
	v_ashrrev_i32_e32 v67, 31, v66
	v_lshlrev_b64 v[76:77], 11, v[64:65]
	v_lshlrev_b64 v[72:73], 11, v[66:67]
	v_lshl_add_u64 v[64:65], v[92:93], 0, v[76:77]
	v_lshl_add_u64 v[66:67], v[92:93], 0, v[72:73]
	v_lshl_add_u32 v169, v69, 2, s0
	global_load_dword v88, v[64:65], off
	global_load_dword v89, v[64:65], off offset:128
	global_load_dword v85, v[64:65], off offset:256
	global_load_dword v84, v[64:65], off offset:384
	global_load_dword v82, v[66:67], off
	global_load_dword v83, v[66:67], off offset:128
	global_load_dword v81, v[66:67], off offset:256
	global_load_dword v80, v[66:67], off offset:384
	ds_read_b128 v[64:67], v169
	v_or_b32_e32 v68, 24, v102
	v_ashrrev_i32_e32 v69, 31, v68
	v_lshlrev_b64 v[74:75], 11, v[68:69]
	ds_read_b128 v[68:71], v169 offset:32
	s_waitcnt lgkmcnt(0)
; DI unsigned short f2bf(float x) { unsigned u = __float_as_uint(x); u += 0x7fffu + ((u >> 16) & 1u); return (unsigned short)(u >> 16); }
; DI float shx(float v, int mask, int lane) { return __int_as_float(__builtin_amdgcn_ds_bpermute((lane ^ mask) << 2, __float_as_int(v))); }
; DI int crow(int r, int hi) { return (r & 3) + 8 * (r >> 2) + 4 * hi; }
; template <int DQK, int MODE, int LDQ, int LDK, int LDV> ...
;     ...
;     for (int r = 0; r < 16; ++r) { const int orow = wid * 32 + crow(r, hi); const float rl = __builtin_amdgcn_rcpf(li_l[crow(r, hi)]);
;         if constexpr (MODE == 0) {
; #pragma unroll
;             for (int d0 = 0; d0 < 4; ++d0) AOb[(size_t)orow * 1024 + d0 * 32 + r32] = f2bf(o[d0][r] * rl);
;         } else if constexpr (MODE == 1) {
; #pragma unroll
;             for (int d0 = 0; d0 < 4; ++d0) S0[(size_t)orow * 512 + d0 * 32 + r32] = o[d0][r] * rl;
;         } else {
;             float v[4]; float ss = 0.f;
; #pragma unroll
;             for (int d0 = 0; d0 < 4; ++d0) { v[d0] = s0v[r][d0] - lam * (o[d0][r] * rl); ss += v[d0] * v[d0]; }
; #pragma unroll
;             for (int mk = 1; mk <= 16; mk <<= 1) ss += shx(ss, mk, lane2);
;             const float rs = rsqrtf(ss * (1.f / 128.f) + EPS) * 0.8f;
; #pragma unroll
;             for (int d0 = 0; d0 < 4; ++d0) AOb[(size_t)orow * 1024 + d0 * 32 + r32] = f2bf(v[d0] * rs * gout[d0 * 32 + r32]);
;         } }
	v_rcp_f32_e32 v64, v64
	v_mov_b32_e32 v162, v0
	v_mov_b32_e32 v163, v48
	v_rcp_f32_e32 v0, v65
	v_pk_mul_f32 v[162:163], v[162:163], v[64:65] op_sel_hi:[1,0]
	v_mov_b32_e32 v48, v1
	v_lshlrev_b32_e32 v166, 2, v114
	v_pk_mul_f32 v[48:49], v[48:49], v[0:1] op_sel_hi:[1,0]
	v_xor_b32_e32 v164, 4, v166
	v_xor_b32_e32 v165, 8, v166
	v_xor_b32_e32 v168, 16, v166
	v_xor_b32_e32 v167, 32, v166
	v_or_b32_e32 v116, 25, v102
	v_ashrrev_i32_e32 v117, 31, v116
	v_xor_b32_e32 v166, 64, v166
	v_lshl_add_u64 v[112:113], v[92:93], 0, v[74:75]
	s_add_u32 s1, s60, s58
	s_mov_b32 s0, 0x358637bd
	s_addc_u32 s3, s61, s59
	s_lshl_b32 s2, s87, 1
	s_add_u32 s2, s1, s2
	s_addc_u32 s3, s3, 0
	s_waitcnt vmcnt(0)
	v_pk_fma_f32 v[172:173], v[128:129], v[162:163], v[110:111] neg_lo:[1,0,0] neg_hi:[1,0,0]
	v_mov_b32_e32 v162, v32
	v_mov_b32_e32 v163, v16
	v_pk_mul_f32 v[162:163], v[162:163], v[64:65] op_sel_hi:[1,0]
	v_mov_b32_e32 v16, v33
	v_pk_fma_f32 v[174:175], v[128:129], v[162:163], v[108:109] neg_lo:[1,0,0] neg_hi:[1,0,0]
	global_load_dword v163, v130, s[50:51]
	global_load_dword v162, v130, s[50:51] offset:128
	global_load_dword v161, v130, s[50:51] offset:256
	s_nop 0
	global_load_dword v130, v130, s[50:51] offset:384
	v_pk_fma_f32 v[176:177], v[128:129], v[48:49], v[106:107] neg_lo:[1,0,0] neg_hi:[1,0,0]
	v_pk_mul_f32 v[0:1], v[16:17], v[0:1] op_sel_hi:[1,0]
	v_pk_mul_f32 v[110:111], v[172:173], v[172:173]
	v_pk_mul_f32 v[48:49], v[176:177], v[176:177]
	v_pk_fma_f32 v[0:1], v[128:129], v[0:1], v[104:105] neg_lo:[1,0,0] neg_hi:[1,0,0]
	v_pk_mul_f32 v[108:109], v[174:175], v[174:175]
	v_pk_mul_f32 v[16:17], v[0:1], v[0:1]
	v_mov_b32_e32 v32, v48
	v_mov_b32_e32 v33, v110
	v_mov_b32_e32 v110, v49
	v_pk_add_f32 v[32:33], v[32:33], v[110:111]
	v_mov_b32_e32 v48, v17
	v_mov_b32_e32 v49, v109
	v_pk_add_f32 v[32:33], v[48:49], v[32:33]
	v_mov_b32_e32 v17, v108
	v_pk_add_f32 v[16:17], v[16:17], v[32:33]
	ds_bpermute_b32 v33, v164, v17
	ds_bpermute_b32 v32, v164, v16
	v_lshlrev_b64 v[64:65], 11, v[116:117]
	v_lshl_add_u64 v[48:49], v[92:93], 0, v[64:65]
	global_load_dword v116, v[112:113], off
	global_load_dword v117, v[112:113], off offset:128
	global_load_dword v115, v[112:113], off offset:256
	global_load_dword v114, v[112:113], off offset:384
	s_nop 0
	global_load_dword v112, v[48:49], off
	global_load_dword v113, v[48:49], off offset:128
	global_load_dword v111, v[48:49], off offset:256
	global_load_dword v110, v[48:49], off offset:384
	v_or_b32_e32 v48, 26, v102
	s_waitcnt lgkmcnt(0)
	v_pk_add_f32 v[16:17], v[16:17], v[32:33]
	ds_bpermute_b32 v33, v165, v17
	ds_bpermute_b32 v32, v165, v16
	v_or_b32_e32 v102, 27, v102
	v_ashrrev_i32_e32 v49, 31, v48
	v_ashrrev_i32_e32 v103, 31, v102
	v_lshlrev_b64 v[48:49], 11, v[48:49]
	s_waitcnt lgkmcnt(0)
	v_pk_add_f32 v[16:17], v[16:17], v[32:33]
	ds_bpermute_b32 v33, v168, v17
	ds_bpermute_b32 v32, v168, v16
	v_lshl_add_u64 v[104:105], v[92:93], 0, v[48:49]
	v_lshlrev_b32_e32 v170, 1, v170
	v_mov_b32_e32 v171, v131
	v_rcp_f32_e32 v66, v66
	s_waitcnt lgkmcnt(0)
	v_pk_add_f32 v[32:33], v[16:17], v[32:33]
	ds_bpermute_b32 v107, v167, v33
	ds_bpermute_b32 v106, v167, v32
	v_lshlrev_b64 v[16:17], 11, v[102:103]
	v_lshl_add_u64 v[92:93], v[92:93], 0, v[16:17]
	s_waitcnt lgkmcnt(0)
	v_pk_add_f32 v[32:33], v[32:33], v[106:107]
	ds_bpermute_b32 v179, v166, v33
	ds_bpermute_b32 v178, v166, v32
	global_load_dword v108, v[104:105], off
	global_load_dword v109, v[104:105], off offset:128
	global_load_dword v107, v[104:105], off offset:256
	global_load_dword v106, v[104:105], off offset:384
	s_nop 0
	global_load_dword v104, v[92:93], off
	global_load_dword v105, v[92:93], off offset:128
	global_load_dword v103, v[92:93], off offset:256
	global_load_dword v102, v[92:93], off offset:384
	v_mov_b64_e32 v[92:93], s[0:1]
	s_waitcnt lgkmcnt(0)
	v_pk_add_f32 v[32:33], v[32:33], v[178:179]
	s_nop 0
	v_pk_fma_f32 v[178:179], v[32:33], s[24:25], v[92:93] op_sel_hi:[1,0,0]
	s_nop 0
	v_mul_f32_e32 v32, 0x4b800000, v179
	v_cmp_gt_f32_e32 vcc, s67, v179
	s_nop 1
	v_cndmask_b32_e32 v32, v179, v32, vcc
	v_rsq_f32_e32 v179, v32
	v_lshl_add_u64 v[32:33], s[2:3], 0, v[170:171]
	v_lshl_add_u64 v[156:157], v[32:33], 0, v[156:157]
	v_lshl_add_u64 v[148:149], v[32:33], 0, v[148:149]
	v_mul_f32_e32 v170, 0x45800000, v179
	v_cndmask_b32_e32 v170, v179, v170, vcc
	v_mul_f32_e32 v170, 0x3f4ccccd, v170
	v_mul_f32_e32 v171, v172, v170
	v_cmp_gt_f32_e32 vcc, s67, v178
	s_mov_b64 s[2:3], 0
	s_waitcnt vmcnt(19)
	v_mul_f32_e32 v171, v163, v171
	v_bfe_u32 v172, v171, 16, 1
	v_add3_u32 v171, v171, v172, s68
	global_store_short_d16_hi v[156:157], v171, off offset:1024
	v_mul_f32_e32 v171, v173, v170
	s_waitcnt vmcnt(19)
	v_mul_f32_e32 v171, v162, v171
	v_bfe_u32 v172, v171, 16, 1
	v_add3_u32 v171, v171, v172, s68
	global_store_short_d16_hi v[156:157], v171, off offset:1088
	v_mul_f32_e32 v171, v175, v170
	s_waitcnt vmcnt(19)
	v_mul_f32_e32 v171, v161, v171
	v_bfe_u32 v172, v171, 16, 1
	v_add3_u32 v171, v171, v172, s68
	global_store_short_d16_hi v[156:157], v171, off offset:1152
	v_mul_f32_e32 v171, 0x4b800000, v178
	v_cndmask_b32_e32 v171, v178, v171, vcc
	v_mul_f32_e32 v170, v174, v170
	v_rsq_f32_e32 v171, v171
	s_waitcnt vmcnt(19)
; DI unsigned short f2bf(float x) { unsigned u = __float_as_uint(x); u += 0x7fffu + ((u >> 16) & 1u); return (unsigned short)(u >> 16); }
; DI float shx(float v, int mask, int lane) { return __int_as_float(__builtin_amdgcn_ds_bpermute((lane ^ mask) << 2, __float_as_int(v))); }
; DI int crow(int r, int hi) { return (r & 3) + 8 * (r >> 2) + 4 * hi; }
; template <int DQK, int MODE, int LDQ, int LDK, int LDV> ...
;     ...
;     for (int r = 0; r < 16; ++r) { const int orow = wid * 32 + crow(r, hi); const float rl = __builtin_amdgcn_rcpf(li_l[crow(r, hi)]);
;         if constexpr (MODE == 0) {
; #pragma unroll
;             for (int d0 = 0; d0 < 4; ++d0) AOb[(size_t)orow * 1024 + d0 * 32 + r32] = f2bf(o[d0][r] * rl);
;         } else if constexpr (MODE == 1) {
; #pragma unroll
;             for (int d0 = 0; d0 < 4; ++d0) S0[(size_t)orow * 512 + d0 * 32 + r32] = o[d0][r] * rl;
;         } else {
;             float v[4]; float ss = 0.f;
; #pragma unroll
;             for (int d0 = 0; d0 < 4; ++d0) { v[d0] = s0v[r][d0] - lam * (o[d0][r] * rl); ss += v[d0] * v[d0]; }
; #pragma unroll
;             for (int mk = 1; mk <= 16; mk <<= 1) ss += shx(ss, mk, lane2);
;             const float rs = rsqrtf(ss * (1.f / 128.f) + EPS) * 0.8f;
; #pragma unroll
;             for (int d0 = 0; d0 < 4; ++d0) AOb[(size_t)orow * 1024 + d0 * 32 + r32] = f2bf(v[d0] * rs * gout[d0 * 32 + r32]);
;         } }
	v_mul_f32_e32 v170, v130, v170
	v_bfe_u32 v172, v170, 16, 1
	v_add3_u32 v170, v170, v172, s68
	global_store_short_d16_hi v[156:157], v170, off offset:1216
	v_mul_f32_e32 v156, 0x45800000, v171
	v_cndmask_b32_e32 v172, v171, v156, vcc
	v_mov_b32_e32 v156, v2
	v_rcp_f32_e32 v2, v67
	v_mov_b32_e32 v157, v50
	v_mov_b32_e32 v50, v3
	v_pk_mul_f32 v[156:157], v[156:157], v[66:67] op_sel_hi:[1,0]
	v_mov_b32_e32 v170, v34
	v_mov_b32_e32 v171, v18
	v_pk_mul_f32 v[50:51], v[50:51], v[2:3] op_sel_hi:[1,0]
	v_mov_b32_e32 v18, v35
	v_pk_fma_f32 v[156:157], v[128:129], v[156:157], v[158:159] neg_lo:[1,0,0] neg_hi:[1,0,0]
	v_pk_mul_f32 v[170:171], v[170:171], v[66:67] op_sel_hi:[1,0]
	v_pk_fma_f32 v[50:51], v[128:129], v[50:51], v[152:153] neg_lo:[1,0,0] neg_hi:[1,0,0]
	v_pk_mul_f32 v[2:3], v[18:19], v[2:3] op_sel_hi:[1,0]
	v_pk_mul_f32 v[158:159], v[156:157], v[156:157]
	v_pk_fma_f32 v[66:67], v[128:129], v[170:171], v[154:155] neg_lo:[1,0,0] neg_hi:[1,0,0]
	v_pk_mul_f32 v[152:153], v[50:51], v[50:51]
	v_pk_fma_f32 v[2:3], v[128:129], v[2:3], v[150:151] neg_lo:[1,0,0] neg_hi:[1,0,0]
	v_pk_mul_f32 v[154:155], v[66:67], v[66:67]
	v_pk_mul_f32 v[18:19], v[2:3], v[2:3]
	v_mov_b32_e32 v34, v152
	v_mov_b32_e32 v35, v158
	v_mov_b32_e32 v158, v153
	v_pk_add_f32 v[34:35], v[34:35], v[158:159]
	v_mov_b32_e32 v150, v19
	v_mov_b32_e32 v151, v155
	v_pk_add_f32 v[34:35], v[150:151], v[34:35]
	v_mov_b32_e32 v19, v154
	v_pk_add_f32 v[18:19], v[18:19], v[34:35]
	ds_bpermute_b32 v35, v164, v19
	ds_bpermute_b32 v34, v164, v18
	v_mul_f32_e32 v150, 0x3f4ccccd, v172
	v_mul_f32_e32 v151, v176, v150
	v_mul_f32_e32 v151, v163, v151
	v_bfe_u32 v152, v151, 16, 1
	s_waitcnt lgkmcnt(0)
	v_pk_add_f32 v[18:19], v[18:19], v[34:35]
	ds_bpermute_b32 v35, v165, v19
	ds_bpermute_b32 v34, v165, v18
	v_add3_u32 v151, v151, v152, s68
	global_store_short_d16_hi v[148:149], v151, off offset:1024
	v_mul_f32_e32 v151, v177, v150
	v_mul_f32_e32 v151, v162, v151
	s_waitcnt lgkmcnt(0)
	v_pk_add_f32 v[18:19], v[18:19], v[34:35]
	ds_bpermute_b32 v35, v168, v19
	ds_bpermute_b32 v34, v168, v18
	v_bfe_u32 v152, v151, 16, 1
	v_mul_f32_e32 v1, v1, v150
	v_add3_u32 v151, v151, v152, s68
	v_mul_f32_e32 v1, v161, v1
	s_waitcnt lgkmcnt(0)
	v_pk_add_f32 v[18:19], v[18:19], v[34:35]
	ds_bpermute_b32 v35, v167, v19
	ds_bpermute_b32 v34, v167, v18
	global_store_short_d16_hi v[148:149], v151, off offset:1088
	v_bfe_u32 v151, v1, 16, 1
	v_add3_u32 v1, v1, v151, s68
	v_mul_f32_e32 v0, v0, v150
	s_waitcnt lgkmcnt(0)
	v_pk_add_f32 v[18:19], v[18:19], v[34:35]
	ds_bpermute_b32 v35, v166, v19
	ds_bpermute_b32 v34, v166, v18
	global_store_short_d16_hi v[148:149], v1, off offset:1152
	v_mul_f32_e32 v150, v130, v0
	v_bfe_u32 v151, v150, 16, 1
	s_waitcnt lgkmcnt(0)
	v_pk_add_f32 v[0:1], v[18:19], v[34:35]
	s_nop 0
	v_pk_fma_f32 v[0:1], v[0:1], s[24:25], v[92:93] op_sel_hi:[1,0,0]
	s_nop 0
	v_mul_f32_e32 v18, 0x4b800000, v1
	v_cmp_gt_f32_e32 vcc, s67, v1
	s_nop 1
	v_cndmask_b32_e32 v1, v1, v18, vcc
	v_rsq_f32_e32 v1, v1
	v_add3_u32 v18, v150, v151, s68
	global_store_short_d16_hi v[148:149], v18, off offset:1216
	v_lshl_add_u64 v[18:19], v[32:33], 0, v[146:147]
	v_mul_f32_e32 v34, 0x45800000, v1
	v_cndmask_b32_e32 v1, v1, v34, vcc
	v_mul_f32_e32 v1, 0x3f4ccccd, v1
	v_mul_f32_e32 v34, v156, v1
	v_mul_f32_e32 v34, v163, v34
	v_bfe_u32 v35, v34, 16, 1
	v_add3_u32 v34, v34, v35, s68
	global_store_short_d16_hi v[18:19], v34, off offset:1024
	v_mul_f32_e32 v34, v157, v1
	v_mul_f32_e32 v34, v162, v34
	v_bfe_u32 v35, v34, 16, 1
	v_add3_u32 v34, v34, v35, s68
	global_store_short_d16_hi v[18:19], v34, off offset:1088
	v_mul_f32_e32 v34, v67, v1
	v_mul_f32_e32 v34, v161, v34
	v_bfe_u32 v35, v34, 16, 1
	v_add3_u32 v34, v34, v35, s68
	global_store_short_d16_hi v[18:19], v34, off offset:1152
	v_mul_f32_e32 v1, v66, v1
	v_mul_f32_e32 v34, 0x4b800000, v0
	v_cmp_gt_f32_e32 vcc, s67, v0
	v_mul_f32_e32 v1, v130, v1
	v_mov_b32_e32 v66, v36
	v_cndmask_b32_e32 v0, v0, v34, vcc
	v_rsq_f32_e32 v34, v0
	v_bfe_u32 v0, v1, 16, 1
	v_add3_u32 v0, v1, v0, s68
	global_store_short_d16_hi v[18:19], v0, off offset:1216
	v_rcp_f32_e32 v0, v68
	v_mov_b32_e32 v18, v4
	v_rcp_f32_e32 v4, v69
	v_mul_f32_e32 v1, 0x45800000, v34
	v_mov_b32_e32 v19, v52
	v_mov_b32_e32 v52, v5
	v_pk_mul_f32 v[18:19], v[18:19], v[0:1] op_sel_hi:[1,0]
	v_mov_b32_e32 v67, v20
	v_pk_mul_f32 v[52:53], v[52:53], v[4:5] op_sel_hi:[1,0]
	v_mov_b32_e32 v20, v37
	v_cndmask_b32_e32 v146, v34, v1, vcc
	v_pk_fma_f32 v[18:19], v[128:129], v[18:19], v[144:145] neg_lo:[1,0,0] neg_hi:[1,0,0]
	v_pk_mul_f32 v[0:1], v[66:67], v[0:1] op_sel_hi:[1,0]
	v_pk_fma_f32 v[52:53], v[128:129], v[52:53], v[140:141] neg_lo:[1,0,0] neg_hi:[1,0,0]
	v_pk_mul_f32 v[4:5], v[20:21], v[4:5] op_sel_hi:[1,0]
	v_pk_mul_f32 v[34:35], v[18:19], v[18:19]
	v_pk_fma_f32 v[0:1], v[128:129], v[0:1], v[142:143] neg_lo:[1,0,0] neg_hi:[1,0,0]
	v_pk_mul_f32 v[68:69], v[52:53], v[52:53]
	v_pk_fma_f32 v[4:5], v[128:129], v[4:5], v[138:139] neg_lo:[1,0,0] neg_hi:[1,0,0]
	v_pk_mul_f32 v[66:67], v[0:1], v[0:1]
	v_pk_mul_f32 v[20:21], v[4:5], v[4:5]
	v_mov_b32_e32 v36, v68
	v_mov_b32_e32 v37, v34
	v_mov_b32_e32 v34, v69
	v_pk_add_f32 v[34:35], v[36:37], v[34:35]
	v_mov_b32_e32 v36, v21
	v_mov_b32_e32 v37, v67
	v_pk_add_f32 v[34:35], v[36:37], v[34:35]
	v_mov_b32_e32 v21, v66
	v_pk_add_f32 v[20:21], v[20:21], v[34:35]
	ds_bpermute_b32 v35, v164, v21
	ds_bpermute_b32 v34, v164, v20
	v_mul_f32_e32 v66, 0x3f4ccccd, v146
	v_mul_f32_e32 v50, v50, v66
	v_mul_f32_e32 v50, v163, v50
	v_bfe_u32 v67, v50, 16, 1
	s_waitcnt lgkmcnt(0)
; DI unsigned short f2bf(float x) { unsigned u = __float_as_uint(x); u += 0x7fffu + ((u >> 16) & 1u); return (unsigned short)(u >> 16); }
; DI float shx(float v, int mask, int lane) { return __int_as_float(__builtin_amdgcn_ds_bpermute((lane ^ mask) << 2, __float_as_int(v))); }
; DI int crow(int r, int hi) { return (r & 3) + 8 * (r >> 2) + 4 * hi; }
; template <int DQK, int MODE, int LDQ, int LDK, int LDV> ...
;     ...
;     for (int r = 0; r < 16; ++r) { const int orow = wid * 32 + crow(r, hi); const float rl = __builtin_amdgcn_rcpf(li_l[crow(r, hi)]);
;         if constexpr (MODE == 0) {
; #pragma unroll
;             for (int d0 = 0; d0 < 4; ++d0) AOb[(size_t)orow * 1024 + d0 * 32 + r32] = f2bf(o[d0][r] * rl);
;         } else if constexpr (MODE == 1) {
; #pragma unroll
;             for (int d0 = 0; d0 < 4; ++d0) S0[(size_t)orow * 512 + d0 * 32 + r32] = o[d0][r] * rl;
;         } else {
;             float v[4]; float ss = 0.f;
; #pragma unroll
;             for (int d0 = 0; d0 < 4; ++d0) { v[d0] = s0v[r][d0] - lam * (o[d0][r] * rl); ss += v[d0] * v[d0]; }
; #pragma unroll
;             for (int mk = 1; mk <= 16; mk <<= 1) ss += shx(ss, mk, lane2);
;             const float rs = rsqrtf(ss * (1.f / 128.f) + EPS) * 0.8f;
; #pragma unroll
;             for (int d0 = 0; d0 < 4; ++d0) AOb[(size_t)orow * 1024 + d0 * 32 + r32] = f2bf(v[d0] * rs * gout[d0 * 32 + r32]);
;         } }
	v_pk_add_f32 v[20:21], v[20:21], v[34:35]
	ds_bpermute_b32 v35, v165, v21
	ds_bpermute_b32 v34, v165, v20
	v_lshl_add_u64 v[36:37], v[32:33], 0, v[136:137]
	v_add3_u32 v50, v50, v67, s68
	global_store_short_d16_hi v[36:37], v50, off offset:1024
	v_mul_f32_e32 v50, v51, v66
	s_waitcnt lgkmcnt(0)
	v_pk_add_f32 v[20:21], v[20:21], v[34:35]
	ds_bpermute_b32 v35, v168, v21
	ds_bpermute_b32 v34, v168, v20
	v_mul_f32_e32 v50, v162, v50
	v_bfe_u32 v51, v50, 16, 1
	v_mul_f32_e32 v3, v3, v66
	v_add3_u32 v50, v50, v51, s68
	s_waitcnt lgkmcnt(0)
	v_pk_add_f32 v[20:21], v[20:21], v[34:35]
	ds_bpermute_b32 v35, v167, v21
	ds_bpermute_b32 v34, v167, v20
	v_mul_f32_e32 v3, v161, v3
	global_store_short_d16_hi v[36:37], v50, off offset:1088
	v_bfe_u32 v50, v3, 16, 1
	v_add3_u32 v3, v3, v50, s68
	s_waitcnt lgkmcnt(0)
	v_pk_add_f32 v[20:21], v[20:21], v[34:35]
	ds_bpermute_b32 v35, v166, v21
	ds_bpermute_b32 v34, v166, v20
	v_mul_f32_e32 v2, v2, v66
	global_store_short_d16_hi v[36:37], v3, off offset:1152
	v_mul_f32_e32 v50, v130, v2
	v_bfe_u32 v51, v50, 16, 1
	s_waitcnt lgkmcnt(0)
	v_pk_add_f32 v[2:3], v[20:21], v[34:35]
	s_nop 0
	v_pk_fma_f32 v[2:3], v[2:3], s[24:25], v[92:93] op_sel_hi:[1,0,0]
	s_nop 0
	v_mul_f32_e32 v20, 0x4b800000, v3
	v_cmp_gt_f32_e32 vcc, s67, v3
	s_nop 1
	v_cndmask_b32_e32 v3, v3, v20, vcc
	v_rsq_f32_e32 v3, v3
	v_add3_u32 v20, v50, v51, s68
	global_store_short_d16_hi v[36:37], v20, off offset:1216
	v_lshl_add_u64 v[20:21], v[32:33], 0, v[134:135]
	v_mul_f32_e32 v34, 0x45800000, v3
	v_cndmask_b32_e32 v3, v3, v34, vcc
	v_mul_f32_e32 v3, 0x3f4ccccd, v3
	v_mul_f32_e32 v18, v18, v3
	v_mul_f32_e32 v18, v163, v18
	v_bfe_u32 v34, v18, 16, 1
	v_add3_u32 v18, v18, v34, s68
	global_store_short_d16_hi v[20:21], v18, off offset:1024
	v_mul_f32_e32 v18, v19, v3
	v_mul_f32_e32 v18, v162, v18
	v_bfe_u32 v19, v18, 16, 1
	v_mul_f32_e32 v1, v1, v3
	v_add3_u32 v18, v18, v19, s68
	v_mul_f32_e32 v1, v161, v1
	global_store_short_d16_hi v[20:21], v18, off offset:1088
	v_bfe_u32 v18, v1, 16, 1
	v_add3_u32 v1, v1, v18, s68
	global_store_short_d16_hi v[20:21], v1, off offset:1152
	v_mul_f32_e32 v1, 0x4b800000, v2
	v_cmp_gt_f32_e32 vcc, s67, v2
	v_mul_f32_e32 v0, v0, v3
	v_mul_f32_e32 v0, v130, v0
	v_cndmask_b32_e32 v1, v2, v1, vcc
	v_rsq_f32_e32 v1, v1
	v_bfe_u32 v2, v0, 16, 1
	v_add3_u32 v0, v0, v2, s68
	global_store_short_d16_hi v[20:21], v0, off offset:1216
	v_mul_f32_e32 v2, 0x45800000, v1
	v_rcp_f32_e32 v0, v70
	v_cndmask_b32_e32 v66, v1, v2, vcc
	v_mov_b32_e32 v2, v6
	v_rcp_f32_e32 v6, v71
	v_mov_b32_e32 v3, v54
	v_mov_b32_e32 v18, v38
	v_mov_b32_e32 v19, v22
	v_mov_b32_e32 v54, v7
	v_pk_mul_f32 v[2:3], v[2:3], v[0:1] op_sel_hi:[1,0]
	v_pk_mul_f32 v[0:1], v[18:19], v[0:1] op_sel_hi:[1,0]
	v_pk_mul_f32 v[18:19], v[54:55], v[6:7] op_sel_hi:[1,0]
	v_mov_b32_e32 v22, v39
	v_pk_fma_f32 v[2:3], v[128:129], v[2:3], v[132:133] neg_lo:[1,0,0] neg_hi:[1,0,0]
	v_pk_fma_f32 v[20:21], v[128:129], v[18:19], v[124:125] neg_lo:[1,0,0] neg_hi:[1,0,0]
	v_pk_mul_f32 v[6:7], v[22:23], v[6:7] op_sel_hi:[1,0]
	v_pk_mul_f32 v[34:35], v[2:3], v[2:3]
	v_pk_fma_f32 v[0:1], v[128:129], v[0:1], v[126:127] neg_lo:[1,0,0] neg_hi:[1,0,0]
	v_pk_mul_f32 v[50:51], v[20:21], v[20:21]
	v_pk_fma_f32 v[18:19], v[128:129], v[6:7], v[122:123] neg_lo:[1,0,0] neg_hi:[1,0,0]
	v_pk_mul_f32 v[36:37], v[0:1], v[0:1]
	v_pk_mul_f32 v[6:7], v[18:19], v[18:19]
	v_mov_b32_e32 v22, v50
	v_mov_b32_e32 v23, v34
	v_mov_b32_e32 v34, v51
	v_pk_add_f32 v[22:23], v[22:23], v[34:35]
	v_mov_b32_e32 v34, v7
	v_mov_b32_e32 v35, v37
	v_pk_add_f32 v[22:23], v[34:35], v[22:23]
	v_mov_b32_e32 v7, v36
	v_pk_add_f32 v[6:7], v[6:7], v[22:23]
	ds_bpermute_b32 v23, v164, v7
	ds_bpermute_b32 v22, v164, v6
	v_mul_f32_e32 v36, 0x3f4ccccd, v66
	v_mul_f32_e32 v37, v52, v36
	v_mul_f32_e32 v37, v163, v37
	v_bfe_u32 v38, v37, 16, 1
	s_waitcnt lgkmcnt(0)
	v_pk_add_f32 v[6:7], v[6:7], v[22:23]
	ds_bpermute_b32 v23, v165, v7
	ds_bpermute_b32 v22, v165, v6
	v_lshl_add_u64 v[34:35], v[32:33], 0, v[120:121]
	v_add3_u32 v37, v37, v38, s68
	global_store_short_d16_hi v[34:35], v37, off offset:1024
	v_mul_f32_e32 v37, v53, v36
	s_waitcnt lgkmcnt(0)
	v_pk_add_f32 v[6:7], v[6:7], v[22:23]
	ds_bpermute_b32 v23, v168, v7
	ds_bpermute_b32 v22, v168, v6
	v_mul_f32_e32 v37, v162, v37
	v_bfe_u32 v38, v37, 16, 1
	v_mul_f32_e32 v5, v5, v36
	v_add3_u32 v37, v37, v38, s68
	s_waitcnt lgkmcnt(0)
	v_pk_add_f32 v[6:7], v[6:7], v[22:23]
	ds_bpermute_b32 v23, v167, v7
	ds_bpermute_b32 v22, v167, v6
	v_mul_f32_e32 v5, v161, v5
	global_store_short_d16_hi v[34:35], v37, off offset:1088
	v_bfe_u32 v37, v5, 16, 1
	v_add3_u32 v5, v5, v37, s68
	s_waitcnt lgkmcnt(0)
	v_pk_add_f32 v[6:7], v[6:7], v[22:23]
	ds_bpermute_b32 v23, v166, v7
	ds_bpermute_b32 v22, v166, v6
	v_mul_f32_e32 v4, v4, v36
	global_store_short_d16_hi v[34:35], v5, off offset:1152
	v_mul_f32_e32 v36, v130, v4
	v_bfe_u32 v37, v36, 16, 1
	s_waitcnt lgkmcnt(0)
	v_pk_add_f32 v[4:5], v[6:7], v[22:23]
	v_lshl_add_u64 v[22:23], v[32:33], 0, v[118:119]
	v_pk_fma_f32 v[4:5], v[4:5], s[24:25], v[92:93] op_sel_hi:[1,0,0]
	s_nop 0
	v_mul_f32_e32 v6, 0x4b800000, v5
	v_cmp_gt_f32_e32 vcc, s67, v5
	s_nop 1
	v_cndmask_b32_e32 v5, v5, v6, vcc
	v_rsq_f32_e32 v5, v5
	v_add3_u32 v6, v36, v37, s68
	global_store_short_d16_hi v[34:35], v6, off offset:1216
	v_mov_b32_e32 v36, v40
	v_mul_f32_e32 v6, 0x45800000, v5
	v_cndmask_b32_e32 v5, v5, v6, vcc
	v_mul_f32_e32 v5, 0x3f4ccccd, v5
	v_mul_f32_e32 v2, v2, v5
	v_mul_f32_e32 v2, v163, v2
	v_bfe_u32 v6, v2, 16, 1
	v_add3_u32 v2, v2, v6, s68
	global_store_short_d16_hi v[22:23], v2, off offset:1024
	v_mul_f32_e32 v2, v3, v5
	v_mul_f32_e32 v2, v162, v2
	v_bfe_u32 v3, v2, 16, 1
	v_mul_f32_e32 v1, v1, v5
	v_add3_u32 v2, v2, v3, s68
	v_mul_f32_e32 v1, v161, v1
	global_store_short_d16_hi v[22:23], v2, off offset:1088
	v_bfe_u32 v2, v1, 16, 1
	v_add3_u32 v1, v1, v2, s68
	v_mul_f32_e32 v2, 0x4b800000, v4
	v_cmp_gt_f32_e32 vcc, s67, v4
	v_mul_f32_e32 v0, v0, v5
	v_mul_f32_e32 v0, v130, v0
	v_cndmask_b32_e32 v2, v4, v2, vcc
	ds_read_b128 v[4:7], v169 offset:64
	global_store_short_d16_hi v[22:23], v1, off offset:1152
	v_bfe_u32 v1, v0, 16, 1
	v_rsq_f32_e32 v34, v2
	v_add3_u32 v0, v0, v1, s68
	global_store_short_d16_hi v[22:23], v0, off offset:1216
	ds_read_b128 v[0:3], v169 offset:96
	s_waitcnt lgkmcnt(1)
; DI unsigned short f2bf(float x) { unsigned u = __float_as_uint(x); u += 0x7fffu + ((u >> 16) & 1u); return (unsigned short)(u >> 16); }
; DI float shx(float v, int mask, int lane) { return __int_as_float(__builtin_amdgcn_ds_bpermute((lane ^ mask) << 2, __float_as_int(v))); }
; DI int crow(int r, int hi) { return (r & 3) + 8 * (r >> 2) + 4 * hi; }
; template <int DQK, int MODE, int LDQ, int LDK, int LDV> ...
;     ...
;     for (int r = 0; r < 16; ++r) { const int orow = wid * 32 + crow(r, hi); const float rl = __builtin_amdgcn_rcpf(li_l[crow(r, hi)]);
;         if constexpr (MODE == 0) {
; #pragma unroll
;             for (int d0 = 0; d0 < 4; ++d0) AOb[(size_t)orow * 1024 + d0 * 32 + r32] = f2bf(o[d0][r] * rl);
;         } else if constexpr (MODE == 1) {
; #pragma unroll
;             for (int d0 = 0; d0 < 4; ++d0) S0[(size_t)orow * 512 + d0 * 32 + r32] = o[d0][r] * rl;
;         } else {
;             float v[4]; float ss = 0.f;
; #pragma unroll
;             for (int d0 = 0; d0 < 4; ++d0) { v[d0] = s0v[r][d0] - lam * (o[d0][r] * rl); ss += v[d0] * v[d0]; }
; #pragma unroll
;             for (int mk = 1; mk <= 16; mk <<= 1) ss += shx(ss, mk, lane2);
;             const float rs = rsqrtf(ss * (1.f / 128.f) + EPS) * 0.8f;
; #pragma unroll
;             for (int d0 = 0; d0 < 4; ++d0) AOb[(size_t)orow * 1024 + d0 * 32 + r32] = f2bf(v[d0] * rs * gout[d0 * 32 + r32]);
;         } }
	v_rcp_f32_e32 v4, v4
	v_mul_f32_e32 v22, 0x45800000, v34
	v_cndmask_b32_e32 v52, v34, v22, vcc
	v_mov_b32_e32 v22, v8
	v_mov_b32_e32 v23, v56
	v_mov_b32_e32 v37, v24
	v_pk_mul_f32 v[22:23], v[22:23], v[4:5] op_sel_hi:[1,0]
	v_pk_mul_f32 v[36:37], v[36:37], v[4:5] op_sel_hi:[1,0]
	v_rcp_f32_e32 v4, v5
	v_mov_b32_e32 v56, v9
	v_mov_b32_e32 v24, v41
	v_pk_fma_f32 v[22:23], v[128:129], v[22:23], v[100:101] neg_lo:[1,0,0] neg_hi:[1,0,0]
	v_pk_mul_f32 v[8:9], v[56:57], v[4:5] op_sel_hi:[1,0]
	v_pk_mul_f32 v[4:5], v[24:25], v[4:5] op_sel_hi:[1,0]
	v_pk_fma_f32 v[8:9], v[128:129], v[8:9], v[96:97] neg_lo:[1,0,0] neg_hi:[1,0,0]
	v_pk_mul_f32 v[34:35], v[22:23], v[22:23]
	v_pk_fma_f32 v[36:37], v[128:129], v[36:37], v[98:99] neg_lo:[1,0,0] neg_hi:[1,0,0]
	v_pk_mul_f32 v[50:51], v[8:9], v[8:9]
	v_pk_fma_f32 v[4:5], v[128:129], v[4:5], v[94:95] neg_lo:[1,0,0] neg_hi:[1,0,0]
	v_pk_mul_f32 v[38:39], v[36:37], v[36:37]
	v_pk_mul_f32 v[24:25], v[4:5], v[4:5]
	v_mov_b32_e32 v40, v50
	v_mov_b32_e32 v41, v34
	v_mov_b32_e32 v34, v51
	v_pk_add_f32 v[34:35], v[40:41], v[34:35]
	v_mov_b32_e32 v40, v25
	v_mov_b32_e32 v41, v39
	v_pk_add_f32 v[34:35], v[40:41], v[34:35]
	v_mov_b32_e32 v25, v38
	v_pk_add_f32 v[24:25], v[24:25], v[34:35]
	ds_bpermute_b32 v35, v164, v25
	ds_bpermute_b32 v34, v164, v24
	v_mul_f32_e32 v40, 0x3f4ccccd, v52
	v_mul_f32_e32 v20, v20, v40
	v_mul_f32_e32 v20, v163, v20
	v_bfe_u32 v41, v20, 16, 1
	s_waitcnt lgkmcnt(0)
	v_pk_add_f32 v[24:25], v[24:25], v[34:35]
	ds_bpermute_b32 v35, v165, v25
	ds_bpermute_b32 v34, v165, v24
	v_lshl_add_u64 v[38:39], v[32:33], 0, v[90:91]
	v_add3_u32 v20, v20, v41, s68
	global_store_short_d16_hi v[38:39], v20, off offset:1024
	v_mul_f32_e32 v41, v21, v40
	s_waitcnt lgkmcnt(0)
	v_pk_add_f32 v[20:21], v[24:25], v[34:35]
	ds_bpermute_b32 v25, v168, v21
	ds_bpermute_b32 v24, v168, v20
	v_mul_f32_e32 v34, v162, v41
	v_bfe_u32 v35, v34, 16, 1
	v_mul_f32_e32 v19, v19, v40
	v_add3_u32 v34, v34, v35, s68
	s_waitcnt lgkmcnt(0)
	v_pk_add_f32 v[20:21], v[20:21], v[24:25]
	ds_bpermute_b32 v25, v167, v21
	ds_bpermute_b32 v24, v167, v20
	v_mul_f32_e32 v19, v161, v19
	global_store_short_d16_hi v[38:39], v34, off offset:1088
	v_bfe_u32 v34, v19, 16, 1
	v_add3_u32 v19, v19, v34, s68
	s_waitcnt lgkmcnt(0)
	v_pk_add_f32 v[20:21], v[20:21], v[24:25]
	ds_bpermute_b32 v25, v166, v21
	ds_bpermute_b32 v24, v166, v20
	v_mul_f32_e32 v18, v18, v40
	global_store_short_d16_hi v[38:39], v19, off offset:1152
	v_mul_f32_e32 v34, v130, v18
	v_bfe_u32 v35, v34, 16, 1
	s_waitcnt lgkmcnt(0)
	v_pk_add_f32 v[18:19], v[20:21], v[24:25]
	v_rcp_f32_e32 v6, v6
	v_pk_fma_f32 v[18:19], v[18:19], s[24:25], v[92:93] op_sel_hi:[1,0,0]
	v_rcp_f32_e32 v0, v0
	v_mul_f32_e32 v20, 0x4b800000, v19
	v_cmp_gt_f32_e32 vcc, s67, v19
	v_rcp_f32_e32 v2, v2
	s_nop 0
	v_cndmask_b32_e32 v19, v19, v20, vcc
	v_rsq_f32_e32 v19, v19
	v_add3_u32 v20, v34, v35, s68
	global_store_short_d16_hi v[38:39], v20, off offset:1216
	v_lshl_add_u64 v[20:21], v[32:33], 0, v[86:87]
	v_mul_f32_e32 v24, 0x45800000, v19
	v_cndmask_b32_e32 v19, v19, v24, vcc
	v_mul_f32_e32 v19, 0x3f4ccccd, v19
	v_mul_f32_e32 v22, v22, v19
	v_mul_f32_e32 v22, v163, v22
	v_bfe_u32 v24, v22, 16, 1
	v_add3_u32 v22, v22, v24, s68
	global_store_short_d16_hi v[20:21], v22, off offset:1024
	v_mul_f32_e32 v22, v23, v19
	v_mul_f32_e32 v22, v162, v22
	v_bfe_u32 v23, v22, 16, 1
	v_add3_u32 v22, v22, v23, s68
	global_store_short_d16_hi v[20:21], v22, off offset:1088
	v_mul_f32_e32 v22, v37, v19
	v_mul_f32_e32 v22, v161, v22
	v_bfe_u32 v23, v22, 16, 1
	v_add3_u32 v22, v22, v23, s68
	global_store_short_d16_hi v[20:21], v22, off offset:1152
	v_mul_f32_e32 v22, 0x4b800000, v18
	v_cmp_gt_f32_e32 vcc, s67, v18
	v_mul_f32_e32 v19, v36, v19
	v_mul_f32_e32 v19, v130, v19
	v_cndmask_b32_e32 v18, v18, v22, vcc
	v_rsq_f32_e32 v18, v18
	v_bfe_u32 v22, v19, 16, 1
	v_add3_u32 v19, v19, v22, s68
	global_store_short_d16_hi v[20:21], v19, off offset:1216
	v_mul_f32_e32 v19, 0x45800000, v18
	v_cndmask_b32_e32 v38, v18, v19, vcc
	v_mov_b32_e32 v18, v10
	v_mov_b32_e32 v19, v58
	v_mov_b32_e32 v22, v42
	v_mov_b32_e32 v23, v26
	v_pk_mul_f32 v[18:19], v[18:19], v[6:7] op_sel_hi:[1,0]
	v_pk_mul_f32 v[22:23], v[22:23], v[6:7] op_sel_hi:[1,0]
	v_rcp_f32_e32 v6, v7
	v_mov_b32_e32 v58, v11
	v_mov_b32_e32 v26, v43
	v_pk_fma_f32 v[18:19], v[128:129], v[18:19], v[88:89] neg_lo:[1,0,0] neg_hi:[1,0,0]
	v_pk_mul_f32 v[10:11], v[58:59], v[6:7] op_sel_hi:[1,0]
	v_pk_mul_f32 v[6:7], v[26:27], v[6:7] op_sel_hi:[1,0]
	v_pk_fma_f32 v[10:11], v[128:129], v[10:11], v[82:83] neg_lo:[1,0,0] neg_hi:[1,0,0]
	v_pk_mul_f32 v[20:21], v[18:19], v[18:19]
	v_pk_fma_f32 v[22:23], v[128:129], v[22:23], v[84:85] neg_lo:[1,0,0] neg_hi:[1,0,0]
	v_pk_mul_f32 v[34:35], v[10:11], v[10:11]
	v_pk_fma_f32 v[6:7], v[128:129], v[6:7], v[80:81] neg_lo:[1,0,0] neg_hi:[1,0,0]
	v_pk_mul_f32 v[24:25], v[22:23], v[22:23]
	v_pk_mul_f32 v[26:27], v[6:7], v[6:7]
	v_mov_b32_e32 v36, v34
	v_mov_b32_e32 v37, v20
	v_mov_b32_e32 v20, v35
	v_pk_add_f32 v[20:21], v[36:37], v[20:21]
	v_mov_b32_e32 v34, v27
	v_mov_b32_e32 v35, v25
	v_pk_add_f32 v[20:21], v[34:35], v[20:21]
	v_mov_b32_e32 v27, v24
	v_pk_add_f32 v[20:21], v[26:27], v[20:21]
	ds_bpermute_b32 v25, v164, v21
	ds_bpermute_b32 v24, v164, v20
	v_mul_f32_e32 v34, 0x3f4ccccd, v38
	v_mul_f32_e32 v8, v8, v34
	v_mul_f32_e32 v8, v163, v8
	v_bfe_u32 v35, v8, 16, 1
	s_waitcnt lgkmcnt(0)
	v_pk_add_f32 v[20:21], v[20:21], v[24:25]
	ds_bpermute_b32 v25, v165, v21
	ds_bpermute_b32 v24, v165, v20
	v_lshl_add_u64 v[26:27], v[32:33], 0, v[78:79]
	v_add3_u32 v8, v8, v35, s68
	global_store_short_d16_hi v[26:27], v8, off offset:1024
	v_mul_f32_e32 v35, v9, v34
	s_waitcnt lgkmcnt(0)
; DI unsigned short f2bf(float x) { unsigned u = __float_as_uint(x); u += 0x7fffu + ((u >> 16) & 1u); return (unsigned short)(u >> 16); }
; DI float shx(float v, int mask, int lane) { return __int_as_float(__builtin_amdgcn_ds_bpermute((lane ^ mask) << 2, __float_as_int(v))); }
; DI int crow(int r, int hi) { return (r & 3) + 8 * (r >> 2) + 4 * hi; }
; template <int DQK, int MODE, int LDQ, int LDK, int LDV> ...
;     ...
;     for (int r = 0; r < 16; ++r) { const int orow = wid * 32 + crow(r, hi); const float rl = __builtin_amdgcn_rcpf(li_l[crow(r, hi)]);
;         if constexpr (MODE == 0) {
; #pragma unroll
;             for (int d0 = 0; d0 < 4; ++d0) AOb[(size_t)orow * 1024 + d0 * 32 + r32] = f2bf(o[d0][r] * rl);
;         } else if constexpr (MODE == 1) {
; #pragma unroll
;             for (int d0 = 0; d0 < 4; ++d0) S0[(size_t)orow * 512 + d0 * 32 + r32] = o[d0][r] * rl;
;         } else {
;             float v[4]; float ss = 0.f;
; #pragma unroll
;             for (int d0 = 0; d0 < 4; ++d0) { v[d0] = s0v[r][d0] - lam * (o[d0][r] * rl); ss += v[d0] * v[d0]; }
; #pragma unroll
;             for (int mk = 1; mk <= 16; mk <<= 1) ss += shx(ss, mk, lane2);
;             const float rs = rsqrtf(ss * (1.f / 128.f) + EPS) * 0.8f;
; #pragma unroll
;             for (int d0 = 0; d0 < 4; ++d0) AOb[(size_t)orow * 1024 + d0 * 32 + r32] = f2bf(v[d0] * rs * gout[d0 * 32 + r32]);
;         } }
	v_pk_add_f32 v[8:9], v[20:21], v[24:25]
	ds_bpermute_b32 v21, v168, v9
	ds_bpermute_b32 v20, v168, v8
	v_mul_f32_e32 v24, v162, v35
	v_bfe_u32 v25, v24, 16, 1
	v_mul_f32_e32 v5, v5, v34
	v_add3_u32 v24, v24, v25, s68
	s_waitcnt lgkmcnt(0)
	v_pk_add_f32 v[8:9], v[8:9], v[20:21]
	ds_bpermute_b32 v21, v167, v9
	ds_bpermute_b32 v20, v167, v8
	v_mul_f32_e32 v5, v161, v5
	global_store_short_d16_hi v[26:27], v24, off offset:1088
	v_bfe_u32 v24, v5, 16, 1
	v_add3_u32 v5, v5, v24, s68
	s_waitcnt lgkmcnt(0)
	v_pk_add_f32 v[8:9], v[8:9], v[20:21]
	ds_bpermute_b32 v21, v166, v9
	ds_bpermute_b32 v20, v166, v8
	v_mul_f32_e32 v4, v4, v34
	global_store_short_d16_hi v[26:27], v5, off offset:1152
	v_mul_f32_e32 v24, v130, v4
	v_bfe_u32 v25, v24, 16, 1
	s_waitcnt lgkmcnt(0)
	v_pk_add_f32 v[4:5], v[8:9], v[20:21]
	s_nop 0
	v_pk_fma_f32 v[4:5], v[4:5], s[24:25], v[92:93] op_sel_hi:[1,0,0]
	s_nop 0
	v_mul_f32_e32 v8, 0x4b800000, v5
	v_cmp_gt_f32_e32 vcc, s67, v5
	s_nop 1
	v_cndmask_b32_e32 v5, v5, v8, vcc
	v_rsq_f32_e32 v5, v5
	v_add3_u32 v8, v24, v25, s68
	global_store_short_d16_hi v[26:27], v8, off offset:1216
	v_lshl_add_u64 v[8:9], v[32:33], 0, v[76:77]
	v_mul_f32_e32 v20, 0x45800000, v5
	v_cndmask_b32_e32 v5, v5, v20, vcc
	v_mul_f32_e32 v5, 0x3f4ccccd, v5
	v_mul_f32_e32 v18, v18, v5
	v_mul_f32_e32 v18, v163, v18
	v_bfe_u32 v20, v18, 16, 1
	v_add3_u32 v18, v18, v20, s68
	global_store_short_d16_hi v[8:9], v18, off offset:1024
	v_mul_f32_e32 v18, v19, v5
	v_mul_f32_e32 v18, v162, v18
	v_bfe_u32 v19, v18, 16, 1
	v_add3_u32 v18, v18, v19, s68
	global_store_short_d16_hi v[8:9], v18, off offset:1088
	v_mul_f32_e32 v18, v23, v5
	v_mul_f32_e32 v18, v161, v18
	v_bfe_u32 v19, v18, 16, 1
	v_add3_u32 v18, v18, v19, s68
	global_store_short_d16_hi v[8:9], v18, off offset:1152
	v_mul_f32_e32 v18, 0x4b800000, v4
	v_cmp_gt_f32_e32 vcc, s67, v4
	v_mul_f32_e32 v5, v22, v5
	v_mul_f32_e32 v5, v130, v5
	v_cndmask_b32_e32 v4, v4, v18, vcc
	v_rsq_f32_e32 v4, v4
	v_bfe_u32 v18, v5, 16, 1
	v_add3_u32 v5, v5, v18, s68
	global_store_short_d16_hi v[8:9], v5, off offset:1216
	v_mul_f32_e32 v5, 0x45800000, v4
	v_cndmask_b32_e32 v34, v4, v5, vcc
	v_mov_b32_e32 v4, v12
	v_mov_b32_e32 v5, v60
	v_mov_b32_e32 v18, v44
	v_mov_b32_e32 v19, v28
	v_pk_mul_f32 v[4:5], v[4:5], v[0:1] op_sel_hi:[1,0]
	v_pk_mul_f32 v[18:19], v[18:19], v[0:1] op_sel_hi:[1,0]
	v_rcp_f32_e32 v0, v1
	v_mov_b32_e32 v60, v13
	v_mov_b32_e32 v28, v45
	s_waitcnt vmcnt(58)
	v_pk_fma_f32 v[4:5], v[128:129], v[4:5], v[116:117] neg_lo:[1,0,0] neg_hi:[1,0,0]
	v_pk_mul_f32 v[12:13], v[60:61], v[0:1] op_sel_hi:[1,0]
	v_pk_mul_f32 v[0:1], v[28:29], v[0:1] op_sel_hi:[1,0]
	s_waitcnt vmcnt(54)
	v_pk_fma_f32 v[12:13], v[128:129], v[12:13], v[112:113] neg_lo:[1,0,0] neg_hi:[1,0,0]
	v_pk_mul_f32 v[8:9], v[4:5], v[4:5]
	v_pk_fma_f32 v[18:19], v[128:129], v[18:19], v[114:115] neg_lo:[1,0,0] neg_hi:[1,0,0]
	v_pk_mul_f32 v[22:23], v[12:13], v[12:13]
	s_waitcnt vmcnt(52)
	v_pk_fma_f32 v[0:1], v[128:129], v[0:1], v[110:111] neg_lo:[1,0,0] neg_hi:[1,0,0]
	v_pk_mul_f32 v[20:21], v[18:19], v[18:19]
	v_pk_mul_f32 v[24:25], v[0:1], v[0:1]
	v_mov_b32_e32 v26, v22
	v_mov_b32_e32 v27, v8
	v_mov_b32_e32 v8, v23
	v_pk_add_f32 v[8:9], v[26:27], v[8:9]
	v_mov_b32_e32 v22, v25
	v_mov_b32_e32 v23, v21
	v_pk_add_f32 v[8:9], v[22:23], v[8:9]
	v_mov_b32_e32 v25, v20
	v_pk_add_f32 v[8:9], v[24:25], v[8:9]
	ds_bpermute_b32 v21, v164, v9
	ds_bpermute_b32 v20, v164, v8
	v_mul_f32_e32 v24, 0x3f4ccccd, v34
	v_mul_f32_e32 v10, v10, v24
	v_mul_f32_e32 v10, v163, v10
	v_bfe_u32 v25, v10, 16, 1
	s_waitcnt lgkmcnt(0)
	v_pk_add_f32 v[8:9], v[8:9], v[20:21]
	ds_bpermute_b32 v21, v165, v9
	ds_bpermute_b32 v20, v165, v8
	v_lshl_add_u64 v[22:23], v[32:33], 0, v[72:73]
	v_add3_u32 v10, v10, v25, s68
	global_store_short_d16_hi v[22:23], v10, off offset:1024
	v_mul_f32_e32 v25, v11, v24
	s_waitcnt lgkmcnt(0)
	v_pk_add_f32 v[8:9], v[8:9], v[20:21]
	ds_bpermute_b32 v11, v168, v9
	ds_bpermute_b32 v10, v168, v8
	v_mul_f32_e32 v20, v162, v25
	v_bfe_u32 v21, v20, 16, 1
	v_mul_f32_e32 v7, v7, v24
	v_add3_u32 v20, v20, v21, s68
	s_waitcnt lgkmcnt(0)
	v_pk_add_f32 v[8:9], v[8:9], v[10:11]
	ds_bpermute_b32 v11, v167, v9
	ds_bpermute_b32 v10, v167, v8
	v_mul_f32_e32 v7, v161, v7
	global_store_short_d16_hi v[22:23], v20, off offset:1088
	v_bfe_u32 v20, v7, 16, 1
	v_add3_u32 v7, v7, v20, s68
	s_waitcnt lgkmcnt(0)
	v_pk_add_f32 v[8:9], v[8:9], v[10:11]
	ds_bpermute_b32 v11, v166, v9
	ds_bpermute_b32 v10, v166, v8
	v_mul_f32_e32 v6, v6, v24
	global_store_short_d16_hi v[22:23], v7, off offset:1152
	v_mul_f32_e32 v20, v130, v6
	v_bfe_u32 v21, v20, 16, 1
	s_waitcnt lgkmcnt(0)
; DI unsigned short f2bf(float x) { unsigned u = __float_as_uint(x); u += 0x7fffu + ((u >> 16) & 1u); return (unsigned short)(u >> 16); }
; DI float shx(float v, int mask, int lane) { return __int_as_float(__builtin_amdgcn_ds_bpermute((lane ^ mask) << 2, __float_as_int(v))); }
; DI int crow(int r, int hi) { return (r & 3) + 8 * (r >> 2) + 4 * hi; }
; template <int DQK, int MODE, int LDQ, int LDK, int LDV> ...
;     ...
;     for (int r = 0; r < 16; ++r) { const int orow = wid * 32 + crow(r, hi); const float rl = __builtin_amdgcn_rcpf(li_l[crow(r, hi)]);
;         if constexpr (MODE == 0) {
; #pragma unroll
;             for (int d0 = 0; d0 < 4; ++d0) AOb[(size_t)orow * 1024 + d0 * 32 + r32] = f2bf(o[d0][r] * rl);
;         } else if constexpr (MODE == 1) {
; #pragma unroll
;             for (int d0 = 0; d0 < 4; ++d0) S0[(size_t)orow * 512 + d0 * 32 + r32] = o[d0][r] * rl;
;         } else {
;             float v[4]; float ss = 0.f;
; #pragma unroll
;             for (int d0 = 0; d0 < 4; ++d0) { v[d0] = s0v[r][d0] - lam * (o[d0][r] * rl); ss += v[d0] * v[d0]; }
; #pragma unroll
;             for (int mk = 1; mk <= 16; mk <<= 1) ss += shx(ss, mk, lane2);
;             const float rs = rsqrtf(ss * (1.f / 128.f) + EPS) * 0.8f;
; #pragma unroll
;             for (int d0 = 0; d0 < 4; ++d0) AOb[(size_t)orow * 1024 + d0 * 32 + r32] = f2bf(v[d0] * rs * gout[d0 * 32 + r32]);
;         } }
; DI void phase4(const Params& p, LAS unsigned char* lds, int wv) {
;     ...
;             __syncthreads();
	v_pk_add_f32 v[6:7], v[8:9], v[10:11]
	s_nop 0
	v_pk_fma_f32 v[6:7], v[6:7], s[24:25], v[92:93] op_sel_hi:[1,0,0]
	s_nop 0
	v_mul_f32_e32 v8, 0x4b800000, v7
	v_cmp_gt_f32_e32 vcc, s67, v7
	s_nop 1
	v_cndmask_b32_e32 v7, v7, v8, vcc
	v_rsq_f32_e32 v7, v7
	v_add3_u32 v8, v20, v21, s68
	global_store_short_d16_hi v[22:23], v8, off offset:1216
	v_lshl_add_u64 v[8:9], v[32:33], 0, v[74:75]
	v_mul_f32_e32 v10, 0x45800000, v7
	v_cndmask_b32_e32 v7, v7, v10, vcc
	v_mul_f32_e32 v7, 0x3f4ccccd, v7
	v_mul_f32_e32 v4, v4, v7
	v_mul_f32_e32 v4, v163, v4
	v_bfe_u32 v10, v4, 16, 1
	v_add3_u32 v4, v4, v10, s68
	global_store_short_d16_hi v[8:9], v4, off offset:1024
	v_mul_f32_e32 v4, v5, v7
	v_mul_f32_e32 v4, v162, v4
	v_bfe_u32 v5, v4, 16, 1
	v_add3_u32 v4, v4, v5, s68
	global_store_short_d16_hi v[8:9], v4, off offset:1088
	v_mul_f32_e32 v4, v19, v7
	v_mul_f32_e32 v4, v161, v4
	v_bfe_u32 v5, v4, 16, 1
	v_add3_u32 v4, v4, v5, s68
	v_mul_f32_e32 v5, 0x4b800000, v6
	v_cmp_gt_f32_e32 vcc, s67, v6
	global_store_short_d16_hi v[8:9], v4, off offset:1152
	v_mul_f32_e32 v4, v18, v7
	v_cndmask_b32_e32 v5, v6, v5, vcc
	v_rsq_f32_e32 v5, v5
	v_mul_f32_e32 v4, v130, v4
	v_bfe_u32 v6, v4, 16, 1
	v_add3_u32 v4, v4, v6, s68
	global_store_short_d16_hi v[8:9], v4, off offset:1216
	v_mul_f32_e32 v4, 0x45800000, v5
	v_cndmask_b32_e32 v24, v5, v4, vcc
	v_mov_b32_e32 v4, v14
	v_mov_b32_e32 v5, v62
	v_mov_b32_e32 v8, v46
	v_mov_b32_e32 v9, v30
	v_pk_mul_f32 v[4:5], v[4:5], v[2:3] op_sel_hi:[1,0]
	v_pk_mul_f32 v[8:9], v[8:9], v[2:3] op_sel_hi:[1,0]
	v_rcp_f32_e32 v2, v3
	v_mov_b32_e32 v62, v15
	v_mov_b32_e32 v30, v47
	s_waitcnt vmcnt(58)
	v_pk_fma_f32 v[4:5], v[128:129], v[4:5], v[108:109] neg_lo:[1,0,0] neg_hi:[1,0,0]
	v_pk_mul_f32 v[14:15], v[62:63], v[2:3] op_sel_hi:[1,0]
	v_pk_mul_f32 v[2:3], v[30:31], v[2:3] op_sel_hi:[1,0]
	s_waitcnt vmcnt(54)
	v_pk_fma_f32 v[14:15], v[128:129], v[14:15], v[104:105] neg_lo:[1,0,0] neg_hi:[1,0,0]
	v_pk_mul_f32 v[6:7], v[4:5], v[4:5]
	v_pk_fma_f32 v[8:9], v[128:129], v[8:9], v[106:107] neg_lo:[1,0,0] neg_hi:[1,0,0]
	v_pk_mul_f32 v[18:19], v[14:15], v[14:15]
	s_waitcnt vmcnt(52)
	v_pk_fma_f32 v[2:3], v[128:129], v[2:3], v[102:103] neg_lo:[1,0,0] neg_hi:[1,0,0]
	v_pk_mul_f32 v[10:11], v[8:9], v[8:9]
	v_pk_mul_f32 v[20:21], v[2:3], v[2:3]
	v_mov_b32_e32 v22, v18
	v_mov_b32_e32 v23, v6
	v_mov_b32_e32 v6, v19
	v_pk_add_f32 v[6:7], v[22:23], v[6:7]
	v_mov_b32_e32 v18, v21
	v_mov_b32_e32 v19, v11
	v_pk_add_f32 v[6:7], v[18:19], v[6:7]
	v_mov_b32_e32 v21, v10
	v_pk_add_f32 v[6:7], v[20:21], v[6:7]
	ds_bpermute_b32 v11, v164, v7
	ds_bpermute_b32 v10, v164, v6
	v_mul_f32_e32 v20, 0x3f4ccccd, v24
	v_mul_f32_e32 v12, v12, v20
	v_mul_f32_e32 v12, v163, v12
	v_bfe_u32 v21, v12, 16, 1
	s_waitcnt lgkmcnt(0)
	v_pk_add_f32 v[6:7], v[6:7], v[10:11]
	ds_bpermute_b32 v11, v165, v7
	ds_bpermute_b32 v10, v165, v6
	v_lshl_add_u64 v[18:19], v[32:33], 0, v[64:65]
	v_add3_u32 v12, v12, v21, s68
	global_store_short_d16_hi v[18:19], v12, off offset:1024
	v_mul_f32_e32 v12, v13, v20
	s_waitcnt lgkmcnt(0)
	v_pk_add_f32 v[6:7], v[6:7], v[10:11]
	ds_bpermute_b32 v11, v168, v7
	ds_bpermute_b32 v10, v168, v6
	v_mul_f32_e32 v12, v162, v12
	v_bfe_u32 v13, v12, 16, 1
	v_mul_f32_e32 v1, v1, v20
	v_add3_u32 v12, v12, v13, s68
	s_waitcnt lgkmcnt(0)
	v_pk_add_f32 v[6:7], v[6:7], v[10:11]
	ds_bpermute_b32 v11, v167, v7
	ds_bpermute_b32 v10, v167, v6
	v_mul_f32_e32 v1, v161, v1
	global_store_short_d16_hi v[18:19], v12, off offset:1088
	v_bfe_u32 v12, v1, 16, 1
	v_add3_u32 v1, v1, v12, s68
	s_waitcnt lgkmcnt(0)
	v_pk_add_f32 v[6:7], v[6:7], v[10:11]
	ds_bpermute_b32 v11, v166, v7
	ds_bpermute_b32 v10, v166, v6
	v_mul_f32_e32 v0, v0, v20
	global_store_short_d16_hi v[18:19], v1, off offset:1152
	v_mul_f32_e32 v12, v130, v0
	v_bfe_u32 v13, v12, 16, 1
	s_waitcnt lgkmcnt(0)
	v_pk_add_f32 v[0:1], v[6:7], v[10:11]
	s_nop 0
	v_pk_fma_f32 v[0:1], v[0:1], s[24:25], v[92:93] op_sel_hi:[1,0,0]
	s_nop 0
	v_mul_f32_e32 v6, 0x4b800000, v1
	v_cmp_gt_f32_e32 vcc, s67, v1
	s_nop 1
	v_cndmask_b32_e32 v1, v1, v6, vcc
	v_rsq_f32_e32 v1, v1
	v_add3_u32 v6, v12, v13, s68
	global_store_short_d16_hi v[18:19], v6, off offset:1216
	v_lshl_add_u64 v[6:7], v[32:33], 0, v[48:49]
	v_mul_f32_e32 v10, 0x45800000, v1
	v_cndmask_b32_e32 v1, v1, v10, vcc
	v_mul_f32_e32 v1, 0x3f4ccccd, v1
	v_mul_f32_e32 v4, v4, v1
	v_mul_f32_e32 v4, v163, v4
	v_bfe_u32 v10, v4, 16, 1
	v_add3_u32 v4, v4, v10, s68
	global_store_short_d16_hi v[6:7], v4, off offset:1024
	v_mul_f32_e32 v4, v5, v1
	v_mul_f32_e32 v4, v162, v4
	v_bfe_u32 v5, v4, 16, 1
	v_add3_u32 v4, v4, v5, s68
	global_store_short_d16_hi v[6:7], v4, off offset:1088
	v_mul_f32_e32 v4, v9, v1
	v_mul_f32_e32 v4, v161, v4
	v_bfe_u32 v5, v4, 16, 1
	v_add3_u32 v4, v4, v5, s68
	global_store_short_d16_hi v[6:7], v4, off offset:1152
	v_mul_f32_e32 v4, 0x4b800000, v0
	v_cmp_gt_f32_e32 vcc, s67, v0
	v_mul_f32_e32 v1, v8, v1
	v_mul_f32_e32 v1, v130, v1
	v_cndmask_b32_e32 v0, v0, v4, vcc
	v_rsq_f32_e32 v0, v0
	v_bfe_u32 v4, v1, 16, 1
	v_add3_u32 v1, v1, v4, s68
	global_store_short_d16_hi v[6:7], v1, off offset:1216
	v_mul_f32_e32 v1, 0x45800000, v0
	v_cndmask_b32_e32 v0, v0, v1, vcc
	v_mul_f32_e32 v4, 0x3f4ccccd, v0
	v_mul_f32_e32 v5, v14, v4
	v_mul_f32_e32 v5, v163, v5
	v_bfe_u32 v6, v5, 16, 1
	v_lshl_add_u64 v[0:1], v[32:33], 0, v[16:17]
	v_add3_u32 v5, v5, v6, s68
	global_store_short_d16_hi v[0:1], v5, off offset:1024
	v_mul_f32_e32 v5, v15, v4
	v_mul_f32_e32 v5, v162, v5
	v_bfe_u32 v6, v5, 16, 1
	v_mul_f32_e32 v3, v3, v4
	v_add3_u32 v5, v5, v6, s68
	v_mul_f32_e32 v3, v161, v3
	global_store_short_d16_hi v[0:1], v5, off offset:1088
	v_bfe_u32 v5, v3, 16, 1
	v_mul_f32_e32 v2, v2, v4
	v_add3_u32 v3, v3, v5, s68
	v_mul_f32_e32 v2, v130, v2
	global_store_short_d16_hi v[0:1], v3, off offset:1152
	v_bfe_u32 v3, v2, 16, 1
	v_add3_u32 v2, v2, v3, s68
	global_store_short_d16_hi v[0:1], v2, off offset:1216
	s_waitcnt vmcnt(63) expcnt(7) lgkmcnt(15)
	s_barrier

; #define LAS __attribute__((address_space(3)))
; DI void expsum(f32x16& p, float& l_reg, bf16x8& pa0, bf16x8& pa1) {
; #pragma unroll
;     for (int r = 0; r < 16; ++r) p[r] = __builtin_amdgcn_exp2f(p[r]);
;     float ps = 0.f;
; #pragma unroll
;     for (int r = 0; r < 16; ++r) ps += p[r];
;     l_reg += ps; asm volatile("" : "+v"(l_reg));
;     ...
;     ATT_PK4(p, 0, pa0); ATT_PK4(p, 8, pa1);
;     ...
; }
; DI int v_rd_base(int lane) { return ((lane & 3) << 3) | (((lane >> 2) & 3) << 6) | (((lane >> 4) & 1) << 5) | (((lane >> 5) & 1) << 8); }
; template <int OFF> DI s16x4 tr_read(int vb) { s16x4 r; asm volatile("ds_read_b64_tr_b16 %0, %1 offset:%2" : "=&v"(r) : "v"(vb), "i"(OFF) : "memory"); return r; }
; template <int H> DI void v_reads(s16x4* vf, int vb) {
;     vf[0] = tr_read<v_rd_off(0, 2 * H, 0)>(vb); vf[1] = tr_read<v_rd_off(0, 2 * H, 1)>(vb); vf[2] = tr_read<v_rd_off(0, 2 * H + 1, 0)>(vb); vf[3] = tr_read<v_rd_off(0, 2 * H + 1, 1)>(vb);
;     vf[4] = tr_read<v_rd_off(1, 2 * H, 0)>(vb); vf[5] = tr_read<v_rd_off(1, 2 * H, 1)>(vb); vf[6] = tr_read<v_rd_off(1, 2 * H + 1, 0)>(vb); vf[7] = tr_read<v_rd_off(1, 2 * H + 1, 1)>(vb);
;     vf[8] = tr_read<v_rd_off(2, 2 * H, 0)>(vb); vf[9] = tr_read<v_rd_off(2, 2 * H, 1)>(vb); vf[10] = tr_read<v_rd_off(2, 2 * H + 1, 0)>(vb); vf[11] = tr_read<v_rd_off(2, 2 * H + 1, 1)>(vb);
;     vf[12] = tr_read<v_rd_off(3, 2 * H, 0)>(vb); vf[13] = tr_read<v_rd_off(3, 2 * H, 1)>(vb); vf[14] = tr_read<v_rd_off(3, 2 * H + 1, 0)>(vb); vf[15] = tr_read<v_rd_off(3, 2 * H + 1, 1)>(vb);
; }
; DI void pv_mma(f32x16* o, const s16x4* vf, bf16x8 pa0, bf16x8 pa1) {
;     ...
; #pragma unroll
;     for (int d0 = 0; d0 < 4; ++d0) {
;         o[d0] = __builtin_amdgcn_mfma_f32_32x32x16_bf16(pa0, ATT_PK(vf[4 * d0], vf[4 * d0 + 1]), o[d0], 0, 0, 0);
;         o[d0] = __builtin_amdgcn_mfma_f32_32x32x16_bf16(pa1, ATT_PK(vf[4 * d0 + 2], vf[4 * d0 + 3]), o[d0], 0, 0, 0); }
;     ...
; }
; template <int DQK, int D0A, int D0B> DI void k_reads(bf16x8* kf, const LAS unsigned char* Ks, int half, int r32, int hi) {
; #pragma unroll
;     for (int d0 = D0A; d0 < D0B; ++d0) kf[d0 - D0A] = *(const LAS bf16x8*)(Ks + half * (32 * DQK * 2) + kswz<DQK>(r32, (d0 * 16 + hi * 8) * 2));
; }
.Lstg_mla_top_2:
	s_setprio 0
	s_mov_b32 m0, s1
	s_mov_b32 s0, s5
	s_mov_b32 s5, s44
	s_mov_b32 s44, s4
	s_lshl_b32 s4, s4, 14
	global_load_lds_dwordx4 v136, s[34:35]
	s_add_i32 m0, s1, 0x2000
	s_add_i32 s4, s52, s4
	global_load_lds_dwordx4 v138, s[34:35]
	s_add_i32 m0, s1, 0x4000
	s_add_i32 s6, s4, 0x400
	global_load_lds_dwordx4 v140, s[34:35]
	s_mov_b32 m0, s4
	s_add_i32 s1, s43, -3
	global_load_lds_dwordx4 v144, s[34:35]
	s_mov_b32 m0, s6
	s_nop 0
	global_load_lds_dwordx4 v142, s[34:35]
	s_and_b32 s1, s1, 3
	s_mulk_i32 s1, 0x6000
	v_add_u32_e32 v246, s1, v158
	v_add_u32_e32 v174, v246, v151
	v_add_u32_e32 v178, v246, v149
	v_add_u32_e32 v182, v246, v148
	v_add_u32_e32 v186, v246, v147
	s_lshl_b32 s1, s0, 14
	ds_read_b128 v[190:193], v174 offset:12416
	ds_read_b128 v[194:197], v178 offset:12416
	ds_read_b128 v[174:177], v174 offset:12288
	ds_read_b128 v[178:181], v178 offset:12288
	ds_read_b128 v[182:185], v182 offset:12288
	ds_read_b128 v[186:189], v186 offset:12288
	v_add_u32_e32 v254, s1, v130
	ds_read_b64_tr_b16 v[198:199], v254 offset:0
	ds_read_b64_tr_b16 v[200:201], v254 offset:0x800
	ds_read_b64_tr_b16 v[202:203], v254 offset:0x1000
	ds_read_b64_tr_b16 v[204:205], v254 offset:0x1800
	ds_read_b64_tr_b16 v[206:207], v254 offset:0x200
	ds_read_b64_tr_b16 v[208:209], v254 offset:0xa00
	ds_read_b64_tr_b16 v[210:211], v254 offset:0x1200
	ds_read_b64_tr_b16 v[212:213], v254 offset:0x1a00
	ds_read_b64_tr_b16 v[214:215], v254 offset:0x400
	ds_read_b64_tr_b16 v[216:217], v254 offset:0xc00
	ds_read_b64_tr_b16 v[218:219], v254 offset:0x1400
	ds_read_b64_tr_b16 v[220:221], v254 offset:0x1c00
	ds_read_b64_tr_b16 v[222:223], v254 offset:0x600
	ds_read_b64_tr_b16 v[224:225], v254 offset:0xe00
	ds_read_b64_tr_b16 v[226:227], v254 offset:0x1600
	ds_read_b64_tr_b16 v[228:229], v254 offset:0x1e00
	s_setprio 2
	v_exp_f32_e32 v64, v64
	v_exp_f32_e32 v65, v65
	v_exp_f32_e32 v66, v66
	v_exp_f32_e32 v67, v67
	v_exp_f32_e32 v68, v68
	v_exp_f32_e32 v69, v69
	v_add_f32_e32 v230, v65, v64
	v_exp_f32_e32 v70, v70
	v_add_f32_e32 v230, v66, v230
	v_exp_f32_e32 v71, v71
	v_add_f32_e32 v230, v67, v230
	v_exp_f32_e32 v72, v72
	v_add_f32_e32 v230, v68, v230
	v_exp_f32_e32 v73, v73
	v_add_f32_e32 v230, v69, v230
	v_exp_f32_e32 v74, v74
	v_add_f32_e32 v230, v70, v230
	v_exp_f32_e32 v75, v75
	v_add_f32_e32 v230, v71, v230
	v_exp_f32_e32 v76, v76
	v_add_f32_e32 v230, v72, v230
	v_exp_f32_e32 v77, v77
	v_add_f32_e32 v230, v73, v230
	v_exp_f32_e32 v78, v78
	v_add_f32_e32 v230, v74, v230
	v_exp_f32_e32 v79, v79
	v_add_f32_e32 v230, v75, v230
	v_add_f32_e32 v230, v76, v230
	v_add_f32_e32 v230, v77, v230
	v_add_f32_e32 v230, v78, v230
	v_add_f32_e32 v230, v79, v230
	v_add_f32_e32 v173, v173, v230
	v_cvt_pk_bf16_f32 v64, v64, v65
	v_cvt_pk_bf16_f32 v65, v66, v67
	v_cvt_pk_bf16_f32 v66, v68, v69
	v_cvt_pk_bf16_f32 v67, v70, v71
	v_cvt_pk_bf16_f32 v68, v72, v73
	v_cvt_pk_bf16_f32 v69, v74, v75
	v_cvt_pk_bf16_f32 v70, v76, v77
	v_cvt_pk_bf16_f32 v71, v78, v79
	v_permlane32_swap_b32_e32 v64, v66
	v_permlane32_swap_b32_e32 v65, v67
	v_permlane32_swap_b32_e32 v68, v70
	v_permlane32_swap_b32_e32 v69, v71
	s_waitcnt lgkmcnt(0)
	v_add_u32_e32 v72, v246, v151
	v_add_u32_e32 v73, v246, v149
	v_add_u32_e32 v74, v246, v148
	v_add_u32_e32 v75, v246, v147
	ds_read_b128 v[230:233], v74 offset:12416
	ds_read_b128 v[234:237], v75 offset:12416
	ds_read_b128 v[238:241], v72 offset:12544
	ds_read_b128 v[242:245], v73 offset:12544
	ds_read_b128 v[246:249], v74 offset:12544
	ds_read_b128 v[250:253], v75 offset:12544
	s_setprio 1
	v_mfma_f32_32x32x16_bf16 v[48:63], v[64:67], v[198:201], v[48:63]
	v_mfma_f32_32x32x16_bf16 v[32:47], v[64:67], v[206:209], v[32:47]
	v_mfma_f32_32x32x16_bf16 v[16:31], v[64:67], v[214:217], v[16:31]
	v_mfma_f32_32x32x16_bf16 v[0:15], v[64:67], v[222:225], v[0:15]
	v_mfma_f32_32x32x16_bf16 v[48:63], v[68:71], v[202:205], v[48:63]
	v_mfma_f32_32x32x16_bf16 v[32:47], v[68:71], v[210:213], v[32:47]
	v_mfma_f32_32x32x16_bf16 v[16:31], v[68:71], v[218:221], v[16:31]
	v_mfma_f32_32x32x16_bf16 v[0:15], v[68:71], v[226:229], v[0:15]
	s_waitcnt lgkmcnt(0)
; #define LAS __attribute__((address_space(3)))
; DI void expsum(f32x16& p, float& l_reg, bf16x8& pa0, bf16x8& pa1) {
; #pragma unroll
;     for (int r = 0; r < 16; ++r) p[r] = __builtin_amdgcn_exp2f(p[r]);
;     float ps = 0.f;
; #pragma unroll
;     for (int r = 0; r < 16; ++r) ps += p[r];
;     l_reg += ps; asm volatile("" : "+v"(l_reg));
;     ...
;     ATT_PK4(p, 0, pa0); ATT_PK4(p, 8, pa1);
;     ...
; }
; DI int v_rd_base(int lane) { return ((lane & 3) << 3) | (((lane >> 2) & 3) << 6) | (((lane >> 4) & 1) << 5) | (((lane >> 5) & 1) << 8); }
; template <int OFF> DI s16x4 tr_read(int vb) { s16x4 r; asm volatile("ds_read_b64_tr_b16 %0, %1 offset:%2" : "=&v"(r) : "v"(vb), "i"(OFF) : "memory"); return r; }
; template <int H> DI void v_reads(s16x4* vf, int vb) {
;     vf[0] = tr_read<v_rd_off(0, 2 * H, 0)>(vb); vf[1] = tr_read<v_rd_off(0, 2 * H, 1)>(vb); vf[2] = tr_read<v_rd_off(0, 2 * H + 1, 0)>(vb); vf[3] = tr_read<v_rd_off(0, 2 * H + 1, 1)>(vb);
;     vf[4] = tr_read<v_rd_off(1, 2 * H, 0)>(vb); vf[5] = tr_read<v_rd_off(1, 2 * H, 1)>(vb); vf[6] = tr_read<v_rd_off(1, 2 * H + 1, 0)>(vb); vf[7] = tr_read<v_rd_off(1, 2 * H + 1, 1)>(vb);
;     vf[8] = tr_read<v_rd_off(2, 2 * H, 0)>(vb); vf[9] = tr_read<v_rd_off(2, 2 * H, 1)>(vb); vf[10] = tr_read<v_rd_off(2, 2 * H + 1, 0)>(vb); vf[11] = tr_read<v_rd_off(2, 2 * H + 1, 1)>(vb);
;     vf[12] = tr_read<v_rd_off(3, 2 * H, 0)>(vb); vf[13] = tr_read<v_rd_off(3, 2 * H, 1)>(vb); vf[14] = tr_read<v_rd_off(3, 2 * H + 1, 0)>(vb); vf[15] = tr_read<v_rd_off(3, 2 * H + 1, 1)>(vb);
; }
; DI void pv_mma(f32x16* o, const s16x4* vf, bf16x8 pa0, bf16x8 pa1) {
;     ...
; #pragma unroll
;     for (int d0 = 0; d0 < 4; ++d0) {
;         o[d0] = __builtin_amdgcn_mfma_f32_32x32x16_bf16(pa0, ATT_PK(vf[4 * d0], vf[4 * d0 + 1]), o[d0], 0, 0, 0);
;         o[d0] = __builtin_amdgcn_mfma_f32_32x32x16_bf16(pa1, ATT_PK(vf[4 * d0 + 2], vf[4 * d0 + 3]), o[d0], 0, 0, 0); }
;     ...
; }
; template <int DQK, int D0A, int D0B> DI void k_reads(bf16x8* kf, const LAS unsigned char* Ks, int half, int r32, int hi) {
; #pragma unroll
;     for (int d0 = D0A; d0 < D0B; ++d0) kf[d0 - D0A] = *(const LAS bf16x8*)(Ks + half * (32 * DQK * 2) + kswz<DQK>(r32, (d0 * 16 + hi * 8) * 2));
; }
; template <int D0A, int D0B> DI void qk_mma(f32x16& p, const bf16x8* kf, const bf16x8* qr) {
; #pragma unroll
;     for (int d0 = D0A; d0 < D0B; ++d0) {
	v_mfma_f32_32x32x16_bf16 v[64:79], v[174:177], v[80:83], 0
	v_mfma_f32_32x32x16_bf16 v[64:79], v[178:181], v[84:87], v[64:79]
	v_mfma_f32_32x32x16_bf16 v[64:79], v[182:185], v[88:91], v[64:79]
	v_mfma_f32_32x32x16_bf16 v[64:79], v[186:189], v[92:95], v[64:79]
	v_mfma_f32_32x32x16_bf16 v[64:79], v[190:193], v[96:99], v[64:79]
	v_mfma_f32_32x32x16_bf16 v[64:79], v[194:197], v[100:103], v[64:79]
	v_mfma_f32_32x32x16_bf16 v[64:79], v[230:233], v[104:107], v[64:79]
	v_mfma_f32_32x32x16_bf16 v[64:79], v[234:237], v[108:111], v[64:79]
	v_mfma_f32_32x32x16_bf16 v[64:79], v[238:241], v[112:115], v[64:79]
	v_mfma_f32_32x32x16_bf16 v[64:79], v[242:245], v[116:119], v[64:79]
	v_mfma_f32_32x32x16_bf16 v[64:79], v[246:249], v[120:123], v[64:79]
	v_mfma_f32_32x32x16_bf16 v[64:79], v[250:253], v[124:127], v[64:79]
	s_setprio 0
	s_add_i32 s4, s43, -2
	s_and_b32 s4, s4, 3
	s_mulk_i32 s4, 0x6000
	v_add_u32_e32 v246, s4, v158
	v_add_u32_e32 v174, v246, v151
	v_add_u32_e32 v178, v246, v149
	v_add_u32_e32 v182, v246, v148
	v_add_u32_e32 v186, v246, v147
	ds_read_b128 v[190:193], v174 offset:128
	ds_read_b128 v[194:197], v178 offset:128
	ds_read_b128 v[174:177], v174
	ds_read_b128 v[178:181], v178
	ds_read_b128 v[182:185], v182
	ds_read_b128 v[186:189], v186
	ds_read_b64_tr_b16 v[198:199], v254 offset:0x2000
	ds_read_b64_tr_b16 v[200:201], v254 offset:0x2800
	ds_read_b64_tr_b16 v[202:203], v254 offset:0x3000
	ds_read_b64_tr_b16 v[204:205], v254 offset:0x3800
	ds_read_b64_tr_b16 v[206:207], v254 offset:0x2200
	ds_read_b64_tr_b16 v[208:209], v254 offset:0x2a00
	ds_read_b64_tr_b16 v[210:211], v254 offset:0x3200
	ds_read_b64_tr_b16 v[212:213], v254 offset:0x3a00
	ds_read_b64_tr_b16 v[214:215], v254 offset:0x2400
	ds_read_b64_tr_b16 v[216:217], v254 offset:0x2c00
	ds_read_b64_tr_b16 v[218:219], v254 offset:0x3400
	ds_read_b64_tr_b16 v[220:221], v254 offset:0x3c00
	ds_read_b64_tr_b16 v[222:223], v254 offset:0x2600
	ds_read_b64_tr_b16 v[224:225], v254 offset:0x2e00
	ds_read_b64_tr_b16 v[226:227], v254 offset:0x3600
	ds_read_b64_tr_b16 v[228:229], v254 offset:0x3e00
	s_setprio 2
	v_exp_f32_e32 v64, v64
	v_exp_f32_e32 v65, v65
	v_exp_f32_e32 v66, v66
	v_exp_f32_e32 v67, v67
	v_exp_f32_e32 v68, v68
	v_exp_f32_e32 v69, v69
	v_add_f32_e32 v230, v65, v64
	v_exp_f32_e32 v70, v70
	v_add_f32_e32 v230, v66, v230
	v_exp_f32_e32 v71, v71
	v_add_f32_e32 v230, v67, v230
	v_exp_f32_e32 v72, v72
	v_add_f32_e32 v230, v68, v230
	v_exp_f32_e32 v73, v73
	v_add_f32_e32 v230, v69, v230
	v_exp_f32_e32 v74, v74
	v_add_f32_e32 v230, v70, v230
	v_exp_f32_e32 v75, v75
	v_add_f32_e32 v230, v71, v230
	v_exp_f32_e32 v76, v76
	v_add_f32_e32 v230, v72, v230
	v_exp_f32_e32 v77, v77
	v_add_f32_e32 v230, v73, v230
	v_exp_f32_e32 v78, v78
	v_add_f32_e32 v230, v74, v230
	v_exp_f32_e32 v79, v79
	v_add_f32_e32 v230, v75, v230
	v_add_f32_e32 v230, v76, v230
	v_add_f32_e32 v230, v77, v230
	v_add_f32_e32 v230, v78, v230
	v_add_f32_e32 v230, v79, v230
	v_add_f32_e32 v173, v173, v230
	v_cvt_pk_bf16_f32 v64, v64, v65
	v_cvt_pk_bf16_f32 v65, v66, v67
	v_cvt_pk_bf16_f32 v66, v68, v69
	v_cvt_pk_bf16_f32 v67, v70, v71
	v_cvt_pk_bf16_f32 v68, v72, v73
	v_cvt_pk_bf16_f32 v69, v74, v75
	v_cvt_pk_bf16_f32 v70, v76, v77
	v_cvt_pk_bf16_f32 v71, v78, v79
	v_permlane32_swap_b32_e32 v64, v66
	v_permlane32_swap_b32_e32 v65, v67
	v_permlane32_swap_b32_e32 v68, v70
	v_permlane32_swap_b32_e32 v69, v71
	s_waitcnt lgkmcnt(0)
	v_add_u32_e32 v72, v246, v151
	v_add_u32_e32 v73, v246, v149
	v_add_u32_e32 v74, v246, v148
	v_add_u32_e32 v75, v246, v147
	ds_read_b128 v[230:233], v74 offset:128
	ds_read_b128 v[234:237], v75 offset:128
	ds_read_b128 v[238:241], v72 offset:256
	ds_read_b128 v[242:245], v73 offset:256
	ds_read_b128 v[246:249], v74 offset:256
	ds_read_b128 v[250:253], v75 offset:256
	s_setprio 1
	s_cmp_lt_u32 s33, 0x100
	s_cbranch_scc1 .Lstg_mla_mid_3
	s_waitcnt vmcnt(5)
	s_barrier

; #define LAS __attribute__((address_space(3)))
; DI void expsum(f32x16& p, float& l_reg, bf16x8& pa0, bf16x8& pa1) {
; #pragma unroll
;     for (int r = 0; r < 16; ++r) p[r] = __builtin_amdgcn_exp2f(p[r]);
;     float ps = 0.f;
; #pragma unroll
;     for (int r = 0; r < 16; ++r) ps += p[r];
;     l_reg += ps; asm volatile("" : "+v"(l_reg));
;     ...
;     ATT_PK4(p, 0, pa0); ATT_PK4(p, 8, pa1);
;     ...
; }
; DI int v_rd_base(int lane) { return ((lane & 3) << 3) | (((lane >> 2) & 3) << 6) | (((lane >> 4) & 1) << 5) | (((lane >> 5) & 1) << 8); }
; template <int OFF> DI s16x4 tr_read(int vb) { s16x4 r; asm volatile("ds_read_b64_tr_b16 %0, %1 offset:%2" : "=&v"(r) : "v"(vb), "i"(OFF) : "memory"); return r; }
; template <int H> DI void v_reads(s16x4* vf, int vb) {
;     vf[0] = tr_read<v_rd_off(0, 2 * H, 0)>(vb); vf[1] = tr_read<v_rd_off(0, 2 * H, 1)>(vb); vf[2] = tr_read<v_rd_off(0, 2 * H + 1, 0)>(vb); vf[3] = tr_read<v_rd_off(0, 2 * H + 1, 1)>(vb);
;     vf[4] = tr_read<v_rd_off(1, 2 * H, 0)>(vb); vf[5] = tr_read<v_rd_off(1, 2 * H, 1)>(vb); vf[6] = tr_read<v_rd_off(1, 2 * H + 1, 0)>(vb); vf[7] = tr_read<v_rd_off(1, 2 * H + 1, 1)>(vb);
;     vf[8] = tr_read<v_rd_off(2, 2 * H, 0)>(vb); vf[9] = tr_read<v_rd_off(2, 2 * H, 1)>(vb); vf[10] = tr_read<v_rd_off(2, 2 * H + 1, 0)>(vb); vf[11] = tr_read<v_rd_off(2, 2 * H + 1, 1)>(vb);
;     vf[12] = tr_read<v_rd_off(3, 2 * H, 0)>(vb); vf[13] = tr_read<v_rd_off(3, 2 * H, 1)>(vb); vf[14] = tr_read<v_rd_off(3, 2 * H + 1, 0)>(vb); vf[15] = tr_read<v_rd_off(3, 2 * H + 1, 1)>(vb);
; }
; DI void pv_mma(f32x16* o, const s16x4* vf, bf16x8 pa0, bf16x8 pa1) {
;     ...
; #pragma unroll
;     for (int d0 = 0; d0 < 4; ++d0) {
;         o[d0] = __builtin_amdgcn_mfma_f32_32x32x16_bf16(pa0, ATT_PK(vf[4 * d0], vf[4 * d0 + 1]), o[d0], 0, 0, 0);
;         o[d0] = __builtin_amdgcn_mfma_f32_32x32x16_bf16(pa1, ATT_PK(vf[4 * d0 + 2], vf[4 * d0 + 3]), o[d0], 0, 0, 0); }
;     ...
; }
; template <int DQK, int D0A, int D0B> DI void k_reads(bf16x8* kf, const LAS unsigned char* Ks, int half, int r32, int hi) {
; #pragma unroll
;     for (int d0 = D0A; d0 < D0B; ++d0) kf[d0 - D0A] = *(const LAS bf16x8*)(Ks + half * (32 * DQK * 2) + kswz<DQK>(r32, (d0 * 16 + hi * 8) * 2));
; }
.Lstg_mla_t61_4:
	s_setprio 0
	v_lshl_add_u64 v[132:133], v[132:133], 1, s[0:1]
	s_mov_b32 m0, s6
	v_lshl_add_u64 v[134:135], v[134:135], 1, s[0:1]
	global_load_lds_dwordx4 v[132:133], off
	s_mov_b32 m0, s7
	s_nop 0
	global_load_lds_dwordx4 v[134:135], off
	ds_read_b128 v[132:135], v161 offset:36864
	ds_read_b128 v[136:139], v162 offset:36864
	ds_read_b128 v[140:143], v163 offset:36864
	ds_read_b128 v[174:177], v164 offset:36864
	ds_read_b128 v[178:181], v165 offset:36864
	ds_read_b128 v[182:185], v166 offset:36864
	v_lshl_add_u32 v144, s5, 14, v130
	ds_read_b64_tr_b16 v[186:187], v144 offset:0
	ds_read_b64_tr_b16 v[188:189], v144 offset:0x800
	ds_read_b64_tr_b16 v[190:191], v144 offset:0x1000
	ds_read_b64_tr_b16 v[192:193], v144 offset:0x1800
	ds_read_b64_tr_b16 v[194:195], v144 offset:0x200
	ds_read_b64_tr_b16 v[196:197], v144 offset:0xa00
	ds_read_b64_tr_b16 v[198:199], v144 offset:0x1200
	ds_read_b64_tr_b16 v[200:201], v144 offset:0x1a00
	ds_read_b64_tr_b16 v[202:203], v144 offset:0x400
	ds_read_b64_tr_b16 v[204:205], v144 offset:0xc00
	ds_read_b64_tr_b16 v[206:207], v144 offset:0x1400
	ds_read_b64_tr_b16 v[208:209], v144 offset:0x1c00
	ds_read_b64_tr_b16 v[210:211], v144 offset:0x600
	ds_read_b64_tr_b16 v[212:213], v144 offset:0xe00
	ds_read_b64_tr_b16 v[214:215], v144 offset:0x1600
	ds_read_b64_tr_b16 v[216:217], v144 offset:0x1e00
	s_setprio 2
	v_exp_f32_e32 v64, v64
	v_exp_f32_e32 v65, v65
	v_exp_f32_e32 v66, v66
	v_exp_f32_e32 v67, v67
	v_exp_f32_e32 v68, v68
	v_exp_f32_e32 v69, v69
	v_add_f32_e32 v145, v65, v64
	v_exp_f32_e32 v70, v70
	v_add_f32_e32 v145, v66, v145
	v_exp_f32_e32 v71, v71
	v_add_f32_e32 v145, v67, v145
	v_exp_f32_e32 v72, v72
	v_add_f32_e32 v145, v68, v145
	v_exp_f32_e32 v73, v73
	v_add_f32_e32 v145, v69, v145
	v_exp_f32_e32 v74, v74
	v_add_f32_e32 v145, v70, v145
	v_exp_f32_e32 v75, v75
	v_add_f32_e32 v145, v71, v145
	v_exp_f32_e32 v76, v76
	v_add_f32_e32 v145, v72, v145
	v_exp_f32_e32 v77, v77
	v_add_f32_e32 v145, v73, v145
	v_exp_f32_e32 v78, v78
	v_add_f32_e32 v145, v74, v145
	v_exp_f32_e32 v79, v79
	v_add_f32_e32 v145, v75, v145
	v_add_f32_e32 v145, v76, v145
	v_add_f32_e32 v145, v77, v145
	v_add_f32_e32 v145, v78, v145
	v_add_f32_e32 v145, v79, v145
	v_add_f32_e32 v145, v173, v145
	v_cvt_pk_bf16_f32 v64, v64, v65
	v_cvt_pk_bf16_f32 v65, v66, v67
	v_cvt_pk_bf16_f32 v66, v68, v69
	v_cvt_pk_bf16_f32 v67, v70, v71
	v_cvt_pk_bf16_f32 v68, v72, v73
	v_cvt_pk_bf16_f32 v69, v74, v75
	v_cvt_pk_bf16_f32 v70, v76, v77
	v_cvt_pk_bf16_f32 v71, v78, v79
	v_permlane32_swap_b32_e32 v64, v66
	v_permlane32_swap_b32_e32 v65, v67
	v_permlane32_swap_b32_e32 v68, v70
	v_permlane32_swap_b32_e32 v69, v71
	s_waitcnt lgkmcnt(0)
	ds_read_b128 v[218:221], v167 offset:36864
	ds_read_b128 v[222:225], v168 offset:36864
	ds_read_b128 v[226:229], v169 offset:36864
	ds_read_b128 v[230:233], v170 offset:36864
	ds_read_b128 v[234:237], v171 offset:36864
	ds_read_b128 v[238:241], v172 offset:36864
	s_setprio 1
	v_mfma_f32_32x32x16_bf16 v[48:63], v[64:67], v[186:189], v[48:63]
	v_mfma_f32_32x32x16_bf16 v[32:47], v[64:67], v[194:197], v[32:47]
	v_mfma_f32_32x32x16_bf16 v[16:31], v[64:67], v[202:205], v[16:31]
	v_mfma_f32_32x32x16_bf16 v[0:15], v[64:67], v[210:213], v[0:15]
	v_mfma_f32_32x32x16_bf16 v[48:63], v[68:71], v[190:193], v[48:63]
	v_mfma_f32_32x32x16_bf16 v[32:47], v[68:71], v[198:201], v[32:47]
	v_mfma_f32_32x32x16_bf16 v[16:31], v[68:71], v[206:209], v[16:31]
	v_mfma_f32_32x32x16_bf16 v[0:15], v[68:71], v[214:217], v[0:15]
	s_waitcnt lgkmcnt(0)
; #define LAS __attribute__((address_space(3)))
; DI void expsum(f32x16& p, float& l_reg, bf16x8& pa0, bf16x8& pa1) {
; #pragma unroll
;     for (int r = 0; r < 16; ++r) p[r] = __builtin_amdgcn_exp2f(p[r]);
;     float ps = 0.f;
; #pragma unroll
;     for (int r = 0; r < 16; ++r) ps += p[r];
;     l_reg += ps; asm volatile("" : "+v"(l_reg));
;     ...
;     ATT_PK4(p, 0, pa0); ATT_PK4(p, 8, pa1);
;     ...
; }
; DI int v_rd_base(int lane) { return ((lane & 3) << 3) | (((lane >> 2) & 3) << 6) | (((lane >> 4) & 1) << 5) | (((lane >> 5) & 1) << 8); }
; template <int OFF> DI s16x4 tr_read(int vb) { s16x4 r; asm volatile("ds_read_b64_tr_b16 %0, %1 offset:%2" : "=&v"(r) : "v"(vb), "i"(OFF) : "memory"); return r; }
; template <int H> DI void v_reads(s16x4* vf, int vb) {
;     vf[0] = tr_read<v_rd_off(0, 2 * H, 0)>(vb); vf[1] = tr_read<v_rd_off(0, 2 * H, 1)>(vb); vf[2] = tr_read<v_rd_off(0, 2 * H + 1, 0)>(vb); vf[3] = tr_read<v_rd_off(0, 2 * H + 1, 1)>(vb);
;     vf[4] = tr_read<v_rd_off(1, 2 * H, 0)>(vb); vf[5] = tr_read<v_rd_off(1, 2 * H, 1)>(vb); vf[6] = tr_read<v_rd_off(1, 2 * H + 1, 0)>(vb); vf[7] = tr_read<v_rd_off(1, 2 * H + 1, 1)>(vb);
;     vf[8] = tr_read<v_rd_off(2, 2 * H, 0)>(vb); vf[9] = tr_read<v_rd_off(2, 2 * H, 1)>(vb); vf[10] = tr_read<v_rd_off(2, 2 * H + 1, 0)>(vb); vf[11] = tr_read<v_rd_off(2, 2 * H + 1, 1)>(vb);
;     vf[12] = tr_read<v_rd_off(3, 2 * H, 0)>(vb); vf[13] = tr_read<v_rd_off(3, 2 * H, 1)>(vb); vf[14] = tr_read<v_rd_off(3, 2 * H + 1, 0)>(vb); vf[15] = tr_read<v_rd_off(3, 2 * H + 1, 1)>(vb);
; }
; DI void pv_mma(f32x16* o, const s16x4* vf, bf16x8 pa0, bf16x8 pa1) {
;     ...
; #pragma unroll
;     for (int d0 = 0; d0 < 4; ++d0) {
;         o[d0] = __builtin_amdgcn_mfma_f32_32x32x16_bf16(pa0, ATT_PK(vf[4 * d0], vf[4 * d0 + 1]), o[d0], 0, 0, 0);
;         o[d0] = __builtin_amdgcn_mfma_f32_32x32x16_bf16(pa1, ATT_PK(vf[4 * d0 + 2], vf[4 * d0 + 3]), o[d0], 0, 0, 0); }
;     ...
; }
; template <int DQK, int D0A, int D0B> DI void k_reads(bf16x8* kf, const LAS unsigned char* Ks, int half, int r32, int hi) {
; #pragma unroll
;     for (int d0 = D0A; d0 < D0B; ++d0) kf[d0 - D0A] = *(const LAS bf16x8*)(Ks + half * (32 * DQK * 2) + kswz<DQK>(r32, (d0 * 16 + hi * 8) * 2));
; }
; template <int D0A, int D0B> DI void qk_mma(f32x16& p, const bf16x8* kf, const bf16x8* qr) {
; #pragma unroll
;     for (int d0 = D0A; d0 < D0B; ++d0) {
	v_mfma_f32_32x32x16_bf16 v[64:79], v[132:135], v[80:83], 0
	v_mfma_f32_32x32x16_bf16 v[64:79], v[136:139], v[84:87], v[64:79]
	v_mfma_f32_32x32x16_bf16 v[64:79], v[140:143], v[88:91], v[64:79]
	v_mfma_f32_32x32x16_bf16 v[64:79], v[174:177], v[92:95], v[64:79]
	v_mfma_f32_32x32x16_bf16 v[64:79], v[178:181], v[96:99], v[64:79]
	v_mfma_f32_32x32x16_bf16 v[64:79], v[182:185], v[100:103], v[64:79]
	s_waitcnt lgkmcnt(0)
	v_mfma_f32_32x32x16_bf16 v[64:79], v[218:221], v[104:107], v[64:79]
	v_mfma_f32_32x32x16_bf16 v[64:79], v[222:225], v[108:111], v[64:79]
	v_mfma_f32_32x32x16_bf16 v[64:79], v[226:229], v[112:115], v[64:79]
	v_mfma_f32_32x32x16_bf16 v[64:79], v[230:233], v[116:119], v[64:79]
	v_mfma_f32_32x32x16_bf16 v[64:79], v[234:237], v[120:123], v[64:79]
	v_mfma_f32_32x32x16_bf16 v[64:79], v[238:241], v[124:127], v[64:79]
	s_setprio 0
	ds_read_b128 v[132:135], v161 offset:49152
	ds_read_b128 v[136:139], v162 offset:49152
	ds_read_b128 v[140:143], v163 offset:49152
	ds_read_b128 v[174:177], v164 offset:49152
	ds_read_b128 v[178:181], v165 offset:49152
	ds_read_b128 v[182:185], v166 offset:49152
	ds_read_b64_tr_b16 v[186:187], v144 offset:0x2000
	ds_read_b64_tr_b16 v[188:189], v144 offset:0x2800
	ds_read_b64_tr_b16 v[190:191], v144 offset:0x3000
	ds_read_b64_tr_b16 v[192:193], v144 offset:0x3800
	ds_read_b64_tr_b16 v[194:195], v144 offset:0x2200
	ds_read_b64_tr_b16 v[196:197], v144 offset:0x2a00
	ds_read_b64_tr_b16 v[198:199], v144 offset:0x3200
	ds_read_b64_tr_b16 v[200:201], v144 offset:0x3a00
	ds_read_b64_tr_b16 v[202:203], v144 offset:0x2400
	ds_read_b64_tr_b16 v[204:205], v144 offset:0x2c00
	ds_read_b64_tr_b16 v[206:207], v144 offset:0x3400
	ds_read_b64_tr_b16 v[208:209], v144 offset:0x3c00
	ds_read_b64_tr_b16 v[210:211], v144 offset:0x2600
	ds_read_b64_tr_b16 v[212:213], v144 offset:0x2e00
	ds_read_b64_tr_b16 v[214:215], v144 offset:0x3600
	ds_read_b64_tr_b16 v[216:217], v144 offset:0x3e00
	s_nop 5
	s_setprio 2
	v_exp_f32_e32 v64, v64
	v_exp_f32_e32 v65, v65
	v_exp_f32_e32 v66, v66
	v_exp_f32_e32 v67, v67
	v_exp_f32_e32 v68, v68
	v_exp_f32_e32 v69, v69
	v_add_f32_e32 v144, v65, v64
	v_exp_f32_e32 v70, v70
	v_add_f32_e32 v144, v66, v144
	v_exp_f32_e32 v71, v71
	v_add_f32_e32 v144, v67, v144
	v_exp_f32_e32 v72, v72
	v_add_f32_e32 v144, v68, v144
	v_exp_f32_e32 v73, v73
	v_add_f32_e32 v144, v69, v144
	v_exp_f32_e32 v74, v74
	v_add_f32_e32 v144, v70, v144
	v_exp_f32_e32 v75, v75
	v_add_f32_e32 v144, v71, v144
	v_exp_f32_e32 v76, v76
	v_add_f32_e32 v144, v72, v144
	v_exp_f32_e32 v77, v77
	v_add_f32_e32 v144, v73, v144
	v_exp_f32_e32 v78, v78
	v_add_f32_e32 v144, v74, v144
	v_exp_f32_e32 v79, v79
	v_add_f32_e32 v144, v75, v144
	v_add_f32_e32 v144, v76, v144
	v_add_f32_e32 v144, v77, v144
	v_add_f32_e32 v144, v78, v144
	v_add_f32_e32 v144, v79, v144
	v_add_f32_e32 v144, v145, v144
	v_cvt_pk_bf16_f32 v64, v64, v65
	v_cvt_pk_bf16_f32 v65, v66, v67
	v_cvt_pk_bf16_f32 v66, v68, v69
	v_cvt_pk_bf16_f32 v67, v70, v71
	v_cvt_pk_bf16_f32 v68, v72, v73
	v_cvt_pk_bf16_f32 v69, v74, v75
	v_cvt_pk_bf16_f32 v70, v76, v77
	v_cvt_pk_bf16_f32 v71, v78, v79
	v_permlane32_swap_b32_e32 v64, v66
	v_permlane32_swap_b32_e32 v65, v67
	v_permlane32_swap_b32_e32 v68, v70
	v_permlane32_swap_b32_e32 v69, v71
	s_waitcnt lgkmcnt(0)
	ds_read_b128 v[218:221], v167 offset:49152
	ds_read_b128 v[222:225], v168 offset:49152
	ds_read_b128 v[226:229], v169 offset:49152
	ds_read_b128 v[230:233], v170 offset:49152
	ds_read_b128 v[234:237], v171 offset:49152
	ds_read_b128 v[238:241], v172 offset:49152
	s_setprio 1
	s_cmp_lt_u32 s33, 0x100
	s_cbranch_scc1 .Lstg_mla_m61_5
	s_waitcnt vmcnt(0)
	s_barrier

; #define LAS __attribute__((address_space(3)))
; DI void expsum(f32x16& p, float& l_reg, bf16x8& pa0, bf16x8& pa1) {
; #pragma unroll
;     for (int r = 0; r < 16; ++r) p[r] = __builtin_amdgcn_exp2f(p[r]);
;     float ps = 0.f;
; #pragma unroll
;     for (int r = 0; r < 16; ++r) ps += p[r];
;     l_reg += ps; asm volatile("" : "+v"(l_reg));
;     ...
;     ATT_PK4(p, 0, pa0); ATT_PK4(p, 8, pa1);
;     ...
; }
; DI int v_rd_base(int lane) { return ((lane & 3) << 3) | (((lane >> 2) & 3) << 6) | (((lane >> 4) & 1) << 5) | (((lane >> 5) & 1) << 8); }
; template <int OFF> DI s16x4 tr_read(int vb) { s16x4 r; asm volatile("ds_read_b64_tr_b16 %0, %1 offset:%2" : "=&v"(r) : "v"(vb), "i"(OFF) : "memory"); return r; }
; template <int H> DI void v_reads(s16x4* vf, int vb) {
;     vf[0] = tr_read<v_rd_off(0, 2 * H, 0)>(vb); vf[1] = tr_read<v_rd_off(0, 2 * H, 1)>(vb); vf[2] = tr_read<v_rd_off(0, 2 * H + 1, 0)>(vb); vf[3] = tr_read<v_rd_off(0, 2 * H + 1, 1)>(vb);
;     vf[4] = tr_read<v_rd_off(1, 2 * H, 0)>(vb); vf[5] = tr_read<v_rd_off(1, 2 * H, 1)>(vb); vf[6] = tr_read<v_rd_off(1, 2 * H + 1, 0)>(vb); vf[7] = tr_read<v_rd_off(1, 2 * H + 1, 1)>(vb);
;     vf[8] = tr_read<v_rd_off(2, 2 * H, 0)>(vb); vf[9] = tr_read<v_rd_off(2, 2 * H, 1)>(vb); vf[10] = tr_read<v_rd_off(2, 2 * H + 1, 0)>(vb); vf[11] = tr_read<v_rd_off(2, 2 * H + 1, 1)>(vb);
;     vf[12] = tr_read<v_rd_off(3, 2 * H, 0)>(vb); vf[13] = tr_read<v_rd_off(3, 2 * H, 1)>(vb); vf[14] = tr_read<v_rd_off(3, 2 * H + 1, 0)>(vb); vf[15] = tr_read<v_rd_off(3, 2 * H + 1, 1)>(vb);
; }
; DI void pv_mma(f32x16* o, const s16x4* vf, bf16x8 pa0, bf16x8 pa1) {
;     ...
; #pragma unroll
;     for (int d0 = 0; d0 < 4; ++d0) {
;         o[d0] = __builtin_amdgcn_mfma_f32_32x32x16_bf16(pa0, ATT_PK(vf[4 * d0], vf[4 * d0 + 1]), o[d0], 0, 0, 0);
;         o[d0] = __builtin_amdgcn_mfma_f32_32x32x16_bf16(pa1, ATT_PK(vf[4 * d0 + 2], vf[4 * d0 + 3]), o[d0], 0, 0, 0); }
;     ...
; }
; template <int DQK, int D0A, int D0B> DI void k_reads(bf16x8* kf, const LAS unsigned char* Ks, int half, int r32, int hi) {
; #pragma unroll
;     for (int d0 = D0A; d0 < D0B; ++d0) kf[d0 - D0A] = *(const LAS bf16x8*)(Ks + half * (32 * DQK * 2) + kswz<DQK>(r32, (d0 * 16 + hi * 8) * 2));
; }
; template <int D0A, int D0B> DI void qk_mma(f32x16& p, const bf16x8* kf, const bf16x8* qr) {
; #pragma unroll
;     for (int d0 = D0A; d0 < D0B; ++d0) {
.Lstg_mla_t62_6:
	s_setprio 0
	ds_read_b128 v[132:135], v161 offset:61440
	ds_read_b128 v[136:139], v162 offset:61440
	ds_read_b128 v[140:143], v163 offset:61440
	ds_read_b128 v[174:177], v164 offset:61440
	ds_read_b128 v[162:165], v165 offset:61440
	ds_read_b128 v[178:181], v166 offset:61440
	v_add_u32_e32 v145, 0x8000, v130
	ds_read_b64_tr_b16 v[182:183], v145 offset:0
	ds_read_b64_tr_b16 v[184:185], v145 offset:0x800
	ds_read_b64_tr_b16 v[186:187], v145 offset:0x1000
	ds_read_b64_tr_b16 v[188:189], v145 offset:0x1800
	ds_read_b64_tr_b16 v[190:191], v145 offset:0x200
	ds_read_b64_tr_b16 v[192:193], v145 offset:0xa00
	ds_read_b64_tr_b16 v[194:195], v145 offset:0x1200
	ds_read_b64_tr_b16 v[196:197], v145 offset:0x1a00
	ds_read_b64_tr_b16 v[198:199], v145 offset:0x400
	ds_read_b64_tr_b16 v[200:201], v145 offset:0xc00
	ds_read_b64_tr_b16 v[202:203], v145 offset:0x1400
	ds_read_b64_tr_b16 v[204:205], v145 offset:0x1c00
	ds_read_b64_tr_b16 v[206:207], v145 offset:0x600
	ds_read_b64_tr_b16 v[208:209], v145 offset:0xe00
	ds_read_b64_tr_b16 v[210:211], v145 offset:0x1600
	ds_read_b64_tr_b16 v[212:213], v145 offset:0x1e00
	s_nop 3
	s_setprio 2
	v_exp_f32_e32 v64, v64
	v_exp_f32_e32 v65, v65
	v_exp_f32_e32 v66, v66
	v_exp_f32_e32 v67, v67
	v_exp_f32_e32 v68, v68
	v_exp_f32_e32 v69, v69
	v_add_f32_e32 v161, v65, v64
	v_exp_f32_e32 v70, v70
	v_add_f32_e32 v161, v66, v161
	v_exp_f32_e32 v71, v71
	v_add_f32_e32 v161, v67, v161
	v_exp_f32_e32 v72, v72
	v_add_f32_e32 v161, v68, v161
	v_exp_f32_e32 v73, v73
	v_add_f32_e32 v161, v69, v161
	v_exp_f32_e32 v74, v74
	v_add_f32_e32 v161, v70, v161
	v_exp_f32_e32 v75, v75
	v_add_f32_e32 v161, v71, v161
	v_exp_f32_e32 v76, v76
	v_add_f32_e32 v161, v72, v161
	v_exp_f32_e32 v77, v77
	v_add_f32_e32 v161, v73, v161
	v_exp_f32_e32 v78, v78
	v_add_f32_e32 v161, v74, v161
	v_exp_f32_e32 v79, v79
	v_add_f32_e32 v161, v75, v161
	v_add_f32_e32 v161, v76, v161
	v_add_f32_e32 v161, v77, v161
	v_add_f32_e32 v161, v78, v161
	v_add_f32_e32 v161, v79, v161
	v_add_f32_e32 v144, v144, v161
	v_cvt_pk_bf16_f32 v64, v64, v65
	v_cvt_pk_bf16_f32 v65, v66, v67
	v_cvt_pk_bf16_f32 v66, v68, v69
	v_cvt_pk_bf16_f32 v67, v70, v71
	v_cvt_pk_bf16_f32 v68, v72, v73
	v_cvt_pk_bf16_f32 v69, v74, v75
	v_cvt_pk_bf16_f32 v70, v76, v77
	v_cvt_pk_bf16_f32 v71, v78, v79
	v_permlane32_swap_b32_e32 v64, v66
	v_permlane32_swap_b32_e32 v65, v67
	v_permlane32_swap_b32_e32 v68, v70
	v_permlane32_swap_b32_e32 v69, v71
	s_waitcnt lgkmcnt(0)
	ds_read_b128 v[214:217], v167 offset:61440
	ds_read_b128 v[218:221], v168 offset:61440
	ds_read_b128 v[166:169], v169 offset:61440
	ds_read_b128 v[222:225], v170 offset:61440
	ds_read_b128 v[226:229], v171 offset:61440
	ds_read_b128 v[170:173], v172 offset:61440
	s_setprio 1
	v_mfma_f32_32x32x16_bf16 v[48:63], v[64:67], v[182:185], v[48:63]
	v_mfma_f32_32x32x16_bf16 v[32:47], v[64:67], v[190:193], v[32:47]
	v_mfma_f32_32x32x16_bf16 v[16:31], v[64:67], v[198:201], v[16:31]
	v_mfma_f32_32x32x16_bf16 v[0:15], v[64:67], v[206:209], v[0:15]
	v_mfma_f32_32x32x16_bf16 v[48:63], v[68:71], v[186:189], v[48:63]
	v_mfma_f32_32x32x16_bf16 v[32:47], v[68:71], v[194:197], v[32:47]
	v_mfma_f32_32x32x16_bf16 v[16:31], v[68:71], v[202:205], v[16:31]
	v_mfma_f32_32x32x16_bf16 v[0:15], v[68:71], v[210:213], v[0:15]
	s_waitcnt lgkmcnt(0)
	v_mfma_f32_32x32x16_bf16 v[64:79], v[132:135], v[80:83], 0
	v_mfma_f32_32x32x16_bf16 v[64:79], v[136:139], v[84:87], v[64:79]
	v_mfma_f32_32x32x16_bf16 v[64:79], v[140:143], v[88:91], v[64:79]
	v_mfma_f32_32x32x16_bf16 v[64:79], v[174:177], v[92:95], v[64:79]
	v_mfma_f32_32x32x16_bf16 v[64:79], v[162:165], v[96:99], v[64:79]
	v_mfma_f32_32x32x16_bf16 v[64:79], v[178:181], v[100:103], v[64:79]
	s_waitcnt lgkmcnt(0)
; #define LAS __attribute__((address_space(3)))
; DI void expsum(f32x16& p, float& l_reg, bf16x8& pa0, bf16x8& pa1) {
; #pragma unroll
;     for (int r = 0; r < 16; ++r) p[r] = __builtin_amdgcn_exp2f(p[r]);
;     float ps = 0.f;
; #pragma unroll
;     for (int r = 0; r < 16; ++r) ps += p[r];
;     l_reg += ps; asm volatile("" : "+v"(l_reg));
;     ...
;     ATT_PK4(p, 0, pa0); ATT_PK4(p, 8, pa1);
;     ...
; }
; DI int v_rd_base(int lane) { return ((lane & 3) << 3) | (((lane >> 2) & 3) << 6) | (((lane >> 4) & 1) << 5) | (((lane >> 5) & 1) << 8); }
; template <int OFF> DI s16x4 tr_read(int vb) { s16x4 r; asm volatile("ds_read_b64_tr_b16 %0, %1 offset:%2" : "=&v"(r) : "v"(vb), "i"(OFF) : "memory"); return r; }
; template <int H> DI void v_reads(s16x4* vf, int vb) {
;     vf[0] = tr_read<v_rd_off(0, 2 * H, 0)>(vb); vf[1] = tr_read<v_rd_off(0, 2 * H, 1)>(vb); vf[2] = tr_read<v_rd_off(0, 2 * H + 1, 0)>(vb); vf[3] = tr_read<v_rd_off(0, 2 * H + 1, 1)>(vb);
;     vf[4] = tr_read<v_rd_off(1, 2 * H, 0)>(vb); vf[5] = tr_read<v_rd_off(1, 2 * H, 1)>(vb); vf[6] = tr_read<v_rd_off(1, 2 * H + 1, 0)>(vb); vf[7] = tr_read<v_rd_off(1, 2 * H + 1, 1)>(vb);
;     vf[8] = tr_read<v_rd_off(2, 2 * H, 0)>(vb); vf[9] = tr_read<v_rd_off(2, 2 * H, 1)>(vb); vf[10] = tr_read<v_rd_off(2, 2 * H + 1, 0)>(vb); vf[11] = tr_read<v_rd_off(2, 2 * H + 1, 1)>(vb);
;     vf[12] = tr_read<v_rd_off(3, 2 * H, 0)>(vb); vf[13] = tr_read<v_rd_off(3, 2 * H, 1)>(vb); vf[14] = tr_read<v_rd_off(3, 2 * H + 1, 0)>(vb); vf[15] = tr_read<v_rd_off(3, 2 * H + 1, 1)>(vb);
; }
; DI void pv_mma(f32x16* o, const s16x4* vf, bf16x8 pa0, bf16x8 pa1) {
;     ...
; #pragma unroll
;     for (int d0 = 0; d0 < 4; ++d0) {
;         o[d0] = __builtin_amdgcn_mfma_f32_32x32x16_bf16(pa0, ATT_PK(vf[4 * d0], vf[4 * d0 + 1]), o[d0], 0, 0, 0);
;         o[d0] = __builtin_amdgcn_mfma_f32_32x32x16_bf16(pa1, ATT_PK(vf[4 * d0 + 2], vf[4 * d0 + 3]), o[d0], 0, 0, 0); }
;     ...
; }
; template <int DQK, int D0A, int D0B> DI void k_reads(bf16x8* kf, const LAS unsigned char* Ks, int half, int r32, int hi) {
; #pragma unroll
;     for (int d0 = D0A; d0 < D0B; ++d0) kf[d0 - D0A] = *(const LAS bf16x8*)(Ks + half * (32 * DQK * 2) + kswz<DQK>(r32, (d0 * 16 + hi * 8) * 2));
; }
; template <int D0A, int D0B> DI void qk_mma(f32x16& p, const bf16x8* kf, const bf16x8* qr) {
; #pragma unroll
;     for (int d0 = D0A; d0 < D0B; ++d0) {
	v_mfma_f32_32x32x16_bf16 v[64:79], v[214:217], v[104:107], v[64:79]
	v_mfma_f32_32x32x16_bf16 v[64:79], v[218:221], v[108:111], v[64:79]
	v_mfma_f32_32x32x16_bf16 v[64:79], v[166:169], v[112:115], v[64:79]
	v_mfma_f32_32x32x16_bf16 v[64:79], v[222:225], v[116:119], v[64:79]
	v_mfma_f32_32x32x16_bf16 v[64:79], v[226:229], v[120:123], v[64:79]
	v_mfma_f32_32x32x16_bf16 v[64:79], v[170:173], v[124:127], v[64:79]
	s_setprio 0
	v_add_u32_e32 v158, 0x12000, v158
	v_add_u32_e32 v132, v158, v151
	v_add_u32_e32 v136, v158, v149
	v_add_u32_e32 v140, v158, v148
	v_add_u32_e32 v161, v158, v147
	ds_read_b128 v[132:135], v132
	ds_read_b128 v[136:139], v136
	ds_read_b128 v[140:143], v140
	ds_read_b128 v[162:165], v161
	v_add_u32_e32 v161, v158, v146
	v_add_u32_e32 v170, v158, v150
	ds_read_b128 v[166:169], v161
	ds_read_b128 v[170:173], v170
	ds_read_b64_tr_b16 v[174:175], v145 offset:0x2000
	ds_read_b64_tr_b16 v[176:177], v145 offset:0x2800
	ds_read_b64_tr_b16 v[178:179], v145 offset:0x3000
	ds_read_b64_tr_b16 v[180:181], v145 offset:0x3800
	ds_read_b64_tr_b16 v[182:183], v145 offset:0x2200
	ds_read_b64_tr_b16 v[184:185], v145 offset:0x2a00
	ds_read_b64_tr_b16 v[186:187], v145 offset:0x3200
	ds_read_b64_tr_b16 v[188:189], v145 offset:0x3a00
	ds_read_b64_tr_b16 v[190:191], v145 offset:0x2400
	ds_read_b64_tr_b16 v[192:193], v145 offset:0x2c00
	ds_read_b64_tr_b16 v[194:195], v145 offset:0x3400
	ds_read_b64_tr_b16 v[196:197], v145 offset:0x3c00
	ds_read_b64_tr_b16 v[198:199], v145 offset:0x2600
	ds_read_b64_tr_b16 v[200:201], v145 offset:0x2e00
	ds_read_b64_tr_b16 v[202:203], v145 offset:0x3600
	ds_read_b64_tr_b16 v[204:205], v145 offset:0x3e00
	s_setprio 2
	v_exp_f32_e32 v64, v64
	v_exp_f32_e32 v65, v65
	v_exp_f32_e32 v66, v66
	v_exp_f32_e32 v67, v67
	v_exp_f32_e32 v68, v68
	v_exp_f32_e32 v69, v69
	v_add_f32_e32 v145, v65, v64
	v_exp_f32_e32 v70, v70
	v_add_f32_e32 v145, v66, v145
	v_exp_f32_e32 v71, v71
	v_add_f32_e32 v145, v67, v145
	v_exp_f32_e32 v72, v72
	v_add_f32_e32 v145, v68, v145
	v_exp_f32_e32 v73, v73
	v_add_f32_e32 v145, v69, v145
	v_exp_f32_e32 v74, v74
	v_add_f32_e32 v145, v70, v145
	v_exp_f32_e32 v75, v75
	v_add_f32_e32 v145, v71, v145
	v_exp_f32_e32 v76, v76
	v_add_f32_e32 v145, v72, v145
	v_exp_f32_e32 v77, v77
	v_add_f32_e32 v145, v73, v145
	v_exp_f32_e32 v78, v78
	v_add_f32_e32 v145, v74, v145
	v_exp_f32_e32 v79, v79
	v_add_f32_e32 v145, v75, v145
	v_add_f32_e32 v145, v76, v145
	v_add_f32_e32 v145, v77, v145
	v_add_f32_e32 v145, v78, v145
	v_add_f32_e32 v145, v79, v145
	v_add_f32_e32 v161, v144, v145
	v_cvt_pk_bf16_f32 v64, v64, v65
	v_cvt_pk_bf16_f32 v65, v66, v67
	v_cvt_pk_bf16_f32 v66, v68, v69
	v_cvt_pk_bf16_f32 v67, v70, v71
	v_cvt_pk_bf16_f32 v68, v72, v73
	v_cvt_pk_bf16_f32 v69, v74, v75
	v_cvt_pk_bf16_f32 v70, v76, v77
	v_cvt_pk_bf16_f32 v71, v78, v79
	v_permlane32_swap_b32_e32 v64, v66
	v_permlane32_swap_b32_e32 v65, v67
	v_permlane32_swap_b32_e32 v68, v70
	v_permlane32_swap_b32_e32 v69, v71
	s_waitcnt lgkmcnt(0)
	v_add_u32_e32 v72, v158, v152
	v_add_u32_e32 v73, v158, v153
	ds_read_b128 v[206:209], v72
	ds_read_b128 v[210:213], v73
	v_add_u32_e32 v72, v158, v154
	v_add_u32_e32 v73, v158, v155
	ds_read_b128 v[214:217], v72
	ds_read_b128 v[218:221], v73
	v_add_u32_e32 v72, v158, v156
	v_add_u32_e32 v73, v158, v157
	ds_read_b128 v[222:225], v72
	ds_read_b128 v[226:229], v73
	s_setprio 1
	s_cmp_lt_u32 s33, 0x100
	s_cbranch_scc1 .Lstg_mla_m62_7
	s_waitcnt vmcnt(0)
	s_barrier

; #define LAS __attribute__((address_space(3)))
; DI void expsum(f32x16& p, float& l_reg, bf16x8& pa0, bf16x8& pa1) {
; #pragma unroll
;     for (int r = 0; r < 16; ++r) p[r] = __builtin_amdgcn_exp2f(p[r]);
;     float ps = 0.f;
; #pragma unroll
;     for (int r = 0; r < 16; ++r) ps += p[r];
;     l_reg += ps; asm volatile("" : "+v"(l_reg));
;     ...
;     ATT_PK4(p, 0, pa0); ATT_PK4(p, 8, pa1);
;     ...
; }
; DI int v_rd_base(int lane) { return ((lane & 3) << 3) | (((lane >> 2) & 3) << 6) | (((lane >> 4) & 1) << 5) | (((lane >> 5) & 1) << 8); }
; template <int OFF> DI s16x4 tr_read(int vb) { s16x4 r; asm volatile("ds_read_b64_tr_b16 %0, %1 offset:%2" : "=&v"(r) : "v"(vb), "i"(OFF) : "memory"); return r; }
; template <int H> DI void v_reads(s16x4* vf, int vb) {
;     vf[0] = tr_read<v_rd_off(0, 2 * H, 0)>(vb); vf[1] = tr_read<v_rd_off(0, 2 * H, 1)>(vb); vf[2] = tr_read<v_rd_off(0, 2 * H + 1, 0)>(vb); vf[3] = tr_read<v_rd_off(0, 2 * H + 1, 1)>(vb);
;     vf[4] = tr_read<v_rd_off(1, 2 * H, 0)>(vb); vf[5] = tr_read<v_rd_off(1, 2 * H, 1)>(vb); vf[6] = tr_read<v_rd_off(1, 2 * H + 1, 0)>(vb); vf[7] = tr_read<v_rd_off(1, 2 * H + 1, 1)>(vb);
;     vf[8] = tr_read<v_rd_off(2, 2 * H, 0)>(vb); vf[9] = tr_read<v_rd_off(2, 2 * H, 1)>(vb); vf[10] = tr_read<v_rd_off(2, 2 * H + 1, 0)>(vb); vf[11] = tr_read<v_rd_off(2, 2 * H + 1, 1)>(vb);
;     vf[12] = tr_read<v_rd_off(3, 2 * H, 0)>(vb); vf[13] = tr_read<v_rd_off(3, 2 * H, 1)>(vb); vf[14] = tr_read<v_rd_off(3, 2 * H + 1, 0)>(vb); vf[15] = tr_read<v_rd_off(3, 2 * H + 1, 1)>(vb);
; }
; DI void pv_mma(f32x16* o, const s16x4* vf, bf16x8 pa0, bf16x8 pa1) {
;     ...
; #pragma unroll
;     for (int d0 = 0; d0 < 4; ++d0) {
;         o[d0] = __builtin_amdgcn_mfma_f32_32x32x16_bf16(pa0, ATT_PK(vf[4 * d0], vf[4 * d0 + 1]), o[d0], 0, 0, 0);
;         o[d0] = __builtin_amdgcn_mfma_f32_32x32x16_bf16(pa1, ATT_PK(vf[4 * d0 + 2], vf[4 * d0 + 3]), o[d0], 0, 0, 0); }
;     ...
; }
; template <int DQK, int D0A, int D0B> DI void k_reads(bf16x8* kf, const LAS unsigned char* Ks, int half, int r32, int hi) {
; #pragma unroll
;     for (int d0 = D0A; d0 < D0B; ++d0) kf[d0 - D0A] = *(const LAS bf16x8*)(Ks + half * (32 * DQK * 2) + kswz<DQK>(r32, (d0 * 16 + hi * 8) * 2));
; }
; template <int D0A, int D0B> DI void qk_mma(f32x16& p, const bf16x8* kf, const bf16x8* qr) {
; #pragma unroll
;     for (int d0 = D0A; d0 < D0B; ++d0) {
.Lstg_mla_t63_8:
	s_setprio 0
	v_add_u32_e32 v158, s82, v159
	v_add_u32_e32 v132, v158, v151
	v_add_u32_e32 v136, v158, v149
	v_add_u32_e32 v140, v158, v148
	v_add_u32_e32 v144, v158, v147
	ds_read_b128 v[132:135], v132
	ds_read_b128 v[136:139], v136
	ds_read_b128 v[140:143], v140
	ds_read_b128 v[162:165], v144
	v_add_u32_e32 v144, v158, v146
	v_add_u32_e32 v148, v158, v150
	ds_read_b128 v[144:147], v144
	ds_read_b128 v[148:151], v148
	ds_read_b64_tr_b16 v[166:167], v130 offset:0
	ds_read_b64_tr_b16 v[168:169], v130 offset:0x800
	ds_read_b64_tr_b16 v[170:171], v130 offset:0x1000
	ds_read_b64_tr_b16 v[172:173], v130 offset:0x1800
	ds_read_b64_tr_b16 v[174:175], v130 offset:0x200
	ds_read_b64_tr_b16 v[176:177], v130 offset:0xa00
	ds_read_b64_tr_b16 v[178:179], v130 offset:0x1200
	ds_read_b64_tr_b16 v[180:181], v130 offset:0x1a00
	ds_read_b64_tr_b16 v[182:183], v130 offset:0x400
	ds_read_b64_tr_b16 v[184:185], v130 offset:0xc00
	ds_read_b64_tr_b16 v[186:187], v130 offset:0x1400
	ds_read_b64_tr_b16 v[188:189], v130 offset:0x1c00
	ds_read_b64_tr_b16 v[190:191], v130 offset:0x600
	ds_read_b64_tr_b16 v[192:193], v130 offset:0xe00
	ds_read_b64_tr_b16 v[194:195], v130 offset:0x1600
	ds_read_b64_tr_b16 v[196:197], v130 offset:0x1e00
	s_setprio 2
	v_exp_f32_e32 v64, v64
	v_exp_f32_e32 v65, v65
	v_exp_f32_e32 v66, v66
	v_exp_f32_e32 v67, v67
	v_exp_f32_e32 v68, v68
	v_exp_f32_e32 v69, v69
	v_add_f32_e32 v159, v65, v64
	v_exp_f32_e32 v70, v70
	v_add_f32_e32 v159, v66, v159
	v_exp_f32_e32 v71, v71
	v_add_f32_e32 v159, v67, v159
	v_exp_f32_e32 v72, v72
	v_add_f32_e32 v159, v68, v159
	v_exp_f32_e32 v73, v73
	v_add_f32_e32 v159, v69, v159
	v_exp_f32_e32 v74, v74
	v_add_f32_e32 v159, v70, v159
	v_exp_f32_e32 v75, v75
	v_add_f32_e32 v159, v71, v159
	v_exp_f32_e32 v76, v76
	v_add_f32_e32 v159, v72, v159
	v_exp_f32_e32 v77, v77
	v_add_f32_e32 v159, v73, v159
	v_exp_f32_e32 v78, v78
	v_add_f32_e32 v159, v74, v159
	v_exp_f32_e32 v79, v79
	v_add_f32_e32 v159, v75, v159
	v_add_f32_e32 v159, v76, v159
	v_add_f32_e32 v159, v77, v159
	v_add_f32_e32 v159, v78, v159
	v_add_f32_e32 v159, v79, v159
	v_add_f32_e32 v161, v161, v159
	v_cvt_pk_bf16_f32 v64, v64, v65
	v_cvt_pk_bf16_f32 v65, v66, v67
	v_cvt_pk_bf16_f32 v66, v68, v69
	v_cvt_pk_bf16_f32 v67, v70, v71
	v_cvt_pk_bf16_f32 v68, v72, v73
	v_cvt_pk_bf16_f32 v69, v74, v75
	v_cvt_pk_bf16_f32 v70, v76, v77
	v_cvt_pk_bf16_f32 v71, v78, v79
	v_permlane32_swap_b32_e32 v64, v66
	v_permlane32_swap_b32_e32 v65, v67
	v_permlane32_swap_b32_e32 v68, v70
	v_permlane32_swap_b32_e32 v69, v71
	s_waitcnt lgkmcnt(0)
	v_add_u32_e32 v72, v158, v152
	v_add_u32_e32 v73, v158, v153
	ds_read_b128 v[198:201], v72
	ds_read_b128 v[202:205], v73
	v_add_u32_e32 v72, v158, v154
	v_add_u32_e32 v73, v158, v155
	ds_read_b128 v[152:155], v72
	ds_read_b128 v[206:209], v73
	v_add_u32_e32 v72, v158, v156
	v_add_u32_e32 v73, v158, v157
	ds_read_b128 v[156:159], v72
	ds_read_b128 v[210:213], v73
	s_setprio 1
	v_mfma_f32_32x32x16_bf16 v[48:63], v[64:67], v[166:169], v[48:63]
	v_mfma_f32_32x32x16_bf16 v[32:47], v[64:67], v[174:177], v[32:47]
	v_mfma_f32_32x32x16_bf16 v[16:31], v[64:67], v[182:185], v[16:31]
	v_mfma_f32_32x32x16_bf16 v[0:15], v[64:67], v[190:193], v[0:15]
	v_mfma_f32_32x32x16_bf16 v[48:63], v[68:71], v[170:173], v[48:63]
	v_mfma_f32_32x32x16_bf16 v[32:47], v[68:71], v[178:181], v[32:47]
	v_mfma_f32_32x32x16_bf16 v[16:31], v[68:71], v[186:189], v[16:31]
	v_mfma_f32_32x32x16_bf16 v[0:15], v[68:71], v[194:197], v[0:15]
	s_waitcnt lgkmcnt(0)
; template <int TAG = 0> DI int fresh_tid(int wv) { int l; asm volatile("v_mbcnt_lo_u32_b32 %0, -1, 0\n\tv_mbcnt_hi_u32_b32 %0, -1, %0 ; site %1" : "=v"(l) : "n"(TAG)); return wv * 64 + l; }
; DI void expsum(f32x16& p, float& l_reg, bf16x8& pa0, bf16x8& pa1) {
; #pragma unroll
;     for (int r = 0; r < 16; ++r) p[r] = __builtin_amdgcn_exp2f(p[r]);
;     float ps = 0.f;
; #pragma unroll
;     for (int r = 0; r < 16; ++r) ps += p[r];
;     l_reg += ps; asm volatile("" : "+v"(l_reg));
;     ...
;     ATT_PK4(p, 0, pa0); ATT_PK4(p, 8, pa1);
;     ...
; }
; DI int v_rd_base(int lane) { return ((lane & 3) << 3) | (((lane >> 2) & 3) << 6) | (((lane >> 4) & 1) << 5) | (((lane >> 5) & 1) << 8); }
; template <int OFF> DI s16x4 tr_read(int vb) { s16x4 r; asm volatile("ds_read_b64_tr_b16 %0, %1 offset:%2" : "=&v"(r) : "v"(vb), "i"(OFF) : "memory"); return r; }
; template <int H> DI void v_reads(s16x4* vf, int vb) {
;     vf[0] = tr_read<v_rd_off(0, 2 * H, 0)>(vb); vf[1] = tr_read<v_rd_off(0, 2 * H, 1)>(vb); vf[2] = tr_read<v_rd_off(0, 2 * H + 1, 0)>(vb); vf[3] = tr_read<v_rd_off(0, 2 * H + 1, 1)>(vb);
;     vf[4] = tr_read<v_rd_off(1, 2 * H, 0)>(vb); vf[5] = tr_read<v_rd_off(1, 2 * H, 1)>(vb); vf[6] = tr_read<v_rd_off(1, 2 * H + 1, 0)>(vb); vf[7] = tr_read<v_rd_off(1, 2 * H + 1, 1)>(vb);
;     vf[8] = tr_read<v_rd_off(2, 2 * H, 0)>(vb); vf[9] = tr_read<v_rd_off(2, 2 * H, 1)>(vb); vf[10] = tr_read<v_rd_off(2, 2 * H + 1, 0)>(vb); vf[11] = tr_read<v_rd_off(2, 2 * H + 1, 1)>(vb);
;     vf[12] = tr_read<v_rd_off(3, 2 * H, 0)>(vb); vf[13] = tr_read<v_rd_off(3, 2 * H, 1)>(vb); vf[14] = tr_read<v_rd_off(3, 2 * H + 1, 0)>(vb); vf[15] = tr_read<v_rd_off(3, 2 * H + 1, 1)>(vb);
; }
; DI void pv_mma(f32x16* o, const s16x4* vf, bf16x8 pa0, bf16x8 pa1) {
;     ...
; #pragma unroll
;     for (int d0 = 0; d0 < 4; ++d0) {
;         o[d0] = __builtin_amdgcn_mfma_f32_32x32x16_bf16(pa0, ATT_PK(vf[4 * d0], vf[4 * d0 + 1]), o[d0], 0, 0, 0);
;         o[d0] = __builtin_amdgcn_mfma_f32_32x32x16_bf16(pa1, ATT_PK(vf[4 * d0 + 2], vf[4 * d0 + 3]), o[d0], 0, 0, 0); }
;     ...
; }
; template <int DQK, int MODE, int LDQ, int LDK, int LDV> ...
;     ...
;     __builtin_amdgcn_s_setprio(0);
;     ...
;     l_reg = swap_sum(l_reg);
;     { const int lane2 = fresh_tid<110 + MODE>(wv) & 63, r32 = lane2 & 31, hi = lane2 >> 5;
;     if (hi == 0) li_l[r32] = l_reg;
	v_mfma_f32_32x32x16_bf16 v[64:79], v[132:135], v[80:83], 0
	v_mfma_f32_32x32x16_bf16 v[64:79], v[136:139], v[84:87], v[64:79]
	v_mfma_f32_32x32x16_bf16 v[64:79], v[140:143], v[88:91], v[64:79]
	v_mfma_f32_32x32x16_bf16 v[64:79], v[162:165], v[92:95], v[64:79]
	v_mfma_f32_32x32x16_bf16 v[64:79], v[144:147], v[96:99], v[64:79]
	v_mfma_f32_32x32x16_bf16 v[64:79], v[148:151], v[100:103], v[64:79]
	s_waitcnt lgkmcnt(0)
	v_mfma_f32_32x32x16_bf16 v[64:79], v[198:201], v[104:107], v[64:79]
	v_mfma_f32_32x32x16_bf16 v[64:79], v[202:205], v[108:111], v[64:79]
	v_mfma_f32_32x32x16_bf16 v[64:79], v[152:155], v[112:115], v[64:79]
	v_mfma_f32_32x32x16_bf16 v[64:79], v[206:209], v[116:119], v[64:79]
	v_mfma_f32_32x32x16_bf16 v[64:79], v[156:159], v[120:123], v[64:79]
	v_mfma_f32_32x32x16_bf16 v[64:79], v[210:213], v[124:127], v[64:79]
	s_setprio 0
	ds_read_b64_tr_b16 v[80:81], v130 offset:0x2000
	ds_read_b64_tr_b16 v[82:83], v130 offset:0x2800
	ds_read_b64_tr_b16 v[84:85], v130 offset:0x3000
	ds_read_b64_tr_b16 v[86:87], v130 offset:0x3800
	ds_read_b64_tr_b16 v[88:89], v130 offset:0x2200
	ds_read_b64_tr_b16 v[90:91], v130 offset:0x2a00
	ds_read_b64_tr_b16 v[92:93], v130 offset:0x3200
	ds_read_b64_tr_b16 v[94:95], v130 offset:0x3a00
	ds_read_b64_tr_b16 v[96:97], v130 offset:0x2400
	ds_read_b64_tr_b16 v[98:99], v130 offset:0x2c00
	ds_read_b64_tr_b16 v[100:101], v130 offset:0x3400
	ds_read_b64_tr_b16 v[102:103], v130 offset:0x3c00
	ds_read_b64_tr_b16 v[104:105], v130 offset:0x2600
	ds_read_b64_tr_b16 v[106:107], v130 offset:0x2e00
	ds_read_b64_tr_b16 v[108:109], v130 offset:0x3600
	ds_read_b64_tr_b16 v[110:111], v130 offset:0x3e00
	s_nop 11
	s_setprio 2
	v_exp_f32_e32 v112, v64
	v_exp_f32_e32 v65, v65
	v_exp_f32_e32 v113, v66
	v_exp_f32_e32 v67, v67
	v_exp_f32_e32 v68, v68
	v_exp_f32_e32 v69, v69
	v_add_f32_e32 v64, v65, v112
	v_exp_f32_e32 v70, v70
	v_add_f32_e32 v64, v113, v64
	v_exp_f32_e32 v71, v71
	v_add_f32_e32 v64, v67, v64
	v_exp_f32_e32 v72, v72
	v_add_f32_e32 v64, v68, v64
	v_exp_f32_e32 v73, v73
	v_add_f32_e32 v64, v69, v64
	v_exp_f32_e32 v74, v74
	v_add_f32_e32 v64, v70, v64
	v_exp_f32_e32 v75, v75
	v_add_f32_e32 v64, v71, v64
	v_exp_f32_e32 v76, v76
	v_add_f32_e32 v64, v72, v64
	v_exp_f32_e32 v77, v77
	v_add_f32_e32 v64, v73, v64
	v_exp_f32_e32 v78, v78
	v_add_f32_e32 v64, v74, v64
	v_exp_f32_e32 v79, v79
	v_add_f32_e32 v64, v75, v64
	v_add_f32_e32 v64, v76, v64
	v_add_f32_e32 v64, v77, v64
	v_add_f32_e32 v64, v78, v64
	v_add_f32_e32 v64, v79, v64
	v_add_f32_e32 v64, v161, v64
	v_cvt_pk_bf16_f32 v66, v112, v65
	v_cvt_pk_bf16_f32 v67, v113, v67
	v_cvt_pk_bf16_f32 v68, v68, v69
	v_cvt_pk_bf16_f32 v69, v70, v71
	v_cvt_pk_bf16_f32 v70, v72, v73
	v_cvt_pk_bf16_f32 v71, v74, v75
	v_cvt_pk_bf16_f32 v72, v76, v77
	v_cvt_pk_bf16_f32 v73, v78, v79
	v_permlane32_swap_b32_e32 v66, v68
	v_permlane32_swap_b32_e32 v67, v69
	v_permlane32_swap_b32_e32 v70, v72
	v_permlane32_swap_b32_e32 v71, v73
	s_waitcnt lgkmcnt(0)
	s_setprio 1
	v_mfma_f32_32x32x16_bf16 v[48:63], v[66:69], v[80:83], v[48:63]
	v_mfma_f32_32x32x16_bf16 v[32:47], v[66:69], v[88:91], v[32:47]
	v_mfma_f32_32x32x16_bf16 v[16:31], v[66:69], v[96:99], v[16:31]
	v_mfma_f32_32x32x16_bf16 v[0:15], v[66:69], v[104:107], v[0:15]
	v_mfma_f32_32x32x16_bf16 v[48:63], v[70:73], v[84:87], v[48:63]
	v_mfma_f32_32x32x16_bf16 v[32:47], v[70:73], v[92:95], v[32:47]
	v_mfma_f32_32x32x16_bf16 v[16:31], v[70:73], v[100:103], v[16:31]
	v_mfma_f32_32x32x16_bf16 v[0:15], v[70:73], v[108:111], v[0:15]
	s_setprio 0
	v_mbcnt_lo_u32_b32 v66, -1, 0
	v_mbcnt_hi_u32_b32 v66, -1, v66
	v_mov_b32_e32 v67, v64
	v_and_b32_e32 v65, 31, v66
	v_bfe_u32 v66, v66, 5, 1
	v_permlane32_swap_b32_e32 v64, v67
	v_cmp_eq_u32_e32 vcc, 0, v66
	s_and_saveexec_b64 s[2:3], vcc
	s_cbranch_execz .LBB0_1910
	v_lshl_add_u32 v68, v65, 2, s4
	v_add_f32_e32 v64, v64, v67
	ds_write_b32 v68, v64
	s_branch .LBB0_1910
